# MFMA fp4->f32 v-row sweep with f32 sums, LN2 gamma/beta preloaded per half, P6 epilogue x loads prefetched 8 steps deep
# speedup vs baseline: 1.0040x; 1.0040x over previous
.LBB0_535:
	s_andn2_b64 vcc, exec, s[0:1]
	s_mov_b64 s[0:1], -1
	v_lshl_add_u32 v244, s38, 8, v188
	v_lshl_or_b32 v245, s56, 8, v189
	v_lshl_add_u32 v246, v244, 11, v245
	v_lshlrev_b32_e32 v247, 2, v246
	v_lshlrev_b32_e32 v248, 1, v246
	v_mov_b32_e32 v249, v247
	global_load_dwordx4 v[198:201], v249, s[4:5] offset:0
	global_load_dwordx4 v[202:205], v249, s[4:5] offset:16
	global_load_dwordx4 v[206:209], v249, s[4:5] offset:512
	global_load_dwordx4 v[210:213], v249, s[4:5] offset:528
	v_add_u32_e32 v249, 0x20000, v247
	global_load_dwordx4 v[214:217], v249, s[4:5] offset:0
	global_load_dwordx4 v[218:221], v249, s[4:5] offset:16
	global_load_dwordx4 v[222:225], v249, s[4:5] offset:512
	global_load_dwordx4 v[226:229], v249, s[4:5] offset:528
	v_add_u32_e32 v249, 0x40000, v247
	global_load_dwordx4 v[2:5], v249, s[4:5] offset:0
	global_load_dwordx4 v[6:9], v249, s[4:5] offset:16
	global_load_dwordx4 v[10:13], v249, s[4:5] offset:512
	global_load_dwordx4 v[14:17], v249, s[4:5] offset:528
	v_add_u32_e32 v249, 0x60000, v247
	global_load_dwordx4 v[18:21], v249, s[4:5] offset:0
	global_load_dwordx4 v[22:25], v249, s[4:5] offset:16
	global_load_dwordx4 v[26:29], v249, s[4:5] offset:512
	global_load_dwordx4 v[30:33], v249, s[4:5] offset:528
	s_waitcnt vmcnt(14)
	v_pk_mul_f32 v[200:201], v[200:201], s[14:15] op_sel_hi:[1,0]
	v_pk_mul_f32 v[198:199], v[198:199], s[14:15] op_sel_hi:[1,0]
	v_pk_mul_f32 v[204:205], v[204:205], s[14:15] op_sel_hi:[1,0]
	v_pk_mul_f32 v[202:203], v[202:203], s[14:15] op_sel_hi:[1,0]
	v_pk_fma_f32 v[200:201], v[160:161], s[16:17], v[200:201] op_sel_hi:[1,0,1]
	v_pk_fma_f32 v[198:199], v[158:159], s[16:17], v[198:199] op_sel_hi:[1,0,1]
	v_pk_fma_f32 v[204:205], v[156:157], s[16:17], v[204:205] op_sel_hi:[1,0,1]
	v_pk_fma_f32 v[202:203], v[154:155], s[16:17], v[202:203] op_sel_hi:[1,0,1]
	v_cvt_pk_bf16_f32 v198, v198, v199
	v_cvt_pk_bf16_f32 v199, v200, v201
	v_cvt_pk_bf16_f32 v200, v202, v203
	v_cvt_pk_bf16_f32 v201, v204, v205
	v_mov_b32_e32 v250, v248
	global_store_dwordx4 v250, v[198:201], s[20:21] offset:0
	s_nop 1
	v_add_u32_e32 v249, 0x100000, v247
	global_load_dwordx4 v[198:201], v249, s[4:5] offset:0
	global_load_dwordx4 v[202:205], v249, s[4:5] offset:16
	s_waitcnt vmcnt(15)
	v_pk_mul_f32 v[208:209], v[208:209], s[14:15] op_sel_hi:[1,0]
	v_pk_mul_f32 v[206:207], v[206:207], s[14:15] op_sel_hi:[1,0]
	v_pk_mul_f32 v[212:213], v[212:213], s[14:15] op_sel_hi:[1,0]
	v_pk_mul_f32 v[210:211], v[210:211], s[14:15] op_sel_hi:[1,0]
	v_pk_fma_f32 v[208:209], v[152:153], s[16:17], v[208:209] op_sel_hi:[1,0,1]
	v_pk_fma_f32 v[206:207], v[150:151], s[16:17], v[206:207] op_sel_hi:[1,0,1]
	v_pk_fma_f32 v[212:213], v[148:149], s[16:17], v[212:213] op_sel_hi:[1,0,1]
	v_pk_fma_f32 v[210:211], v[146:147], s[16:17], v[210:211] op_sel_hi:[1,0,1]
	v_cvt_pk_bf16_f32 v206, v206, v207
	v_cvt_pk_bf16_f32 v207, v208, v209
	v_cvt_pk_bf16_f32 v208, v210, v211
	v_cvt_pk_bf16_f32 v209, v212, v213
	global_store_dwordx4 v250, v[206:209], s[20:21] offset:256
	s_nop 1
	global_load_dwordx4 v[206:209], v249, s[4:5] offset:512
	global_load_dwordx4 v[210:213], v249, s[4:5] offset:528
	s_waitcnt vmcnt(16)
	v_pk_mul_f32 v[216:217], v[216:217], s[14:15] op_sel_hi:[1,0]
	v_pk_mul_f32 v[214:215], v[214:215], s[14:15] op_sel_hi:[1,0]
	v_pk_mul_f32 v[220:221], v[220:221], s[14:15] op_sel_hi:[1,0]
	v_pk_mul_f32 v[218:219], v[218:219], s[14:15] op_sel_hi:[1,0]
	v_pk_fma_f32 v[216:217], v[144:145], s[16:17], v[216:217] op_sel_hi:[1,0,1]
	v_pk_fma_f32 v[214:215], v[142:143], s[16:17], v[214:215] op_sel_hi:[1,0,1]
	v_pk_fma_f32 v[220:221], v[140:141], s[16:17], v[220:221] op_sel_hi:[1,0,1]
	v_pk_fma_f32 v[218:219], v[138:139], s[16:17], v[218:219] op_sel_hi:[1,0,1]
	v_cvt_pk_bf16_f32 v214, v214, v215
	v_cvt_pk_bf16_f32 v215, v216, v217
	v_cvt_pk_bf16_f32 v216, v218, v219
	v_cvt_pk_bf16_f32 v217, v220, v221
	v_add_u32_e32 v250, 0x10000, v248
	global_store_dwordx4 v250, v[214:217], s[20:21] offset:0
	s_nop 1
	v_add_u32_e32 v249, 0x120000, v247
	global_load_dwordx4 v[214:217], v249, s[4:5] offset:0
	global_load_dwordx4 v[218:221], v249, s[4:5] offset:16
	s_waitcnt vmcnt(17)
	v_pk_mul_f32 v[224:225], v[224:225], s[14:15] op_sel_hi:[1,0]
	v_pk_mul_f32 v[222:223], v[222:223], s[14:15] op_sel_hi:[1,0]
	v_pk_mul_f32 v[228:229], v[228:229], s[14:15] op_sel_hi:[1,0]
	v_pk_mul_f32 v[226:227], v[226:227], s[14:15] op_sel_hi:[1,0]
	v_pk_fma_f32 v[224:225], v[136:137], s[16:17], v[224:225] op_sel_hi:[1,0,1]
	v_pk_fma_f32 v[222:223], v[134:135], s[16:17], v[222:223] op_sel_hi:[1,0,1]
	v_pk_fma_f32 v[228:229], v[132:133], s[16:17], v[228:229] op_sel_hi:[1,0,1]
	v_pk_fma_f32 v[226:227], v[130:131], s[16:17], v[226:227] op_sel_hi:[1,0,1]
	v_cvt_pk_bf16_f32 v222, v222, v223
	v_cvt_pk_bf16_f32 v223, v224, v225
	v_cvt_pk_bf16_f32 v224, v226, v227
	v_cvt_pk_bf16_f32 v225, v228, v229
	global_store_dwordx4 v250, v[222:225], s[20:21] offset:256
	s_nop 1
	global_load_dwordx4 v[222:225], v249, s[4:5] offset:512
	global_load_dwordx4 v[226:229], v249, s[4:5] offset:528
	s_waitcnt vmcnt(18)
	v_pk_mul_f32 v[4:5], v[4:5], s[14:15] op_sel_hi:[1,0]
	v_pk_mul_f32 v[2:3], v[2:3], s[14:15] op_sel_hi:[1,0]
	v_pk_mul_f32 v[8:9], v[8:9], s[14:15] op_sel_hi:[1,0]
	v_pk_mul_f32 v[6:7], v[6:7], s[14:15] op_sel_hi:[1,0]
	v_pk_fma_f32 v[4:5], v[128:129], s[16:17], v[4:5] op_sel_hi:[1,0,1]
	v_pk_fma_f32 v[2:3], v[126:127], s[16:17], v[2:3] op_sel_hi:[1,0,1]
	v_pk_fma_f32 v[8:9], v[124:125], s[16:17], v[8:9] op_sel_hi:[1,0,1]
	v_pk_fma_f32 v[6:7], v[122:123], s[16:17], v[6:7] op_sel_hi:[1,0,1]
	v_cvt_pk_bf16_f32 v2, v2, v3
	v_cvt_pk_bf16_f32 v3, v4, v5
	v_cvt_pk_bf16_f32 v4, v6, v7
	v_cvt_pk_bf16_f32 v5, v8, v9
	v_add_u32_e32 v250, 0x20000, v248
	global_store_dwordx4 v250, v[2:5], s[20:21] offset:0
	s_nop 1
	v_add_u32_e32 v249, 0x140000, v247
	global_load_dwordx4 v[2:5], v249, s[4:5] offset:0
	global_load_dwordx4 v[6:9], v249, s[4:5] offset:16
	s_waitcnt vmcnt(19)
	v_pk_mul_f32 v[12:13], v[12:13], s[14:15] op_sel_hi:[1,0]
	v_pk_mul_f32 v[10:11], v[10:11], s[14:15] op_sel_hi:[1,0]
	v_pk_mul_f32 v[16:17], v[16:17], s[14:15] op_sel_hi:[1,0]
	v_pk_mul_f32 v[14:15], v[14:15], s[14:15] op_sel_hi:[1,0]
	v_pk_fma_f32 v[12:13], v[120:121], s[16:17], v[12:13] op_sel_hi:[1,0,1]
	v_pk_fma_f32 v[10:11], v[118:119], s[16:17], v[10:11] op_sel_hi:[1,0,1]
	v_pk_fma_f32 v[16:17], v[116:117], s[16:17], v[16:17] op_sel_hi:[1,0,1]
	v_pk_fma_f32 v[14:15], v[114:115], s[16:17], v[14:15] op_sel_hi:[1,0,1]
	v_cvt_pk_bf16_f32 v10, v10, v11
	v_cvt_pk_bf16_f32 v11, v12, v13
	v_cvt_pk_bf16_f32 v12, v14, v15
	v_cvt_pk_bf16_f32 v13, v16, v17
	global_store_dwordx4 v250, v[10:13], s[20:21] offset:256
	s_nop 1
	global_load_dwordx4 v[10:13], v249, s[4:5] offset:512
	global_load_dwordx4 v[14:17], v249, s[4:5] offset:528
	s_waitcnt vmcnt(20)
	v_pk_mul_f32 v[20:21], v[20:21], s[14:15] op_sel_hi:[1,0]
	v_pk_mul_f32 v[18:19], v[18:19], s[14:15] op_sel_hi:[1,0]
	v_pk_mul_f32 v[24:25], v[24:25], s[14:15] op_sel_hi:[1,0]
	v_pk_mul_f32 v[22:23], v[22:23], s[14:15] op_sel_hi:[1,0]
	v_pk_fma_f32 v[20:21], v[112:113], s[16:17], v[20:21] op_sel_hi:[1,0,1]
	v_pk_fma_f32 v[18:19], v[110:111], s[16:17], v[18:19] op_sel_hi:[1,0,1]
	v_pk_fma_f32 v[24:25], v[108:109], s[16:17], v[24:25] op_sel_hi:[1,0,1]
	v_pk_fma_f32 v[22:23], v[106:107], s[16:17], v[22:23] op_sel_hi:[1,0,1]
	v_cvt_pk_bf16_f32 v18, v18, v19
	v_cvt_pk_bf16_f32 v19, v20, v21
	v_cvt_pk_bf16_f32 v20, v22, v23
	v_cvt_pk_bf16_f32 v21, v24, v25
	v_add_u32_e32 v250, 0x30000, v248
	global_store_dwordx4 v250, v[18:21], s[20:21] offset:0
	s_nop 1
	v_add_u32_e32 v249, 0x160000, v247
	global_load_dwordx4 v[18:21], v249, s[4:5] offset:0
	global_load_dwordx4 v[22:25], v249, s[4:5] offset:16
	s_waitcnt vmcnt(21)
	v_pk_mul_f32 v[28:29], v[28:29], s[14:15] op_sel_hi:[1,0]
	v_pk_mul_f32 v[26:27], v[26:27], s[14:15] op_sel_hi:[1,0]
	v_pk_mul_f32 v[32:33], v[32:33], s[14:15] op_sel_hi:[1,0]
	v_pk_mul_f32 v[30:31], v[30:31], s[14:15] op_sel_hi:[1,0]
	v_pk_fma_f32 v[28:29], v[104:105], s[16:17], v[28:29] op_sel_hi:[1,0,1]
	v_pk_fma_f32 v[26:27], v[102:103], s[16:17], v[26:27] op_sel_hi:[1,0,1]
	v_pk_fma_f32 v[32:33], v[100:101], s[16:17], v[32:33] op_sel_hi:[1,0,1]
	v_pk_fma_f32 v[30:31], v[98:99], s[16:17], v[30:31] op_sel_hi:[1,0,1]
	v_cvt_pk_bf16_f32 v26, v26, v27
	v_cvt_pk_bf16_f32 v27, v28, v29
	v_cvt_pk_bf16_f32 v28, v30, v31
	v_cvt_pk_bf16_f32 v29, v32, v33
	global_store_dwordx4 v250, v[26:29], s[20:21] offset:256
	s_nop 1
	global_load_dwordx4 v[26:29], v249, s[4:5] offset:512
	global_load_dwordx4 v[30:33], v249, s[4:5] offset:528
	s_waitcnt vmcnt(21)
	v_pk_mul_f32 v[200:201], v[200:201], s[14:15] op_sel_hi:[1,0]
	v_pk_mul_f32 v[198:199], v[198:199], s[14:15] op_sel_hi:[1,0]
	v_pk_mul_f32 v[204:205], v[204:205], s[14:15] op_sel_hi:[1,0]
	v_pk_mul_f32 v[202:203], v[202:203], s[14:15] op_sel_hi:[1,0]
	v_pk_fma_f32 v[200:201], v[96:97], s[16:17], v[200:201] op_sel_hi:[1,0,1]
	v_pk_fma_f32 v[198:199], v[94:95], s[16:17], v[198:199] op_sel_hi:[1,0,1]
	v_pk_fma_f32 v[204:205], v[92:93], s[16:17], v[204:205] op_sel_hi:[1,0,1]
	v_pk_fma_f32 v[202:203], v[90:91], s[16:17], v[202:203] op_sel_hi:[1,0,1]
	v_cvt_pk_bf16_f32 v198, v198, v199
	v_cvt_pk_bf16_f32 v199, v200, v201
	v_cvt_pk_bf16_f32 v200, v202, v203
	v_cvt_pk_bf16_f32 v201, v204, v205
	v_add_u32_e32 v250, 0x80000, v248
	global_store_dwordx4 v250, v[198:201], s[20:21] offset:0
	s_waitcnt vmcnt(19)
	v_pk_mul_f32 v[208:209], v[208:209], s[14:15] op_sel_hi:[1,0]
	v_pk_mul_f32 v[206:207], v[206:207], s[14:15] op_sel_hi:[1,0]
	v_pk_mul_f32 v[212:213], v[212:213], s[14:15] op_sel_hi:[1,0]
	v_pk_mul_f32 v[210:211], v[210:211], s[14:15] op_sel_hi:[1,0]
	v_pk_fma_f32 v[208:209], v[88:89], s[16:17], v[208:209] op_sel_hi:[1,0,1]
	v_pk_fma_f32 v[206:207], v[86:87], s[16:17], v[206:207] op_sel_hi:[1,0,1]
	v_pk_fma_f32 v[212:213], v[84:85], s[16:17], v[212:213] op_sel_hi:[1,0,1]
	v_pk_fma_f32 v[210:211], v[82:83], s[16:17], v[210:211] op_sel_hi:[1,0,1]
	v_cvt_pk_bf16_f32 v206, v206, v207
	v_cvt_pk_bf16_f32 v207, v208, v209
	v_cvt_pk_bf16_f32 v208, v210, v211
	v_cvt_pk_bf16_f32 v209, v212, v213
	global_store_dwordx4 v250, v[206:209], s[20:21] offset:256
	s_waitcnt vmcnt(17)
	v_pk_mul_f32 v[216:217], v[216:217], s[14:15] op_sel_hi:[1,0]
	v_pk_mul_f32 v[214:215], v[214:215], s[14:15] op_sel_hi:[1,0]
	v_pk_mul_f32 v[220:221], v[220:221], s[14:15] op_sel_hi:[1,0]
	v_pk_mul_f32 v[218:219], v[218:219], s[14:15] op_sel_hi:[1,0]
	v_pk_fma_f32 v[216:217], v[80:81], s[16:17], v[216:217] op_sel_hi:[1,0,1]
	v_pk_fma_f32 v[214:215], v[78:79], s[16:17], v[214:215] op_sel_hi:[1,0,1]
	v_pk_fma_f32 v[220:221], v[76:77], s[16:17], v[220:221] op_sel_hi:[1,0,1]
	v_pk_fma_f32 v[218:219], v[74:75], s[16:17], v[218:219] op_sel_hi:[1,0,1]
	v_cvt_pk_bf16_f32 v214, v214, v215
	v_cvt_pk_bf16_f32 v215, v216, v217
	v_cvt_pk_bf16_f32 v216, v218, v219
	v_cvt_pk_bf16_f32 v217, v220, v221
	v_add_u32_e32 v250, 0x90000, v248
	global_store_dwordx4 v250, v[214:217], s[20:21] offset:0
	s_waitcnt vmcnt(15)
	v_pk_mul_f32 v[224:225], v[224:225], s[14:15] op_sel_hi:[1,0]
	v_pk_mul_f32 v[222:223], v[222:223], s[14:15] op_sel_hi:[1,0]
	v_pk_mul_f32 v[228:229], v[228:229], s[14:15] op_sel_hi:[1,0]
	v_pk_mul_f32 v[226:227], v[226:227], s[14:15] op_sel_hi:[1,0]
	v_pk_fma_f32 v[224:225], v[72:73], s[16:17], v[224:225] op_sel_hi:[1,0,1]
	v_pk_fma_f32 v[222:223], v[70:71], s[16:17], v[222:223] op_sel_hi:[1,0,1]
	v_pk_fma_f32 v[228:229], v[68:69], s[16:17], v[228:229] op_sel_hi:[1,0,1]
	v_pk_fma_f32 v[226:227], v[66:67], s[16:17], v[226:227] op_sel_hi:[1,0,1]
	v_cvt_pk_bf16_f32 v222, v222, v223
	v_cvt_pk_bf16_f32 v223, v224, v225
	v_cvt_pk_bf16_f32 v224, v226, v227
	v_cvt_pk_bf16_f32 v225, v228, v229
	global_store_dwordx4 v250, v[222:225], s[20:21] offset:256
	s_waitcnt vmcnt(13)
	v_pk_mul_f32 v[4:5], v[4:5], s[14:15] op_sel_hi:[1,0]
	v_pk_mul_f32 v[2:3], v[2:3], s[14:15] op_sel_hi:[1,0]
	v_pk_mul_f32 v[8:9], v[8:9], s[14:15] op_sel_hi:[1,0]
	v_pk_mul_f32 v[6:7], v[6:7], s[14:15] op_sel_hi:[1,0]
	v_pk_fma_f32 v[4:5], v[64:65], s[16:17], v[4:5] op_sel_hi:[1,0,1]
	v_pk_fma_f32 v[2:3], v[62:63], s[16:17], v[2:3] op_sel_hi:[1,0,1]
	v_pk_fma_f32 v[8:9], v[60:61], s[16:17], v[8:9] op_sel_hi:[1,0,1]
	v_pk_fma_f32 v[6:7], v[58:59], s[16:17], v[6:7] op_sel_hi:[1,0,1]
	v_cvt_pk_bf16_f32 v2, v2, v3
	v_cvt_pk_bf16_f32 v3, v4, v5
	v_cvt_pk_bf16_f32 v4, v6, v7
	v_cvt_pk_bf16_f32 v5, v8, v9
	v_add_u32_e32 v250, 0xa0000, v248
	global_store_dwordx4 v250, v[2:5], s[20:21] offset:0
	s_waitcnt vmcnt(11)
	v_pk_mul_f32 v[12:13], v[12:13], s[14:15] op_sel_hi:[1,0]
	v_pk_mul_f32 v[10:11], v[10:11], s[14:15] op_sel_hi:[1,0]
	v_pk_mul_f32 v[16:17], v[16:17], s[14:15] op_sel_hi:[1,0]
	v_pk_mul_f32 v[14:15], v[14:15], s[14:15] op_sel_hi:[1,0]
	v_pk_fma_f32 v[12:13], v[56:57], s[16:17], v[12:13] op_sel_hi:[1,0,1]
	v_pk_fma_f32 v[10:11], v[54:55], s[16:17], v[10:11] op_sel_hi:[1,0,1]
	v_pk_fma_f32 v[16:17], v[52:53], s[16:17], v[16:17] op_sel_hi:[1,0,1]
	v_pk_fma_f32 v[14:15], v[50:51], s[16:17], v[14:15] op_sel_hi:[1,0,1]
	v_cvt_pk_bf16_f32 v10, v10, v11
	v_cvt_pk_bf16_f32 v11, v12, v13
	v_cvt_pk_bf16_f32 v12, v14, v15
	v_cvt_pk_bf16_f32 v13, v16, v17
	global_store_dwordx4 v250, v[10:13], s[20:21] offset:256
	s_waitcnt vmcnt(9)
	v_pk_mul_f32 v[20:21], v[20:21], s[14:15] op_sel_hi:[1,0]
	v_pk_mul_f32 v[18:19], v[18:19], s[14:15] op_sel_hi:[1,0]
	v_pk_mul_f32 v[24:25], v[24:25], s[14:15] op_sel_hi:[1,0]
	v_pk_mul_f32 v[22:23], v[22:23], s[14:15] op_sel_hi:[1,0]
	v_pk_fma_f32 v[20:21], v[48:49], s[16:17], v[20:21] op_sel_hi:[1,0,1]
	v_pk_fma_f32 v[18:19], v[46:47], s[16:17], v[18:19] op_sel_hi:[1,0,1]
	v_pk_fma_f32 v[24:25], v[44:45], s[16:17], v[24:25] op_sel_hi:[1,0,1]
	v_pk_fma_f32 v[22:23], v[42:43], s[16:17], v[22:23] op_sel_hi:[1,0,1]
	v_cvt_pk_bf16_f32 v18, v18, v19
	v_cvt_pk_bf16_f32 v19, v20, v21
	v_cvt_pk_bf16_f32 v20, v22, v23
	v_cvt_pk_bf16_f32 v21, v24, v25
	v_add_u32_e32 v250, 0xb0000, v248
	global_store_dwordx4 v250, v[18:21], s[20:21] offset:0
	s_waitcnt vmcnt(7)
	v_pk_mul_f32 v[28:29], v[28:29], s[14:15] op_sel_hi:[1,0]
	v_pk_mul_f32 v[26:27], v[26:27], s[14:15] op_sel_hi:[1,0]
	v_pk_mul_f32 v[32:33], v[32:33], s[14:15] op_sel_hi:[1,0]
	v_pk_mul_f32 v[30:31], v[30:31], s[14:15] op_sel_hi:[1,0]
	v_pk_fma_f32 v[28:29], v[40:41], s[16:17], v[28:29] op_sel_hi:[1,0,1]
	v_pk_fma_f32 v[26:27], v[38:39], s[16:17], v[26:27] op_sel_hi:[1,0,1]
	v_pk_fma_f32 v[32:33], v[36:37], s[16:17], v[32:33] op_sel_hi:[1,0,1]
	v_pk_fma_f32 v[30:31], v[34:35], s[16:17], v[30:31] op_sel_hi:[1,0,1]
	v_cvt_pk_bf16_f32 v26, v26, v27
	v_cvt_pk_bf16_f32 v27, v28, v29
	v_cvt_pk_bf16_f32 v28, v30, v31
	v_cvt_pk_bf16_f32 v29, v32, v33
	global_store_dwordx4 v250, v[26:29], s[20:21] offset:256
	s_cbranch_vccnz .LBB0_524
	s_andn2_b64 vcc, exec, s[8:9]
	s_cbranch_vccnz .LBB0_523
	s_barrier
	s_branch .LBB0_523

.LBB0_1012:
	v_cndmask_b32_e64 v103, v97, v93, s[0:1]
	v_cndmask_b32_e64 v104, v87, v85, s[0:1]
	v_cndmask_b32_e64 v105, v99, v95, s[0:1]
	v_cndmask_b32_e64 v106, v92, v86, s[0:1]
	v_cndmask_b32_e64 v107, v98, v94, s[0:1]
	v_cndmask_b32_e64 v108, v91, v89, s[0:1]
	v_cndmask_b32_e64 v109, v100, v96, s[0:1]
	v_cndmask_b32_e64 v110, v88, v90, s[0:1]
	s_xor_b64 s[8:9], s[0:1], -1
	s_lshl_b32 s0, s10, 11
	s_add_i32 s0, s26, s0
	v_mov_b32_e32 v252, s0
	s_add_u32 s14, s72, 0x4300000
	s_addc_u32 s15, s73, 0
	v_mbcnt_lo_u32_b32 v114, -1, 0
	v_mbcnt_hi_u32_b32 v114, -1, v114
	v_lshlrev_b32_e32 v253, 4, v114
	v_readlane_b32 s4, v103, 0
	s_lshr_b32 s4, s4, 7
	s_lshl_b32 s4, s4, 10
	s_add_u32 s24, s14, s4
	s_addc_u32 s25, s15, 0
	global_load_dwordx4 v[132:135], v253, s[24:25]
	v_readlane_b32 s4, v104, 0
	s_lshr_b32 s4, s4, 7
	s_lshl_b32 s4, s4, 10
	s_add_u32 s24, s14, s4
	s_addc_u32 s25, s15, 0
	global_load_dwordx4 v[136:139], v253, s[24:25]
	v_readlane_b32 s4, v105, 0
	s_lshr_b32 s4, s4, 7
	s_lshl_b32 s4, s4, 10
	s_add_u32 s24, s14, s4
	s_addc_u32 s25, s15, 0
	global_load_dwordx4 v[140:143], v253, s[24:25]
	v_readlane_b32 s4, v106, 0
	s_lshr_b32 s4, s4, 7
	s_lshl_b32 s4, s4, 10
	s_add_u32 s24, s14, s4
	s_addc_u32 s25, s15, 0
	global_load_dwordx4 v[144:147], v253, s[24:25]
	v_readlane_b32 s4, v103, 1
	s_lshr_b32 s4, s4, 7
	s_lshl_b32 s4, s4, 10
	s_add_u32 s24, s14, s4
	s_addc_u32 s25, s15, 0
	global_load_dwordx4 v[72:75], v253, s[24:25]
	v_readlane_b32 s4, v104, 1
	s_lshr_b32 s4, s4, 7
	s_lshl_b32 s4, s4, 10
	s_add_u32 s24, s14, s4
	s_addc_u32 s25, s15, 0
	global_load_dwordx4 v[156:159], v253, s[24:25]
	v_readlane_b32 s4, v105, 1
	s_lshr_b32 s4, s4, 7
	s_lshl_b32 s4, s4, 10
	s_add_u32 s24, s14, s4
	s_addc_u32 s25, s15, 0
	global_load_dwordx4 v[236:239], v253, s[24:25]
	ds_read_b32 v112, v252
	v_and_b32_e32 v148, 31, v114
	v_and_b32_e32 v149, 3, v148
	v_lshrrev_b32_e32 v162, 3, v148
	v_lshl_add_u32 v149, v162, 2, v149
	v_bfe_u32 v162, v148, 2, 1
	v_lshl_add_u32 v149, v162, 4, v149
	v_and_b32_e32 v162, 7, v149
	v_lshlrev_b32_e32 v162, 2, v162
	v_mov_b32_e32 v148, 2
	v_lshlrev_b32_e32 v162, v162, v148
	v_lshrrev_b32_e32 v148, 3, v149
	v_cmp_gt_u32_e32 vcc, 32, v114
	s_nop 3
	v_cmp_eq_u32_e64 s[24:25], 0, v148
	s_nop 3
	s_and_b64 s[0:1], s[24:25], vcc
	s_andn2_b64 s[24:25], s[24:25], vcc
	s_nop 1
	v_cndmask_b32_e64 v244, 0, v162, s[0:1]
	v_cndmask_b32_e64 v248, 0, v162, s[24:25]
	v_cmp_eq_u32_e64 s[24:25], 1, v148
	s_nop 3
	s_and_b64 s[0:1], s[24:25], vcc
	s_andn2_b64 s[24:25], s[24:25], vcc
	s_nop 1
	v_cndmask_b32_e64 v245, 0, v162, s[0:1]
	v_cndmask_b32_e64 v249, 0, v162, s[24:25]
	v_cmp_eq_u32_e64 s[24:25], 2, v148
	s_nop 3
	s_and_b64 s[0:1], s[24:25], vcc
	s_andn2_b64 s[24:25], s[24:25], vcc
	s_nop 1
	v_cndmask_b32_e64 v246, 0, v162, s[0:1]
	v_cndmask_b32_e64 v250, 0, v162, s[24:25]
	v_cmp_eq_u32_e64 s[24:25], 3, v148
	s_nop 3
	s_and_b64 s[0:1], s[24:25], vcc
	s_andn2_b64 s[24:25], s[24:25], vcc
	s_nop 1
	v_cndmask_b32_e64 v247, 0, v162, s[0:1]
	v_cndmask_b32_e64 v251, 0, v162, s[24:25]
	v_mov_b32_e32 v0, 0
	v_mov_b32_e32 v1, 0
	v_mov_b32_e32 v2, 0
	v_mov_b32_e32 v3, 0
	v_mov_b32_e32 v4, 0
	v_mov_b32_e32 v5, 0
	v_mov_b32_e32 v6, 0
	v_mov_b32_e32 v7, 0
	v_mov_b32_e32 v8, 0
	v_mov_b32_e32 v9, 0
	v_mov_b32_e32 v10, 0
	v_mov_b32_e32 v11, 0
	v_mov_b32_e32 v12, 0
	v_mov_b32_e32 v13, 0
	v_mov_b32_e32 v14, 0
	v_mov_b32_e32 v15, 0
	v_mov_b32_e32 v16, 0
	v_mov_b32_e32 v17, 0
	v_mov_b32_e32 v18, 0
	v_mov_b32_e32 v19, 0
	v_mov_b32_e32 v20, 0
	v_mov_b32_e32 v21, 0
	v_mov_b32_e32 v22, 0
	v_mov_b32_e32 v23, 0
	v_mov_b32_e32 v24, 0
	v_mov_b32_e32 v25, 0
	v_mov_b32_e32 v26, 0
	v_mov_b32_e32 v27, 0
	v_mov_b32_e32 v28, 0
	v_mov_b32_e32 v29, 0
	v_mov_b32_e32 v30, 0
	v_mov_b32_e32 v31, 0
	v_mov_b32_e32 v164, 0
	v_mov_b32_e32 v165, 0
	v_mov_b32_e32 v166, 0
	v_mov_b32_e32 v167, 0
	v_mov_b32_e32 v168, 0
	v_mov_b32_e32 v169, 0
	v_mov_b32_e32 v170, 0
	v_mov_b32_e32 v171, 0
	v_mov_b32_e32 v172, 0
	v_mov_b32_e32 v173, 0
	v_mov_b32_e32 v174, 0
	v_mov_b32_e32 v175, 0
	v_mov_b32_e32 v176, 0
	v_mov_b32_e32 v177, 0
	v_mov_b32_e32 v178, 0
	v_mov_b32_e32 v179, 0
	v_mov_b32_e32 v180, 0
	v_mov_b32_e32 v181, 0
	v_mov_b32_e32 v182, 0
	v_mov_b32_e32 v183, 0
	v_mov_b32_e32 v184, 0
	v_mov_b32_e32 v185, 0
	v_mov_b32_e32 v186, 0
	v_mov_b32_e32 v187, 0
	v_mov_b32_e32 v188, 0
	v_mov_b32_e32 v189, 0
	v_mov_b32_e32 v190, 0
	v_mov_b32_e32 v191, 0
	v_mov_b32_e32 v192, 0
	v_mov_b32_e32 v193, 0
	v_mov_b32_e32 v194, 0
	v_mov_b32_e32 v195, 0
	v_mov_b32_e32 v196, 0
	v_mov_b32_e32 v197, 0
	v_mov_b32_e32 v198, 0
	v_mov_b32_e32 v199, 0
	v_mov_b32_e32 v200, 0
	v_mov_b32_e32 v201, 0
	v_mov_b32_e32 v202, 0
	v_mov_b32_e32 v203, 0
	v_mov_b32_e32 v204, 0
	v_mov_b32_e32 v205, 0
	v_mov_b32_e32 v206, 0
	v_mov_b32_e32 v207, 0
	v_mov_b32_e32 v208, 0
	v_mov_b32_e32 v209, 0
	v_mov_b32_e32 v210, 0
	v_mov_b32_e32 v211, 0
	v_mov_b32_e32 v212, 0
	v_mov_b32_e32 v213, 0
	v_mov_b32_e32 v214, 0
	v_mov_b32_e32 v215, 0
	v_mov_b32_e32 v216, 0
	v_mov_b32_e32 v217, 0
	v_mov_b32_e32 v218, 0
	v_mov_b32_e32 v219, 0
	v_mov_b32_e32 v220, 0
	v_mov_b32_e32 v221, 0
	v_mov_b32_e32 v222, 0
	v_mov_b32_e32 v223, 0
	v_mov_b32_e32 v224, 0
	v_mov_b32_e32 v225, 0
	v_mov_b32_e32 v226, 0
	v_mov_b32_e32 v227, 0
	v_mov_b32_e32 v32, 0
	v_mov_b32_e32 v33, 0
	v_mov_b32_e32 v34, 0
	v_mov_b32_e32 v35, 0
	v_mov_b32_e32 v36, 0
	v_mov_b32_e32 v37, 0
	v_mov_b32_e32 v38, 0
	v_mov_b32_e32 v39, 0
	v_mov_b32_e32 v40, 0
	v_mov_b32_e32 v41, 0
	v_mov_b32_e32 v42, 0
	v_mov_b32_e32 v43, 0
	v_mov_b32_e32 v44, 0
	v_mov_b32_e32 v45, 0
	v_mov_b32_e32 v46, 0
	v_mov_b32_e32 v47, 0
	v_mov_b32_e32 v48, 0
	v_mov_b32_e32 v49, 0
	v_mov_b32_e32 v50, 0
	v_mov_b32_e32 v51, 0
	v_mov_b32_e32 v52, 0
	v_mov_b32_e32 v53, 0
	v_mov_b32_e32 v54, 0
	v_mov_b32_e32 v55, 0
	v_mov_b32_e32 v228, 0
	v_mov_b32_e32 v229, 0
	v_mov_b32_e32 v230, 0
	v_mov_b32_e32 v231, 0
	v_mov_b32_e32 v232, 0
	v_mov_b32_e32 v233, 0
	v_mov_b32_e32 v234, 0
	v_mov_b32_e32 v235, 0
	v_mov_b32_e32 v116, 0
	v_mov_b32_e32 v117, 0
	v_mov_b32_e32 v118, 0
	v_mov_b32_e32 v119, 0
	v_mov_b32_e32 v120, 0
	v_mov_b32_e32 v121, 0
	v_mov_b32_e32 v122, 0
	v_mov_b32_e32 v123, 0
	v_mov_b32_e32 v124, 0
	v_mov_b32_e32 v125, 0
	v_mov_b32_e32 v126, 0
	v_mov_b32_e32 v127, 0
	v_mov_b32_e32 v128, 0
	v_mov_b32_e32 v129, 0
	v_mov_b32_e32 v130, 0
	v_mov_b32_e32 v131, 0
	v_mov_b32_e32 v160, 0
	s_mov_b32 s11, 0
.Lmy_vloop:
	s_cmp_lt_u32 s11, 4
	s_cselect_b64 vcc, -1, 0
	s_lshl_b32 s13, s11, 4
	s_and_b32 s13, s13, 63
	s_add_i32 s23, s13, 16
	s_and_b32 s23, s23, 63
	v_cndmask_b32_e32 v111, v107, v103, vcc
	v_cndmask_b32_e32 v115, v108, v104, vcc
	v_cndmask_b32_e32 v150, v109, v105, vcc
	v_cndmask_b32_e32 v151, v110, v106, vcc
	s_cmp_lt_u32 s11, 3
	s_cselect_b64 vcc, -1, 0
	s_nop 1
	v_cndmask_b32_e32 v152, v107, v103, vcc
	v_cndmask_b32_e32 v153, v108, v104, vcc
	v_cndmask_b32_e32 v154, v109, v105, vcc
	v_cndmask_b32_e32 v155, v110, v106, vcc
	s_waitcnt vmcnt(6)
	v_mfma_f32_32x32x64_f8f6f4 v[56:71], v[244:247], v[132:135], 0 cbsz:4 blgp:4
	s_add_i32 s1, s13, 1
	s_nop 0
	v_readlane_b32 s4, v151, s1
	v_pk_fma_f32 v[48:49], v[116:117], v[160:161], v[48:49] op_sel_hi:[1,0,1]
	s_lshr_b32 s4, s4, 7
	v_pk_fma_f32 v[50:51], v[118:119], v[160:161], v[50:51] op_sel_hi:[1,0,1]
	s_lshl_b32 s4, s4, 10
	v_pk_fma_f32 v[52:53], v[120:121], v[160:161], v[52:53] op_sel_hi:[1,0,1]
	s_add_u32 s24, s14, s4
	v_pk_fma_f32 v[54:55], v[122:123], v[160:161], v[54:55] op_sel_hi:[1,0,1]
	s_addc_u32 s25, s15, 0
	v_pk_fma_f32 v[228:229], v[124:125], v[160:161], v[228:229] op_sel_hi:[1,0,1]
	v_pk_fma_f32 v[230:231], v[126:127], v[160:161], v[230:231] op_sel_hi:[1,0,1]
	v_pk_fma_f32 v[232:233], v[128:129], v[160:161], v[232:233] op_sel_hi:[1,0,1]
	v_pk_fma_f32 v[234:235], v[130:131], v[160:161], v[234:235] op_sel_hi:[1,0,1]
	v_mfma_f32_32x32x64_f8f6f4 v[116:131], v[248:251], v[132:135], 0 cbsz:4 blgp:4
	global_load_dwordx4 v[240:243], v253, s[24:25]
	s_waitcnt lgkmcnt(0)
	v_cvt_f32_f16_e32 v254, v112
	ds_read_b32 v113, v252 offset:512
	v_pk_fma_f32 v[0:1], v[56:57], v[254:255], v[0:1] op_sel_hi:[1,0,1]
	v_pk_fma_f32 v[2:3], v[58:59], v[254:255], v[2:3] op_sel_hi:[1,0,1]
	v_pk_fma_f32 v[4:5], v[60:61], v[254:255], v[4:5] op_sel_hi:[1,0,1]
	v_pk_fma_f32 v[6:7], v[62:63], v[254:255], v[6:7] op_sel_hi:[1,0,1]
	v_pk_fma_f32 v[8:9], v[64:65], v[254:255], v[8:9] op_sel_hi:[1,0,1]
	v_pk_fma_f32 v[10:11], v[66:67], v[254:255], v[10:11] op_sel_hi:[1,0,1]
	v_pk_fma_f32 v[12:13], v[68:69], v[254:255], v[12:13] op_sel_hi:[1,0,1]
	v_pk_fma_f32 v[14:15], v[70:71], v[254:255], v[14:15] op_sel_hi:[1,0,1]
	s_waitcnt vmcnt(6)
	v_mfma_f32_32x32x64_f8f6f4 v[56:71], v[244:247], v[136:139], 0 cbsz:4 blgp:4
	s_add_i32 s1, s13, 2
	s_nop 0
	v_readlane_b32 s4, v111, s1
	v_pk_fma_f32 v[16:17], v[116:117], v[254:255], v[16:17] op_sel_hi:[1,0,1]
	s_lshr_b32 s4, s4, 7
	v_pk_fma_f32 v[18:19], v[118:119], v[254:255], v[18:19] op_sel_hi:[1,0,1]
	s_lshl_b32 s4, s4, 10
	v_pk_fma_f32 v[20:21], v[120:121], v[254:255], v[20:21] op_sel_hi:[1,0,1]
	s_add_u32 s24, s14, s4
	v_pk_fma_f32 v[22:23], v[122:123], v[254:255], v[22:23] op_sel_hi:[1,0,1]
	s_addc_u32 s25, s15, 0
	v_pk_fma_f32 v[24:25], v[124:125], v[254:255], v[24:25] op_sel_hi:[1,0,1]
	v_pk_fma_f32 v[26:27], v[126:127], v[254:255], v[26:27] op_sel_hi:[1,0,1]
	v_pk_fma_f32 v[28:29], v[128:129], v[254:255], v[28:29] op_sel_hi:[1,0,1]
	v_pk_fma_f32 v[30:31], v[130:131], v[254:255], v[30:31] op_sel_hi:[1,0,1]
	v_mfma_f32_32x32x64_f8f6f4 v[116:131], v[248:251], v[136:139], 0 cbsz:4 blgp:4
	global_load_dwordx4 v[132:135], v253, s[24:25]
	s_waitcnt lgkmcnt(0)
	v_cvt_f32_f16_e32 v160, v113
	ds_read_b32 v112, v252 offset:1024
	v_pk_fma_f32 v[164:165], v[56:57], v[160:161], v[164:165] op_sel_hi:[1,0,1]
	v_pk_fma_f32 v[166:167], v[58:59], v[160:161], v[166:167] op_sel_hi:[1,0,1]
	v_pk_fma_f32 v[168:169], v[60:61], v[160:161], v[168:169] op_sel_hi:[1,0,1]
	v_pk_fma_f32 v[170:171], v[62:63], v[160:161], v[170:171] op_sel_hi:[1,0,1]
	v_pk_fma_f32 v[172:173], v[64:65], v[160:161], v[172:173] op_sel_hi:[1,0,1]
	v_pk_fma_f32 v[174:175], v[66:67], v[160:161], v[174:175] op_sel_hi:[1,0,1]
	v_pk_fma_f32 v[176:177], v[68:69], v[160:161], v[176:177] op_sel_hi:[1,0,1]
	v_pk_fma_f32 v[178:179], v[70:71], v[160:161], v[178:179] op_sel_hi:[1,0,1]
	s_waitcnt vmcnt(6)
	v_mfma_f32_32x32x64_f8f6f4 v[56:71], v[244:247], v[140:143], 0 cbsz:4 blgp:4
	s_add_i32 s1, s13, 2
	s_nop 0
	v_readlane_b32 s4, v115, s1
	v_pk_fma_f32 v[180:181], v[116:117], v[160:161], v[180:181] op_sel_hi:[1,0,1]
	s_lshr_b32 s4, s4, 7
	v_pk_fma_f32 v[182:183], v[118:119], v[160:161], v[182:183] op_sel_hi:[1,0,1]
	s_lshl_b32 s4, s4, 10
	v_pk_fma_f32 v[184:185], v[120:121], v[160:161], v[184:185] op_sel_hi:[1,0,1]
	s_add_u32 s24, s14, s4
	v_pk_fma_f32 v[186:187], v[122:123], v[160:161], v[186:187] op_sel_hi:[1,0,1]
	s_addc_u32 s25, s15, 0
	v_pk_fma_f32 v[188:189], v[124:125], v[160:161], v[188:189] op_sel_hi:[1,0,1]
	v_pk_fma_f32 v[190:191], v[126:127], v[160:161], v[190:191] op_sel_hi:[1,0,1]
	v_pk_fma_f32 v[192:193], v[128:129], v[160:161], v[192:193] op_sel_hi:[1,0,1]
	v_pk_fma_f32 v[194:195], v[130:131], v[160:161], v[194:195] op_sel_hi:[1,0,1]
	v_mfma_f32_32x32x64_f8f6f4 v[116:131], v[248:251], v[140:143], 0 cbsz:4 blgp:4
	global_load_dwordx4 v[136:139], v253, s[24:25]
	s_waitcnt lgkmcnt(0)
	v_cvt_f32_f16_e32 v254, v112
	ds_read_b32 v113, v252 offset:1536
	v_pk_fma_f32 v[196:197], v[56:57], v[254:255], v[196:197] op_sel_hi:[1,0,1]
	v_pk_fma_f32 v[198:199], v[58:59], v[254:255], v[198:199] op_sel_hi:[1,0,1]
	v_pk_fma_f32 v[200:201], v[60:61], v[254:255], v[200:201] op_sel_hi:[1,0,1]
	v_pk_fma_f32 v[202:203], v[62:63], v[254:255], v[202:203] op_sel_hi:[1,0,1]
	v_pk_fma_f32 v[204:205], v[64:65], v[254:255], v[204:205] op_sel_hi:[1,0,1]
	v_pk_fma_f32 v[206:207], v[66:67], v[254:255], v[206:207] op_sel_hi:[1,0,1]
	v_pk_fma_f32 v[208:209], v[68:69], v[254:255], v[208:209] op_sel_hi:[1,0,1]
	v_pk_fma_f32 v[210:211], v[70:71], v[254:255], v[210:211] op_sel_hi:[1,0,1]
	s_waitcnt vmcnt(6)
	v_mfma_f32_32x32x64_f8f6f4 v[56:71], v[244:247], v[144:147], 0 cbsz:4 blgp:4
	s_add_i32 s1, s13, 2
	s_nop 0
	v_readlane_b32 s4, v150, s1
	v_pk_fma_f32 v[212:213], v[116:117], v[254:255], v[212:213] op_sel_hi:[1,0,1]
	s_lshr_b32 s4, s4, 7
	v_pk_fma_f32 v[214:215], v[118:119], v[254:255], v[214:215] op_sel_hi:[1,0,1]
	s_lshl_b32 s4, s4, 10
	v_pk_fma_f32 v[216:217], v[120:121], v[254:255], v[216:217] op_sel_hi:[1,0,1]
	s_add_u32 s24, s14, s4
	v_pk_fma_f32 v[218:219], v[122:123], v[254:255], v[218:219] op_sel_hi:[1,0,1]
	s_addc_u32 s25, s15, 0
	v_pk_fma_f32 v[220:221], v[124:125], v[254:255], v[220:221] op_sel_hi:[1,0,1]
	v_pk_fma_f32 v[222:223], v[126:127], v[254:255], v[222:223] op_sel_hi:[1,0,1]
	v_pk_fma_f32 v[224:225], v[128:129], v[254:255], v[224:225] op_sel_hi:[1,0,1]
	v_pk_fma_f32 v[226:227], v[130:131], v[254:255], v[226:227] op_sel_hi:[1,0,1]
	v_mfma_f32_32x32x64_f8f6f4 v[116:131], v[248:251], v[144:147], 0 cbsz:4 blgp:4
	global_load_dwordx4 v[140:143], v253, s[24:25]
	s_waitcnt lgkmcnt(0)
	v_cvt_f32_f16_e32 v160, v113
	ds_read_b32 v112, v252 offset:4
	v_pk_fma_f32 v[32:33], v[56:57], v[160:161], v[32:33] op_sel_hi:[1,0,1]
	v_pk_fma_f32 v[34:35], v[58:59], v[160:161], v[34:35] op_sel_hi:[1,0,1]
	v_pk_fma_f32 v[36:37], v[60:61], v[160:161], v[36:37] op_sel_hi:[1,0,1]
	v_pk_fma_f32 v[38:39], v[62:63], v[160:161], v[38:39] op_sel_hi:[1,0,1]
	v_pk_fma_f32 v[40:41], v[64:65], v[160:161], v[40:41] op_sel_hi:[1,0,1]
	v_pk_fma_f32 v[42:43], v[66:67], v[160:161], v[42:43] op_sel_hi:[1,0,1]
	v_pk_fma_f32 v[44:45], v[68:69], v[160:161], v[44:45] op_sel_hi:[1,0,1]
	v_pk_fma_f32 v[46:47], v[70:71], v[160:161], v[46:47] op_sel_hi:[1,0,1]
	s_waitcnt vmcnt(6)
	v_mfma_f32_32x32x64_f8f6f4 v[56:71], v[244:247], v[72:75], 0 cbsz:4 blgp:4
	s_add_i32 s1, s13, 2
	s_nop 0
	v_readlane_b32 s4, v151, s1
	v_pk_fma_f32 v[48:49], v[116:117], v[160:161], v[48:49] op_sel_hi:[1,0,1]
	s_lshr_b32 s4, s4, 7
	v_pk_fma_f32 v[50:51], v[118:119], v[160:161], v[50:51] op_sel_hi:[1,0,1]
	s_lshl_b32 s4, s4, 10
	v_pk_fma_f32 v[52:53], v[120:121], v[160:161], v[52:53] op_sel_hi:[1,0,1]
	s_add_u32 s24, s14, s4
	v_pk_fma_f32 v[54:55], v[122:123], v[160:161], v[54:55] op_sel_hi:[1,0,1]
	s_addc_u32 s25, s15, 0
	v_pk_fma_f32 v[228:229], v[124:125], v[160:161], v[228:229] op_sel_hi:[1,0,1]
	v_pk_fma_f32 v[230:231], v[126:127], v[160:161], v[230:231] op_sel_hi:[1,0,1]
	v_pk_fma_f32 v[232:233], v[128:129], v[160:161], v[232:233] op_sel_hi:[1,0,1]
	v_pk_fma_f32 v[234:235], v[130:131], v[160:161], v[234:235] op_sel_hi:[1,0,1]
	v_mfma_f32_32x32x64_f8f6f4 v[116:131], v[248:251], v[72:75], 0 cbsz:4 blgp:4
	global_load_dwordx4 v[144:147], v253, s[24:25]
	s_waitcnt lgkmcnt(0)
	v_cvt_f32_f16_e32 v254, v112
	ds_read_b32 v113, v252 offset:516
	v_pk_fma_f32 v[0:1], v[56:57], v[254:255], v[0:1] op_sel_hi:[1,0,1]
	v_pk_fma_f32 v[2:3], v[58:59], v[254:255], v[2:3] op_sel_hi:[1,0,1]
	v_pk_fma_f32 v[4:5], v[60:61], v[254:255], v[4:5] op_sel_hi:[1,0,1]
	v_pk_fma_f32 v[6:7], v[62:63], v[254:255], v[6:7] op_sel_hi:[1,0,1]
	v_pk_fma_f32 v[8:9], v[64:65], v[254:255], v[8:9] op_sel_hi:[1,0,1]
	v_pk_fma_f32 v[10:11], v[66:67], v[254:255], v[10:11] op_sel_hi:[1,0,1]
	v_pk_fma_f32 v[12:13], v[68:69], v[254:255], v[12:13] op_sel_hi:[1,0,1]
	v_pk_fma_f32 v[14:15], v[70:71], v[254:255], v[14:15] op_sel_hi:[1,0,1]
	s_waitcnt vmcnt(6)
	v_mfma_f32_32x32x64_f8f6f4 v[56:71], v[244:247], v[156:159], 0 cbsz:4 blgp:4
	s_add_i32 s1, s13, 3
	s_nop 0
	v_readlane_b32 s4, v111, s1
	v_pk_fma_f32 v[16:17], v[116:117], v[254:255], v[16:17] op_sel_hi:[1,0,1]
	s_lshr_b32 s4, s4, 7
	v_pk_fma_f32 v[18:19], v[118:119], v[254:255], v[18:19] op_sel_hi:[1,0,1]
	s_lshl_b32 s4, s4, 10
	v_pk_fma_f32 v[20:21], v[120:121], v[254:255], v[20:21] op_sel_hi:[1,0,1]
	s_add_u32 s24, s14, s4
	v_pk_fma_f32 v[22:23], v[122:123], v[254:255], v[22:23] op_sel_hi:[1,0,1]
	s_addc_u32 s25, s15, 0
	v_pk_fma_f32 v[24:25], v[124:125], v[254:255], v[24:25] op_sel_hi:[1,0,1]
	v_pk_fma_f32 v[26:27], v[126:127], v[254:255], v[26:27] op_sel_hi:[1,0,1]
	v_pk_fma_f32 v[28:29], v[128:129], v[254:255], v[28:29] op_sel_hi:[1,0,1]
	v_pk_fma_f32 v[30:31], v[130:131], v[254:255], v[30:31] op_sel_hi:[1,0,1]
	v_mfma_f32_32x32x64_f8f6f4 v[116:131], v[248:251], v[156:159], 0 cbsz:4 blgp:4
	global_load_dwordx4 v[72:75], v253, s[24:25]
	s_waitcnt lgkmcnt(0)
	v_cvt_f32_f16_e32 v160, v113
	ds_read_b32 v112, v252 offset:1028
	v_pk_fma_f32 v[164:165], v[56:57], v[160:161], v[164:165] op_sel_hi:[1,0,1]
	v_pk_fma_f32 v[166:167], v[58:59], v[160:161], v[166:167] op_sel_hi:[1,0,1]
	v_pk_fma_f32 v[168:169], v[60:61], v[160:161], v[168:169] op_sel_hi:[1,0,1]
	v_pk_fma_f32 v[170:171], v[62:63], v[160:161], v[170:171] op_sel_hi:[1,0,1]
	v_pk_fma_f32 v[172:173], v[64:65], v[160:161], v[172:173] op_sel_hi:[1,0,1]
	v_pk_fma_f32 v[174:175], v[66:67], v[160:161], v[174:175] op_sel_hi:[1,0,1]
	v_pk_fma_f32 v[176:177], v[68:69], v[160:161], v[176:177] op_sel_hi:[1,0,1]
	v_pk_fma_f32 v[178:179], v[70:71], v[160:161], v[178:179] op_sel_hi:[1,0,1]
	s_waitcnt vmcnt(6)
	v_mfma_f32_32x32x64_f8f6f4 v[56:71], v[244:247], v[236:239], 0 cbsz:4 blgp:4
	s_add_i32 s1, s13, 3
	s_nop 0
	v_readlane_b32 s4, v115, s1
	v_pk_fma_f32 v[180:181], v[116:117], v[160:161], v[180:181] op_sel_hi:[1,0,1]
	s_lshr_b32 s4, s4, 7
	v_pk_fma_f32 v[182:183], v[118:119], v[160:161], v[182:183] op_sel_hi:[1,0,1]
	s_lshl_b32 s4, s4, 10
	v_pk_fma_f32 v[184:185], v[120:121], v[160:161], v[184:185] op_sel_hi:[1,0,1]
	s_add_u32 s24, s14, s4
	v_pk_fma_f32 v[186:187], v[122:123], v[160:161], v[186:187] op_sel_hi:[1,0,1]
	s_addc_u32 s25, s15, 0
	v_pk_fma_f32 v[188:189], v[124:125], v[160:161], v[188:189] op_sel_hi:[1,0,1]
	v_pk_fma_f32 v[190:191], v[126:127], v[160:161], v[190:191] op_sel_hi:[1,0,1]
	v_pk_fma_f32 v[192:193], v[128:129], v[160:161], v[192:193] op_sel_hi:[1,0,1]
	v_pk_fma_f32 v[194:195], v[130:131], v[160:161], v[194:195] op_sel_hi:[1,0,1]
	v_mfma_f32_32x32x64_f8f6f4 v[116:131], v[248:251], v[236:239], 0 cbsz:4 blgp:4
	global_load_dwordx4 v[156:159], v253, s[24:25]
	s_waitcnt lgkmcnt(0)
	v_cvt_f32_f16_e32 v254, v112
	ds_read_b32 v113, v252 offset:1540
	v_pk_fma_f32 v[196:197], v[56:57], v[254:255], v[196:197] op_sel_hi:[1,0,1]
	v_pk_fma_f32 v[198:199], v[58:59], v[254:255], v[198:199] op_sel_hi:[1,0,1]
	v_pk_fma_f32 v[200:201], v[60:61], v[254:255], v[200:201] op_sel_hi:[1,0,1]
	v_pk_fma_f32 v[202:203], v[62:63], v[254:255], v[202:203] op_sel_hi:[1,0,1]
	v_pk_fma_f32 v[204:205], v[64:65], v[254:255], v[204:205] op_sel_hi:[1,0,1]
	v_pk_fma_f32 v[206:207], v[66:67], v[254:255], v[206:207] op_sel_hi:[1,0,1]
	v_pk_fma_f32 v[208:209], v[68:69], v[254:255], v[208:209] op_sel_hi:[1,0,1]
	v_pk_fma_f32 v[210:211], v[70:71], v[254:255], v[210:211] op_sel_hi:[1,0,1]
	s_waitcnt vmcnt(6)
	v_mfma_f32_32x32x64_f8f6f4 v[56:71], v[244:247], v[240:243], 0 cbsz:4 blgp:4
	s_add_i32 s1, s13, 3
	s_nop 0
	v_readlane_b32 s4, v150, s1
	v_pk_fma_f32 v[212:213], v[116:117], v[254:255], v[212:213] op_sel_hi:[1,0,1]
	s_lshr_b32 s4, s4, 7
	v_pk_fma_f32 v[214:215], v[118:119], v[254:255], v[214:215] op_sel_hi:[1,0,1]
	s_lshl_b32 s4, s4, 10
	v_pk_fma_f32 v[216:217], v[120:121], v[254:255], v[216:217] op_sel_hi:[1,0,1]
	s_add_u32 s24, s14, s4
	v_pk_fma_f32 v[218:219], v[122:123], v[254:255], v[218:219] op_sel_hi:[1,0,1]
	s_addc_u32 s25, s15, 0
	v_pk_fma_f32 v[220:221], v[124:125], v[254:255], v[220:221] op_sel_hi:[1,0,1]
	v_pk_fma_f32 v[222:223], v[126:127], v[254:255], v[222:223] op_sel_hi:[1,0,1]
	v_pk_fma_f32 v[224:225], v[128:129], v[254:255], v[224:225] op_sel_hi:[1,0,1]
	v_pk_fma_f32 v[226:227], v[130:131], v[254:255], v[226:227] op_sel_hi:[1,0,1]
	v_mfma_f32_32x32x64_f8f6f4 v[116:131], v[248:251], v[240:243], 0 cbsz:4 blgp:4
	global_load_dwordx4 v[236:239], v253, s[24:25]
	s_waitcnt lgkmcnt(0)
	v_cvt_f32_f16_e32 v160, v113
	ds_read_b32 v112, v252 offset:8
	v_pk_fma_f32 v[32:33], v[56:57], v[160:161], v[32:33] op_sel_hi:[1,0,1]
	v_pk_fma_f32 v[34:35], v[58:59], v[160:161], v[34:35] op_sel_hi:[1,0,1]
	v_pk_fma_f32 v[36:37], v[60:61], v[160:161], v[36:37] op_sel_hi:[1,0,1]
	v_pk_fma_f32 v[38:39], v[62:63], v[160:161], v[38:39] op_sel_hi:[1,0,1]
	v_pk_fma_f32 v[40:41], v[64:65], v[160:161], v[40:41] op_sel_hi:[1,0,1]
	v_pk_fma_f32 v[42:43], v[66:67], v[160:161], v[42:43] op_sel_hi:[1,0,1]
	v_pk_fma_f32 v[44:45], v[68:69], v[160:161], v[44:45] op_sel_hi:[1,0,1]
	v_pk_fma_f32 v[46:47], v[70:71], v[160:161], v[46:47] op_sel_hi:[1,0,1]
	s_waitcnt vmcnt(6)
	v_mfma_f32_32x32x64_f8f6f4 v[56:71], v[244:247], v[132:135], 0 cbsz:4 blgp:4
	s_add_i32 s1, s13, 3
	s_nop 0
	v_readlane_b32 s4, v151, s1
	v_pk_fma_f32 v[48:49], v[116:117], v[160:161], v[48:49] op_sel_hi:[1,0,1]
	s_lshr_b32 s4, s4, 7
	v_pk_fma_f32 v[50:51], v[118:119], v[160:161], v[50:51] op_sel_hi:[1,0,1]
	s_lshl_b32 s4, s4, 10
	v_pk_fma_f32 v[52:53], v[120:121], v[160:161], v[52:53] op_sel_hi:[1,0,1]
	s_add_u32 s24, s14, s4
	v_pk_fma_f32 v[54:55], v[122:123], v[160:161], v[54:55] op_sel_hi:[1,0,1]
	s_addc_u32 s25, s15, 0
	v_pk_fma_f32 v[228:229], v[124:125], v[160:161], v[228:229] op_sel_hi:[1,0,1]
	v_pk_fma_f32 v[230:231], v[126:127], v[160:161], v[230:231] op_sel_hi:[1,0,1]
	v_pk_fma_f32 v[232:233], v[128:129], v[160:161], v[232:233] op_sel_hi:[1,0,1]
	v_pk_fma_f32 v[234:235], v[130:131], v[160:161], v[234:235] op_sel_hi:[1,0,1]
	v_mfma_f32_32x32x64_f8f6f4 v[116:131], v[248:251], v[132:135], 0 cbsz:4 blgp:4
	global_load_dwordx4 v[240:243], v253, s[24:25]
	s_waitcnt lgkmcnt(0)
	v_cvt_f32_f16_e32 v254, v112
	ds_read_b32 v113, v252 offset:520
	v_pk_fma_f32 v[0:1], v[56:57], v[254:255], v[0:1] op_sel_hi:[1,0,1]
	v_pk_fma_f32 v[2:3], v[58:59], v[254:255], v[2:3] op_sel_hi:[1,0,1]
	v_pk_fma_f32 v[4:5], v[60:61], v[254:255], v[4:5] op_sel_hi:[1,0,1]
	v_pk_fma_f32 v[6:7], v[62:63], v[254:255], v[6:7] op_sel_hi:[1,0,1]
	v_pk_fma_f32 v[8:9], v[64:65], v[254:255], v[8:9] op_sel_hi:[1,0,1]
	v_pk_fma_f32 v[10:11], v[66:67], v[254:255], v[10:11] op_sel_hi:[1,0,1]
	v_pk_fma_f32 v[12:13], v[68:69], v[254:255], v[12:13] op_sel_hi:[1,0,1]
	v_pk_fma_f32 v[14:15], v[70:71], v[254:255], v[14:15] op_sel_hi:[1,0,1]
	s_waitcnt vmcnt(6)
	v_mfma_f32_32x32x64_f8f6f4 v[56:71], v[244:247], v[136:139], 0 cbsz:4 blgp:4
	s_add_i32 s1, s13, 4
	s_nop 0
	v_readlane_b32 s4, v111, s1
	v_pk_fma_f32 v[16:17], v[116:117], v[254:255], v[16:17] op_sel_hi:[1,0,1]
	s_lshr_b32 s4, s4, 7
	v_pk_fma_f32 v[18:19], v[118:119], v[254:255], v[18:19] op_sel_hi:[1,0,1]
	s_lshl_b32 s4, s4, 10
	v_pk_fma_f32 v[20:21], v[120:121], v[254:255], v[20:21] op_sel_hi:[1,0,1]
	s_add_u32 s24, s14, s4
	v_pk_fma_f32 v[22:23], v[122:123], v[254:255], v[22:23] op_sel_hi:[1,0,1]
	s_addc_u32 s25, s15, 0
	v_pk_fma_f32 v[24:25], v[124:125], v[254:255], v[24:25] op_sel_hi:[1,0,1]
	v_pk_fma_f32 v[26:27], v[126:127], v[254:255], v[26:27] op_sel_hi:[1,0,1]
	v_pk_fma_f32 v[28:29], v[128:129], v[254:255], v[28:29] op_sel_hi:[1,0,1]
	v_pk_fma_f32 v[30:31], v[130:131], v[254:255], v[30:31] op_sel_hi:[1,0,1]
	v_mfma_f32_32x32x64_f8f6f4 v[116:131], v[248:251], v[136:139], 0 cbsz:4 blgp:4
	global_load_dwordx4 v[132:135], v253, s[24:25]
	s_waitcnt lgkmcnt(0)
	v_cvt_f32_f16_e32 v160, v113
	ds_read_b32 v112, v252 offset:1032
	v_pk_fma_f32 v[164:165], v[56:57], v[160:161], v[164:165] op_sel_hi:[1,0,1]
	v_pk_fma_f32 v[166:167], v[58:59], v[160:161], v[166:167] op_sel_hi:[1,0,1]
	v_pk_fma_f32 v[168:169], v[60:61], v[160:161], v[168:169] op_sel_hi:[1,0,1]
	v_pk_fma_f32 v[170:171], v[62:63], v[160:161], v[170:171] op_sel_hi:[1,0,1]
	v_pk_fma_f32 v[172:173], v[64:65], v[160:161], v[172:173] op_sel_hi:[1,0,1]
	v_pk_fma_f32 v[174:175], v[66:67], v[160:161], v[174:175] op_sel_hi:[1,0,1]
	v_pk_fma_f32 v[176:177], v[68:69], v[160:161], v[176:177] op_sel_hi:[1,0,1]
	v_pk_fma_f32 v[178:179], v[70:71], v[160:161], v[178:179] op_sel_hi:[1,0,1]
	s_waitcnt vmcnt(6)
	v_mfma_f32_32x32x64_f8f6f4 v[56:71], v[244:247], v[140:143], 0 cbsz:4 blgp:4
	s_add_i32 s1, s13, 4
	s_nop 0
	v_readlane_b32 s4, v115, s1
	v_pk_fma_f32 v[180:181], v[116:117], v[160:161], v[180:181] op_sel_hi:[1,0,1]
	s_lshr_b32 s4, s4, 7
	v_pk_fma_f32 v[182:183], v[118:119], v[160:161], v[182:183] op_sel_hi:[1,0,1]
	s_lshl_b32 s4, s4, 10
	v_pk_fma_f32 v[184:185], v[120:121], v[160:161], v[184:185] op_sel_hi:[1,0,1]
	s_add_u32 s24, s14, s4
	v_pk_fma_f32 v[186:187], v[122:123], v[160:161], v[186:187] op_sel_hi:[1,0,1]
	s_addc_u32 s25, s15, 0
	v_pk_fma_f32 v[188:189], v[124:125], v[160:161], v[188:189] op_sel_hi:[1,0,1]
	v_pk_fma_f32 v[190:191], v[126:127], v[160:161], v[190:191] op_sel_hi:[1,0,1]
	v_pk_fma_f32 v[192:193], v[128:129], v[160:161], v[192:193] op_sel_hi:[1,0,1]
	v_pk_fma_f32 v[194:195], v[130:131], v[160:161], v[194:195] op_sel_hi:[1,0,1]
	v_mfma_f32_32x32x64_f8f6f4 v[116:131], v[248:251], v[140:143], 0 cbsz:4 blgp:4
	global_load_dwordx4 v[136:139], v253, s[24:25]
	s_waitcnt lgkmcnt(0)
	v_cvt_f32_f16_e32 v254, v112
	ds_read_b32 v113, v252 offset:1544
	v_pk_fma_f32 v[196:197], v[56:57], v[254:255], v[196:197] op_sel_hi:[1,0,1]
	v_pk_fma_f32 v[198:199], v[58:59], v[254:255], v[198:199] op_sel_hi:[1,0,1]
	v_pk_fma_f32 v[200:201], v[60:61], v[254:255], v[200:201] op_sel_hi:[1,0,1]
	v_pk_fma_f32 v[202:203], v[62:63], v[254:255], v[202:203] op_sel_hi:[1,0,1]
	v_pk_fma_f32 v[204:205], v[64:65], v[254:255], v[204:205] op_sel_hi:[1,0,1]
	v_pk_fma_f32 v[206:207], v[66:67], v[254:255], v[206:207] op_sel_hi:[1,0,1]
	v_pk_fma_f32 v[208:209], v[68:69], v[254:255], v[208:209] op_sel_hi:[1,0,1]
	v_pk_fma_f32 v[210:211], v[70:71], v[254:255], v[210:211] op_sel_hi:[1,0,1]
	s_waitcnt vmcnt(6)
	v_mfma_f32_32x32x64_f8f6f4 v[56:71], v[244:247], v[144:147], 0 cbsz:4 blgp:4
	s_add_i32 s1, s13, 4
	s_nop 0
	v_readlane_b32 s4, v150, s1
	v_pk_fma_f32 v[212:213], v[116:117], v[254:255], v[212:213] op_sel_hi:[1,0,1]
	s_lshr_b32 s4, s4, 7
	v_pk_fma_f32 v[214:215], v[118:119], v[254:255], v[214:215] op_sel_hi:[1,0,1]
	s_lshl_b32 s4, s4, 10
	v_pk_fma_f32 v[216:217], v[120:121], v[254:255], v[216:217] op_sel_hi:[1,0,1]
	s_add_u32 s24, s14, s4
	v_pk_fma_f32 v[218:219], v[122:123], v[254:255], v[218:219] op_sel_hi:[1,0,1]
	s_addc_u32 s25, s15, 0
	v_pk_fma_f32 v[220:221], v[124:125], v[254:255], v[220:221] op_sel_hi:[1,0,1]
	v_pk_fma_f32 v[222:223], v[126:127], v[254:255], v[222:223] op_sel_hi:[1,0,1]
	v_pk_fma_f32 v[224:225], v[128:129], v[254:255], v[224:225] op_sel_hi:[1,0,1]
	v_pk_fma_f32 v[226:227], v[130:131], v[254:255], v[226:227] op_sel_hi:[1,0,1]
	v_mfma_f32_32x32x64_f8f6f4 v[116:131], v[248:251], v[144:147], 0 cbsz:4 blgp:4
	global_load_dwordx4 v[140:143], v253, s[24:25]
	s_waitcnt lgkmcnt(0)
	v_cvt_f32_f16_e32 v160, v113
	ds_read_b32 v112, v252 offset:12
	v_pk_fma_f32 v[32:33], v[56:57], v[160:161], v[32:33] op_sel_hi:[1,0,1]
	v_pk_fma_f32 v[34:35], v[58:59], v[160:161], v[34:35] op_sel_hi:[1,0,1]
	v_pk_fma_f32 v[36:37], v[60:61], v[160:161], v[36:37] op_sel_hi:[1,0,1]
	v_pk_fma_f32 v[38:39], v[62:63], v[160:161], v[38:39] op_sel_hi:[1,0,1]
	v_pk_fma_f32 v[40:41], v[64:65], v[160:161], v[40:41] op_sel_hi:[1,0,1]
	v_pk_fma_f32 v[42:43], v[66:67], v[160:161], v[42:43] op_sel_hi:[1,0,1]
	v_pk_fma_f32 v[44:45], v[68:69], v[160:161], v[44:45] op_sel_hi:[1,0,1]
	v_pk_fma_f32 v[46:47], v[70:71], v[160:161], v[46:47] op_sel_hi:[1,0,1]
	s_waitcnt vmcnt(6)
	v_mfma_f32_32x32x64_f8f6f4 v[56:71], v[244:247], v[72:75], 0 cbsz:4 blgp:4
	s_add_i32 s1, s13, 4
	s_nop 0
	v_readlane_b32 s4, v151, s1
	v_pk_fma_f32 v[48:49], v[116:117], v[160:161], v[48:49] op_sel_hi:[1,0,1]
	s_lshr_b32 s4, s4, 7
	v_pk_fma_f32 v[50:51], v[118:119], v[160:161], v[50:51] op_sel_hi:[1,0,1]
	s_lshl_b32 s4, s4, 10
	v_pk_fma_f32 v[52:53], v[120:121], v[160:161], v[52:53] op_sel_hi:[1,0,1]
	s_add_u32 s24, s14, s4
	v_pk_fma_f32 v[54:55], v[122:123], v[160:161], v[54:55] op_sel_hi:[1,0,1]
	s_addc_u32 s25, s15, 0
	v_pk_fma_f32 v[228:229], v[124:125], v[160:161], v[228:229] op_sel_hi:[1,0,1]
	v_pk_fma_f32 v[230:231], v[126:127], v[160:161], v[230:231] op_sel_hi:[1,0,1]
	v_pk_fma_f32 v[232:233], v[128:129], v[160:161], v[232:233] op_sel_hi:[1,0,1]
	v_pk_fma_f32 v[234:235], v[130:131], v[160:161], v[234:235] op_sel_hi:[1,0,1]
	v_mfma_f32_32x32x64_f8f6f4 v[116:131], v[248:251], v[72:75], 0 cbsz:4 blgp:4
	global_load_dwordx4 v[144:147], v253, s[24:25]
	s_waitcnt lgkmcnt(0)
	v_cvt_f32_f16_e32 v254, v112
	ds_read_b32 v113, v252 offset:524
	v_pk_fma_f32 v[0:1], v[56:57], v[254:255], v[0:1] op_sel_hi:[1,0,1]
	v_pk_fma_f32 v[2:3], v[58:59], v[254:255], v[2:3] op_sel_hi:[1,0,1]
	v_pk_fma_f32 v[4:5], v[60:61], v[254:255], v[4:5] op_sel_hi:[1,0,1]
	v_pk_fma_f32 v[6:7], v[62:63], v[254:255], v[6:7] op_sel_hi:[1,0,1]
	v_pk_fma_f32 v[8:9], v[64:65], v[254:255], v[8:9] op_sel_hi:[1,0,1]
	v_pk_fma_f32 v[10:11], v[66:67], v[254:255], v[10:11] op_sel_hi:[1,0,1]
	v_pk_fma_f32 v[12:13], v[68:69], v[254:255], v[12:13] op_sel_hi:[1,0,1]
	v_pk_fma_f32 v[14:15], v[70:71], v[254:255], v[14:15] op_sel_hi:[1,0,1]
	s_waitcnt vmcnt(6)
	v_mfma_f32_32x32x64_f8f6f4 v[56:71], v[244:247], v[156:159], 0 cbsz:4 blgp:4
	s_add_i32 s1, s13, 5
	s_nop 0
	v_readlane_b32 s4, v111, s1
	v_pk_fma_f32 v[16:17], v[116:117], v[254:255], v[16:17] op_sel_hi:[1,0,1]
	s_lshr_b32 s4, s4, 7
	v_pk_fma_f32 v[18:19], v[118:119], v[254:255], v[18:19] op_sel_hi:[1,0,1]
	s_lshl_b32 s4, s4, 10
	v_pk_fma_f32 v[20:21], v[120:121], v[254:255], v[20:21] op_sel_hi:[1,0,1]
	s_add_u32 s24, s14, s4
	v_pk_fma_f32 v[22:23], v[122:123], v[254:255], v[22:23] op_sel_hi:[1,0,1]
	s_addc_u32 s25, s15, 0
	v_pk_fma_f32 v[24:25], v[124:125], v[254:255], v[24:25] op_sel_hi:[1,0,1]
	v_pk_fma_f32 v[26:27], v[126:127], v[254:255], v[26:27] op_sel_hi:[1,0,1]
	v_pk_fma_f32 v[28:29], v[128:129], v[254:255], v[28:29] op_sel_hi:[1,0,1]
	v_pk_fma_f32 v[30:31], v[130:131], v[254:255], v[30:31] op_sel_hi:[1,0,1]
	v_mfma_f32_32x32x64_f8f6f4 v[116:131], v[248:251], v[156:159], 0 cbsz:4 blgp:4
	global_load_dwordx4 v[72:75], v253, s[24:25]
	s_waitcnt lgkmcnt(0)
	v_cvt_f32_f16_e32 v160, v113
	ds_read_b32 v112, v252 offset:1036
	v_pk_fma_f32 v[164:165], v[56:57], v[160:161], v[164:165] op_sel_hi:[1,0,1]
	v_pk_fma_f32 v[166:167], v[58:59], v[160:161], v[166:167] op_sel_hi:[1,0,1]
	v_pk_fma_f32 v[168:169], v[60:61], v[160:161], v[168:169] op_sel_hi:[1,0,1]
	v_pk_fma_f32 v[170:171], v[62:63], v[160:161], v[170:171] op_sel_hi:[1,0,1]
	v_pk_fma_f32 v[172:173], v[64:65], v[160:161], v[172:173] op_sel_hi:[1,0,1]
	v_pk_fma_f32 v[174:175], v[66:67], v[160:161], v[174:175] op_sel_hi:[1,0,1]
	v_pk_fma_f32 v[176:177], v[68:69], v[160:161], v[176:177] op_sel_hi:[1,0,1]
	v_pk_fma_f32 v[178:179], v[70:71], v[160:161], v[178:179] op_sel_hi:[1,0,1]
	s_waitcnt vmcnt(6)
	v_mfma_f32_32x32x64_f8f6f4 v[56:71], v[244:247], v[236:239], 0 cbsz:4 blgp:4
	s_add_i32 s1, s13, 5
	s_nop 0
	v_readlane_b32 s4, v115, s1
	v_pk_fma_f32 v[180:181], v[116:117], v[160:161], v[180:181] op_sel_hi:[1,0,1]
	s_lshr_b32 s4, s4, 7
	v_pk_fma_f32 v[182:183], v[118:119], v[160:161], v[182:183] op_sel_hi:[1,0,1]
	s_lshl_b32 s4, s4, 10
	v_pk_fma_f32 v[184:185], v[120:121], v[160:161], v[184:185] op_sel_hi:[1,0,1]
	s_add_u32 s24, s14, s4
	v_pk_fma_f32 v[186:187], v[122:123], v[160:161], v[186:187] op_sel_hi:[1,0,1]
	s_addc_u32 s25, s15, 0
	v_pk_fma_f32 v[188:189], v[124:125], v[160:161], v[188:189] op_sel_hi:[1,0,1]
	v_pk_fma_f32 v[190:191], v[126:127], v[160:161], v[190:191] op_sel_hi:[1,0,1]
	v_pk_fma_f32 v[192:193], v[128:129], v[160:161], v[192:193] op_sel_hi:[1,0,1]
	v_pk_fma_f32 v[194:195], v[130:131], v[160:161], v[194:195] op_sel_hi:[1,0,1]
	v_mfma_f32_32x32x64_f8f6f4 v[116:131], v[248:251], v[236:239], 0 cbsz:4 blgp:4
	global_load_dwordx4 v[156:159], v253, s[24:25]
	s_waitcnt lgkmcnt(0)
	v_cvt_f32_f16_e32 v254, v112
	ds_read_b32 v113, v252 offset:1548
	v_pk_fma_f32 v[196:197], v[56:57], v[254:255], v[196:197] op_sel_hi:[1,0,1]
	v_pk_fma_f32 v[198:199], v[58:59], v[254:255], v[198:199] op_sel_hi:[1,0,1]
	v_pk_fma_f32 v[200:201], v[60:61], v[254:255], v[200:201] op_sel_hi:[1,0,1]
	v_pk_fma_f32 v[202:203], v[62:63], v[254:255], v[202:203] op_sel_hi:[1,0,1]
	v_pk_fma_f32 v[204:205], v[64:65], v[254:255], v[204:205] op_sel_hi:[1,0,1]
	v_pk_fma_f32 v[206:207], v[66:67], v[254:255], v[206:207] op_sel_hi:[1,0,1]
	v_pk_fma_f32 v[208:209], v[68:69], v[254:255], v[208:209] op_sel_hi:[1,0,1]
	v_pk_fma_f32 v[210:211], v[70:71], v[254:255], v[210:211] op_sel_hi:[1,0,1]
	s_waitcnt vmcnt(6)
	v_mfma_f32_32x32x64_f8f6f4 v[56:71], v[244:247], v[240:243], 0 cbsz:4 blgp:4
	s_add_i32 s1, s13, 5
	s_nop 0
	v_readlane_b32 s4, v150, s1
	v_pk_fma_f32 v[212:213], v[116:117], v[254:255], v[212:213] op_sel_hi:[1,0,1]
	s_lshr_b32 s4, s4, 7
	v_pk_fma_f32 v[214:215], v[118:119], v[254:255], v[214:215] op_sel_hi:[1,0,1]
	s_lshl_b32 s4, s4, 10
	v_pk_fma_f32 v[216:217], v[120:121], v[254:255], v[216:217] op_sel_hi:[1,0,1]
	s_add_u32 s24, s14, s4
	v_pk_fma_f32 v[218:219], v[122:123], v[254:255], v[218:219] op_sel_hi:[1,0,1]
	s_addc_u32 s25, s15, 0
	v_pk_fma_f32 v[220:221], v[124:125], v[254:255], v[220:221] op_sel_hi:[1,0,1]
	v_pk_fma_f32 v[222:223], v[126:127], v[254:255], v[222:223] op_sel_hi:[1,0,1]
	v_pk_fma_f32 v[224:225], v[128:129], v[254:255], v[224:225] op_sel_hi:[1,0,1]
	v_pk_fma_f32 v[226:227], v[130:131], v[254:255], v[226:227] op_sel_hi:[1,0,1]
	v_mfma_f32_32x32x64_f8f6f4 v[116:131], v[248:251], v[240:243], 0 cbsz:4 blgp:4
	global_load_dwordx4 v[236:239], v253, s[24:25]
	s_waitcnt lgkmcnt(0)
	v_cvt_f32_f16_e32 v160, v113
	ds_read_b32 v112, v252 offset:16
	v_pk_fma_f32 v[32:33], v[56:57], v[160:161], v[32:33] op_sel_hi:[1,0,1]
	v_pk_fma_f32 v[34:35], v[58:59], v[160:161], v[34:35] op_sel_hi:[1,0,1]
	v_pk_fma_f32 v[36:37], v[60:61], v[160:161], v[36:37] op_sel_hi:[1,0,1]
	v_pk_fma_f32 v[38:39], v[62:63], v[160:161], v[38:39] op_sel_hi:[1,0,1]
	v_pk_fma_f32 v[40:41], v[64:65], v[160:161], v[40:41] op_sel_hi:[1,0,1]
	v_pk_fma_f32 v[42:43], v[66:67], v[160:161], v[42:43] op_sel_hi:[1,0,1]
	v_pk_fma_f32 v[44:45], v[68:69], v[160:161], v[44:45] op_sel_hi:[1,0,1]
	v_pk_fma_f32 v[46:47], v[70:71], v[160:161], v[46:47] op_sel_hi:[1,0,1]
	s_waitcnt vmcnt(6)
	v_mfma_f32_32x32x64_f8f6f4 v[56:71], v[244:247], v[132:135], 0 cbsz:4 blgp:4
	s_add_i32 s1, s13, 5
	s_nop 0
	v_readlane_b32 s4, v151, s1
	v_pk_fma_f32 v[48:49], v[116:117], v[160:161], v[48:49] op_sel_hi:[1,0,1]
	s_lshr_b32 s4, s4, 7
	v_pk_fma_f32 v[50:51], v[118:119], v[160:161], v[50:51] op_sel_hi:[1,0,1]
	s_lshl_b32 s4, s4, 10
	v_pk_fma_f32 v[52:53], v[120:121], v[160:161], v[52:53] op_sel_hi:[1,0,1]
	s_add_u32 s24, s14, s4
	v_pk_fma_f32 v[54:55], v[122:123], v[160:161], v[54:55] op_sel_hi:[1,0,1]
	s_addc_u32 s25, s15, 0
	v_pk_fma_f32 v[228:229], v[124:125], v[160:161], v[228:229] op_sel_hi:[1,0,1]
	v_pk_fma_f32 v[230:231], v[126:127], v[160:161], v[230:231] op_sel_hi:[1,0,1]
	v_pk_fma_f32 v[232:233], v[128:129], v[160:161], v[232:233] op_sel_hi:[1,0,1]
	v_pk_fma_f32 v[234:235], v[130:131], v[160:161], v[234:235] op_sel_hi:[1,0,1]
	v_mfma_f32_32x32x64_f8f6f4 v[116:131], v[248:251], v[132:135], 0 cbsz:4 blgp:4
	global_load_dwordx4 v[240:243], v253, s[24:25]
	s_waitcnt lgkmcnt(0)
	v_cvt_f32_f16_e32 v254, v112
	ds_read_b32 v113, v252 offset:528
	v_pk_fma_f32 v[0:1], v[56:57], v[254:255], v[0:1] op_sel_hi:[1,0,1]
	v_pk_fma_f32 v[2:3], v[58:59], v[254:255], v[2:3] op_sel_hi:[1,0,1]
	v_pk_fma_f32 v[4:5], v[60:61], v[254:255], v[4:5] op_sel_hi:[1,0,1]
	v_pk_fma_f32 v[6:7], v[62:63], v[254:255], v[6:7] op_sel_hi:[1,0,1]
	v_pk_fma_f32 v[8:9], v[64:65], v[254:255], v[8:9] op_sel_hi:[1,0,1]
	v_pk_fma_f32 v[10:11], v[66:67], v[254:255], v[10:11] op_sel_hi:[1,0,1]
	v_pk_fma_f32 v[12:13], v[68:69], v[254:255], v[12:13] op_sel_hi:[1,0,1]
	v_pk_fma_f32 v[14:15], v[70:71], v[254:255], v[14:15] op_sel_hi:[1,0,1]
	s_waitcnt vmcnt(6)
	v_mfma_f32_32x32x64_f8f6f4 v[56:71], v[244:247], v[136:139], 0 cbsz:4 blgp:4
	s_add_i32 s1, s13, 6
	s_nop 0
	v_readlane_b32 s4, v111, s1
	v_pk_fma_f32 v[16:17], v[116:117], v[254:255], v[16:17] op_sel_hi:[1,0,1]
	s_lshr_b32 s4, s4, 7
	v_pk_fma_f32 v[18:19], v[118:119], v[254:255], v[18:19] op_sel_hi:[1,0,1]
	s_lshl_b32 s4, s4, 10
	v_pk_fma_f32 v[20:21], v[120:121], v[254:255], v[20:21] op_sel_hi:[1,0,1]
	s_add_u32 s24, s14, s4
	v_pk_fma_f32 v[22:23], v[122:123], v[254:255], v[22:23] op_sel_hi:[1,0,1]
	s_addc_u32 s25, s15, 0
	v_pk_fma_f32 v[24:25], v[124:125], v[254:255], v[24:25] op_sel_hi:[1,0,1]
	v_pk_fma_f32 v[26:27], v[126:127], v[254:255], v[26:27] op_sel_hi:[1,0,1]
	v_pk_fma_f32 v[28:29], v[128:129], v[254:255], v[28:29] op_sel_hi:[1,0,1]
	v_pk_fma_f32 v[30:31], v[130:131], v[254:255], v[30:31] op_sel_hi:[1,0,1]
	v_mfma_f32_32x32x64_f8f6f4 v[116:131], v[248:251], v[136:139], 0 cbsz:4 blgp:4
	global_load_dwordx4 v[132:135], v253, s[24:25]
	s_waitcnt lgkmcnt(0)
	v_cvt_f32_f16_e32 v160, v113
	ds_read_b32 v112, v252 offset:1040
	v_pk_fma_f32 v[164:165], v[56:57], v[160:161], v[164:165] op_sel_hi:[1,0,1]
	v_pk_fma_f32 v[166:167], v[58:59], v[160:161], v[166:167] op_sel_hi:[1,0,1]
	v_pk_fma_f32 v[168:169], v[60:61], v[160:161], v[168:169] op_sel_hi:[1,0,1]
	v_pk_fma_f32 v[170:171], v[62:63], v[160:161], v[170:171] op_sel_hi:[1,0,1]
	v_pk_fma_f32 v[172:173], v[64:65], v[160:161], v[172:173] op_sel_hi:[1,0,1]
	v_pk_fma_f32 v[174:175], v[66:67], v[160:161], v[174:175] op_sel_hi:[1,0,1]
	v_pk_fma_f32 v[176:177], v[68:69], v[160:161], v[176:177] op_sel_hi:[1,0,1]
	v_pk_fma_f32 v[178:179], v[70:71], v[160:161], v[178:179] op_sel_hi:[1,0,1]
	s_waitcnt vmcnt(6)
	v_mfma_f32_32x32x64_f8f6f4 v[56:71], v[244:247], v[140:143], 0 cbsz:4 blgp:4
	s_add_i32 s1, s13, 6
	s_nop 0
	v_readlane_b32 s4, v115, s1
	v_pk_fma_f32 v[180:181], v[116:117], v[160:161], v[180:181] op_sel_hi:[1,0,1]
	s_lshr_b32 s4, s4, 7
	v_pk_fma_f32 v[182:183], v[118:119], v[160:161], v[182:183] op_sel_hi:[1,0,1]
	s_lshl_b32 s4, s4, 10
	v_pk_fma_f32 v[184:185], v[120:121], v[160:161], v[184:185] op_sel_hi:[1,0,1]
	s_add_u32 s24, s14, s4
	v_pk_fma_f32 v[186:187], v[122:123], v[160:161], v[186:187] op_sel_hi:[1,0,1]
	s_addc_u32 s25, s15, 0
	v_pk_fma_f32 v[188:189], v[124:125], v[160:161], v[188:189] op_sel_hi:[1,0,1]
	v_pk_fma_f32 v[190:191], v[126:127], v[160:161], v[190:191] op_sel_hi:[1,0,1]
	v_pk_fma_f32 v[192:193], v[128:129], v[160:161], v[192:193] op_sel_hi:[1,0,1]
	v_pk_fma_f32 v[194:195], v[130:131], v[160:161], v[194:195] op_sel_hi:[1,0,1]
	v_mfma_f32_32x32x64_f8f6f4 v[116:131], v[248:251], v[140:143], 0 cbsz:4 blgp:4
	global_load_dwordx4 v[136:139], v253, s[24:25]
	s_waitcnt lgkmcnt(0)
	v_cvt_f32_f16_e32 v254, v112
	ds_read_b32 v113, v252 offset:1552
	v_pk_fma_f32 v[196:197], v[56:57], v[254:255], v[196:197] op_sel_hi:[1,0,1]
	v_pk_fma_f32 v[198:199], v[58:59], v[254:255], v[198:199] op_sel_hi:[1,0,1]
	v_pk_fma_f32 v[200:201], v[60:61], v[254:255], v[200:201] op_sel_hi:[1,0,1]
	v_pk_fma_f32 v[202:203], v[62:63], v[254:255], v[202:203] op_sel_hi:[1,0,1]
	v_pk_fma_f32 v[204:205], v[64:65], v[254:255], v[204:205] op_sel_hi:[1,0,1]
	v_pk_fma_f32 v[206:207], v[66:67], v[254:255], v[206:207] op_sel_hi:[1,0,1]
	v_pk_fma_f32 v[208:209], v[68:69], v[254:255], v[208:209] op_sel_hi:[1,0,1]
	v_pk_fma_f32 v[210:211], v[70:71], v[254:255], v[210:211] op_sel_hi:[1,0,1]
	s_waitcnt vmcnt(6)
	v_mfma_f32_32x32x64_f8f6f4 v[56:71], v[244:247], v[144:147], 0 cbsz:4 blgp:4
	s_add_i32 s1, s13, 6
	s_nop 0
	v_readlane_b32 s4, v150, s1
	v_pk_fma_f32 v[212:213], v[116:117], v[254:255], v[212:213] op_sel_hi:[1,0,1]
	s_lshr_b32 s4, s4, 7
	v_pk_fma_f32 v[214:215], v[118:119], v[254:255], v[214:215] op_sel_hi:[1,0,1]
	s_lshl_b32 s4, s4, 10
	v_pk_fma_f32 v[216:217], v[120:121], v[254:255], v[216:217] op_sel_hi:[1,0,1]
	s_add_u32 s24, s14, s4
	v_pk_fma_f32 v[218:219], v[122:123], v[254:255], v[218:219] op_sel_hi:[1,0,1]
	s_addc_u32 s25, s15, 0
	v_pk_fma_f32 v[220:221], v[124:125], v[254:255], v[220:221] op_sel_hi:[1,0,1]
	v_pk_fma_f32 v[222:223], v[126:127], v[254:255], v[222:223] op_sel_hi:[1,0,1]
	v_pk_fma_f32 v[224:225], v[128:129], v[254:255], v[224:225] op_sel_hi:[1,0,1]
	v_pk_fma_f32 v[226:227], v[130:131], v[254:255], v[226:227] op_sel_hi:[1,0,1]
	v_mfma_f32_32x32x64_f8f6f4 v[116:131], v[248:251], v[144:147], 0 cbsz:4 blgp:4
	global_load_dwordx4 v[140:143], v253, s[24:25]
	s_waitcnt lgkmcnt(0)
	v_cvt_f32_f16_e32 v160, v113
	ds_read_b32 v112, v252 offset:20
	v_pk_fma_f32 v[32:33], v[56:57], v[160:161], v[32:33] op_sel_hi:[1,0,1]
	v_pk_fma_f32 v[34:35], v[58:59], v[160:161], v[34:35] op_sel_hi:[1,0,1]
	v_pk_fma_f32 v[36:37], v[60:61], v[160:161], v[36:37] op_sel_hi:[1,0,1]
	v_pk_fma_f32 v[38:39], v[62:63], v[160:161], v[38:39] op_sel_hi:[1,0,1]
	v_pk_fma_f32 v[40:41], v[64:65], v[160:161], v[40:41] op_sel_hi:[1,0,1]
	v_pk_fma_f32 v[42:43], v[66:67], v[160:161], v[42:43] op_sel_hi:[1,0,1]
	v_pk_fma_f32 v[44:45], v[68:69], v[160:161], v[44:45] op_sel_hi:[1,0,1]
	v_pk_fma_f32 v[46:47], v[70:71], v[160:161], v[46:47] op_sel_hi:[1,0,1]
	s_waitcnt vmcnt(6)
	v_mfma_f32_32x32x64_f8f6f4 v[56:71], v[244:247], v[72:75], 0 cbsz:4 blgp:4
	s_add_i32 s1, s13, 6
	s_nop 0
	v_readlane_b32 s4, v151, s1
	v_pk_fma_f32 v[48:49], v[116:117], v[160:161], v[48:49] op_sel_hi:[1,0,1]
	s_lshr_b32 s4, s4, 7
	v_pk_fma_f32 v[50:51], v[118:119], v[160:161], v[50:51] op_sel_hi:[1,0,1]
	s_lshl_b32 s4, s4, 10
	v_pk_fma_f32 v[52:53], v[120:121], v[160:161], v[52:53] op_sel_hi:[1,0,1]
	s_add_u32 s24, s14, s4
	v_pk_fma_f32 v[54:55], v[122:123], v[160:161], v[54:55] op_sel_hi:[1,0,1]
	s_addc_u32 s25, s15, 0
	v_pk_fma_f32 v[228:229], v[124:125], v[160:161], v[228:229] op_sel_hi:[1,0,1]
	v_pk_fma_f32 v[230:231], v[126:127], v[160:161], v[230:231] op_sel_hi:[1,0,1]
	v_pk_fma_f32 v[232:233], v[128:129], v[160:161], v[232:233] op_sel_hi:[1,0,1]
	v_pk_fma_f32 v[234:235], v[130:131], v[160:161], v[234:235] op_sel_hi:[1,0,1]
	v_mfma_f32_32x32x64_f8f6f4 v[116:131], v[248:251], v[72:75], 0 cbsz:4 blgp:4
	global_load_dwordx4 v[144:147], v253, s[24:25]
	s_waitcnt lgkmcnt(0)
	v_cvt_f32_f16_e32 v254, v112
	ds_read_b32 v113, v252 offset:532
	v_pk_fma_f32 v[0:1], v[56:57], v[254:255], v[0:1] op_sel_hi:[1,0,1]
	v_pk_fma_f32 v[2:3], v[58:59], v[254:255], v[2:3] op_sel_hi:[1,0,1]
	v_pk_fma_f32 v[4:5], v[60:61], v[254:255], v[4:5] op_sel_hi:[1,0,1]
	v_pk_fma_f32 v[6:7], v[62:63], v[254:255], v[6:7] op_sel_hi:[1,0,1]
	v_pk_fma_f32 v[8:9], v[64:65], v[254:255], v[8:9] op_sel_hi:[1,0,1]
	v_pk_fma_f32 v[10:11], v[66:67], v[254:255], v[10:11] op_sel_hi:[1,0,1]
	v_pk_fma_f32 v[12:13], v[68:69], v[254:255], v[12:13] op_sel_hi:[1,0,1]
	v_pk_fma_f32 v[14:15], v[70:71], v[254:255], v[14:15] op_sel_hi:[1,0,1]
	s_waitcnt vmcnt(6)
	v_mfma_f32_32x32x64_f8f6f4 v[56:71], v[244:247], v[156:159], 0 cbsz:4 blgp:4
	s_add_i32 s1, s13, 7
	s_nop 0
	v_readlane_b32 s4, v111, s1
	v_pk_fma_f32 v[16:17], v[116:117], v[254:255], v[16:17] op_sel_hi:[1,0,1]
	s_lshr_b32 s4, s4, 7
	v_pk_fma_f32 v[18:19], v[118:119], v[254:255], v[18:19] op_sel_hi:[1,0,1]
	s_lshl_b32 s4, s4, 10
	v_pk_fma_f32 v[20:21], v[120:121], v[254:255], v[20:21] op_sel_hi:[1,0,1]
	s_add_u32 s24, s14, s4
	v_pk_fma_f32 v[22:23], v[122:123], v[254:255], v[22:23] op_sel_hi:[1,0,1]
	s_addc_u32 s25, s15, 0
	v_pk_fma_f32 v[24:25], v[124:125], v[254:255], v[24:25] op_sel_hi:[1,0,1]
	v_pk_fma_f32 v[26:27], v[126:127], v[254:255], v[26:27] op_sel_hi:[1,0,1]
	v_pk_fma_f32 v[28:29], v[128:129], v[254:255], v[28:29] op_sel_hi:[1,0,1]
	v_pk_fma_f32 v[30:31], v[130:131], v[254:255], v[30:31] op_sel_hi:[1,0,1]
	v_mfma_f32_32x32x64_f8f6f4 v[116:131], v[248:251], v[156:159], 0 cbsz:4 blgp:4
	global_load_dwordx4 v[72:75], v253, s[24:25]
	s_waitcnt lgkmcnt(0)
	v_cvt_f32_f16_e32 v160, v113
	ds_read_b32 v112, v252 offset:1044
	v_pk_fma_f32 v[164:165], v[56:57], v[160:161], v[164:165] op_sel_hi:[1,0,1]
	v_pk_fma_f32 v[166:167], v[58:59], v[160:161], v[166:167] op_sel_hi:[1,0,1]
	v_pk_fma_f32 v[168:169], v[60:61], v[160:161], v[168:169] op_sel_hi:[1,0,1]
	v_pk_fma_f32 v[170:171], v[62:63], v[160:161], v[170:171] op_sel_hi:[1,0,1]
	v_pk_fma_f32 v[172:173], v[64:65], v[160:161], v[172:173] op_sel_hi:[1,0,1]
	v_pk_fma_f32 v[174:175], v[66:67], v[160:161], v[174:175] op_sel_hi:[1,0,1]
	v_pk_fma_f32 v[176:177], v[68:69], v[160:161], v[176:177] op_sel_hi:[1,0,1]
	v_pk_fma_f32 v[178:179], v[70:71], v[160:161], v[178:179] op_sel_hi:[1,0,1]
	s_waitcnt vmcnt(6)
	v_mfma_f32_32x32x64_f8f6f4 v[56:71], v[244:247], v[236:239], 0 cbsz:4 blgp:4
	s_add_i32 s1, s13, 7
	s_nop 0
	v_readlane_b32 s4, v115, s1
	v_pk_fma_f32 v[180:181], v[116:117], v[160:161], v[180:181] op_sel_hi:[1,0,1]
	s_lshr_b32 s4, s4, 7
	v_pk_fma_f32 v[182:183], v[118:119], v[160:161], v[182:183] op_sel_hi:[1,0,1]
	s_lshl_b32 s4, s4, 10
	v_pk_fma_f32 v[184:185], v[120:121], v[160:161], v[184:185] op_sel_hi:[1,0,1]
	s_add_u32 s24, s14, s4
	v_pk_fma_f32 v[186:187], v[122:123], v[160:161], v[186:187] op_sel_hi:[1,0,1]
	s_addc_u32 s25, s15, 0
	v_pk_fma_f32 v[188:189], v[124:125], v[160:161], v[188:189] op_sel_hi:[1,0,1]
	v_pk_fma_f32 v[190:191], v[126:127], v[160:161], v[190:191] op_sel_hi:[1,0,1]
	v_pk_fma_f32 v[192:193], v[128:129], v[160:161], v[192:193] op_sel_hi:[1,0,1]
	v_pk_fma_f32 v[194:195], v[130:131], v[160:161], v[194:195] op_sel_hi:[1,0,1]
	v_mfma_f32_32x32x64_f8f6f4 v[116:131], v[248:251], v[236:239], 0 cbsz:4 blgp:4
	global_load_dwordx4 v[156:159], v253, s[24:25]
	s_waitcnt lgkmcnt(0)
	v_cvt_f32_f16_e32 v254, v112
	ds_read_b32 v113, v252 offset:1556
	v_pk_fma_f32 v[196:197], v[56:57], v[254:255], v[196:197] op_sel_hi:[1,0,1]
	v_pk_fma_f32 v[198:199], v[58:59], v[254:255], v[198:199] op_sel_hi:[1,0,1]
	v_pk_fma_f32 v[200:201], v[60:61], v[254:255], v[200:201] op_sel_hi:[1,0,1]
	v_pk_fma_f32 v[202:203], v[62:63], v[254:255], v[202:203] op_sel_hi:[1,0,1]
	v_pk_fma_f32 v[204:205], v[64:65], v[254:255], v[204:205] op_sel_hi:[1,0,1]
	v_pk_fma_f32 v[206:207], v[66:67], v[254:255], v[206:207] op_sel_hi:[1,0,1]
	v_pk_fma_f32 v[208:209], v[68:69], v[254:255], v[208:209] op_sel_hi:[1,0,1]
	v_pk_fma_f32 v[210:211], v[70:71], v[254:255], v[210:211] op_sel_hi:[1,0,1]
	s_waitcnt vmcnt(6)
	v_mfma_f32_32x32x64_f8f6f4 v[56:71], v[244:247], v[240:243], 0 cbsz:4 blgp:4
	s_add_i32 s1, s13, 7
	s_nop 0
	v_readlane_b32 s4, v150, s1
	v_pk_fma_f32 v[212:213], v[116:117], v[254:255], v[212:213] op_sel_hi:[1,0,1]
	s_lshr_b32 s4, s4, 7
	v_pk_fma_f32 v[214:215], v[118:119], v[254:255], v[214:215] op_sel_hi:[1,0,1]
	s_lshl_b32 s4, s4, 10
	v_pk_fma_f32 v[216:217], v[120:121], v[254:255], v[216:217] op_sel_hi:[1,0,1]
	s_add_u32 s24, s14, s4
	v_pk_fma_f32 v[218:219], v[122:123], v[254:255], v[218:219] op_sel_hi:[1,0,1]
	s_addc_u32 s25, s15, 0
	v_pk_fma_f32 v[220:221], v[124:125], v[254:255], v[220:221] op_sel_hi:[1,0,1]
	v_pk_fma_f32 v[222:223], v[126:127], v[254:255], v[222:223] op_sel_hi:[1,0,1]
	v_pk_fma_f32 v[224:225], v[128:129], v[254:255], v[224:225] op_sel_hi:[1,0,1]
	v_pk_fma_f32 v[226:227], v[130:131], v[254:255], v[226:227] op_sel_hi:[1,0,1]
	v_mfma_f32_32x32x64_f8f6f4 v[116:131], v[248:251], v[240:243], 0 cbsz:4 blgp:4
	global_load_dwordx4 v[236:239], v253, s[24:25]
	s_waitcnt lgkmcnt(0)
	v_cvt_f32_f16_e32 v160, v113
	ds_read_b32 v112, v252 offset:24
	v_pk_fma_f32 v[32:33], v[56:57], v[160:161], v[32:33] op_sel_hi:[1,0,1]
	v_pk_fma_f32 v[34:35], v[58:59], v[160:161], v[34:35] op_sel_hi:[1,0,1]
	v_pk_fma_f32 v[36:37], v[60:61], v[160:161], v[36:37] op_sel_hi:[1,0,1]
	v_pk_fma_f32 v[38:39], v[62:63], v[160:161], v[38:39] op_sel_hi:[1,0,1]
	v_pk_fma_f32 v[40:41], v[64:65], v[160:161], v[40:41] op_sel_hi:[1,0,1]
	v_pk_fma_f32 v[42:43], v[66:67], v[160:161], v[42:43] op_sel_hi:[1,0,1]
	v_pk_fma_f32 v[44:45], v[68:69], v[160:161], v[44:45] op_sel_hi:[1,0,1]
	v_pk_fma_f32 v[46:47], v[70:71], v[160:161], v[46:47] op_sel_hi:[1,0,1]
	s_waitcnt vmcnt(6)
	v_mfma_f32_32x32x64_f8f6f4 v[56:71], v[244:247], v[132:135], 0 cbsz:4 blgp:4
	s_add_i32 s1, s13, 7
	s_nop 0
	v_readlane_b32 s4, v151, s1
	v_pk_fma_f32 v[48:49], v[116:117], v[160:161], v[48:49] op_sel_hi:[1,0,1]
	s_lshr_b32 s4, s4, 7
	v_pk_fma_f32 v[50:51], v[118:119], v[160:161], v[50:51] op_sel_hi:[1,0,1]
	s_lshl_b32 s4, s4, 10
	v_pk_fma_f32 v[52:53], v[120:121], v[160:161], v[52:53] op_sel_hi:[1,0,1]
	s_add_u32 s24, s14, s4
	v_pk_fma_f32 v[54:55], v[122:123], v[160:161], v[54:55] op_sel_hi:[1,0,1]
	s_addc_u32 s25, s15, 0
	v_pk_fma_f32 v[228:229], v[124:125], v[160:161], v[228:229] op_sel_hi:[1,0,1]
	v_pk_fma_f32 v[230:231], v[126:127], v[160:161], v[230:231] op_sel_hi:[1,0,1]
	v_pk_fma_f32 v[232:233], v[128:129], v[160:161], v[232:233] op_sel_hi:[1,0,1]
	v_pk_fma_f32 v[234:235], v[130:131], v[160:161], v[234:235] op_sel_hi:[1,0,1]
	v_mfma_f32_32x32x64_f8f6f4 v[116:131], v[248:251], v[132:135], 0 cbsz:4 blgp:4
	global_load_dwordx4 v[240:243], v253, s[24:25]
	s_waitcnt lgkmcnt(0)
	v_cvt_f32_f16_e32 v254, v112
	ds_read_b32 v113, v252 offset:536
	v_pk_fma_f32 v[0:1], v[56:57], v[254:255], v[0:1] op_sel_hi:[1,0,1]
	v_pk_fma_f32 v[2:3], v[58:59], v[254:255], v[2:3] op_sel_hi:[1,0,1]
	v_pk_fma_f32 v[4:5], v[60:61], v[254:255], v[4:5] op_sel_hi:[1,0,1]
	v_pk_fma_f32 v[6:7], v[62:63], v[254:255], v[6:7] op_sel_hi:[1,0,1]
	v_pk_fma_f32 v[8:9], v[64:65], v[254:255], v[8:9] op_sel_hi:[1,0,1]
	v_pk_fma_f32 v[10:11], v[66:67], v[254:255], v[10:11] op_sel_hi:[1,0,1]
	v_pk_fma_f32 v[12:13], v[68:69], v[254:255], v[12:13] op_sel_hi:[1,0,1]
	v_pk_fma_f32 v[14:15], v[70:71], v[254:255], v[14:15] op_sel_hi:[1,0,1]
	s_waitcnt vmcnt(6)
	v_mfma_f32_32x32x64_f8f6f4 v[56:71], v[244:247], v[136:139], 0 cbsz:4 blgp:4
	s_add_i32 s1, s13, 8
	s_nop 0
	v_readlane_b32 s4, v111, s1
	v_pk_fma_f32 v[16:17], v[116:117], v[254:255], v[16:17] op_sel_hi:[1,0,1]
	s_lshr_b32 s4, s4, 7
	v_pk_fma_f32 v[18:19], v[118:119], v[254:255], v[18:19] op_sel_hi:[1,0,1]
	s_lshl_b32 s4, s4, 10
	v_pk_fma_f32 v[20:21], v[120:121], v[254:255], v[20:21] op_sel_hi:[1,0,1]
	s_add_u32 s24, s14, s4
	v_pk_fma_f32 v[22:23], v[122:123], v[254:255], v[22:23] op_sel_hi:[1,0,1]
	s_addc_u32 s25, s15, 0
	v_pk_fma_f32 v[24:25], v[124:125], v[254:255], v[24:25] op_sel_hi:[1,0,1]
	v_pk_fma_f32 v[26:27], v[126:127], v[254:255], v[26:27] op_sel_hi:[1,0,1]
	v_pk_fma_f32 v[28:29], v[128:129], v[254:255], v[28:29] op_sel_hi:[1,0,1]
	v_pk_fma_f32 v[30:31], v[130:131], v[254:255], v[30:31] op_sel_hi:[1,0,1]
	v_mfma_f32_32x32x64_f8f6f4 v[116:131], v[248:251], v[136:139], 0 cbsz:4 blgp:4
	global_load_dwordx4 v[132:135], v253, s[24:25]
	s_waitcnt lgkmcnt(0)
	v_cvt_f32_f16_e32 v160, v113
	ds_read_b32 v112, v252 offset:1048
	v_pk_fma_f32 v[164:165], v[56:57], v[160:161], v[164:165] op_sel_hi:[1,0,1]
	v_pk_fma_f32 v[166:167], v[58:59], v[160:161], v[166:167] op_sel_hi:[1,0,1]
	v_pk_fma_f32 v[168:169], v[60:61], v[160:161], v[168:169] op_sel_hi:[1,0,1]
	v_pk_fma_f32 v[170:171], v[62:63], v[160:161], v[170:171] op_sel_hi:[1,0,1]
	v_pk_fma_f32 v[172:173], v[64:65], v[160:161], v[172:173] op_sel_hi:[1,0,1]
	v_pk_fma_f32 v[174:175], v[66:67], v[160:161], v[174:175] op_sel_hi:[1,0,1]
	v_pk_fma_f32 v[176:177], v[68:69], v[160:161], v[176:177] op_sel_hi:[1,0,1]
	v_pk_fma_f32 v[178:179], v[70:71], v[160:161], v[178:179] op_sel_hi:[1,0,1]
	s_waitcnt vmcnt(6)
	v_mfma_f32_32x32x64_f8f6f4 v[56:71], v[244:247], v[140:143], 0 cbsz:4 blgp:4
	s_add_i32 s1, s13, 8
	s_nop 0
	v_readlane_b32 s4, v115, s1
	v_pk_fma_f32 v[180:181], v[116:117], v[160:161], v[180:181] op_sel_hi:[1,0,1]
	s_lshr_b32 s4, s4, 7
	v_pk_fma_f32 v[182:183], v[118:119], v[160:161], v[182:183] op_sel_hi:[1,0,1]
	s_lshl_b32 s4, s4, 10
	v_pk_fma_f32 v[184:185], v[120:121], v[160:161], v[184:185] op_sel_hi:[1,0,1]
	s_add_u32 s24, s14, s4
	v_pk_fma_f32 v[186:187], v[122:123], v[160:161], v[186:187] op_sel_hi:[1,0,1]
	s_addc_u32 s25, s15, 0
	v_pk_fma_f32 v[188:189], v[124:125], v[160:161], v[188:189] op_sel_hi:[1,0,1]
	v_pk_fma_f32 v[190:191], v[126:127], v[160:161], v[190:191] op_sel_hi:[1,0,1]
	v_pk_fma_f32 v[192:193], v[128:129], v[160:161], v[192:193] op_sel_hi:[1,0,1]
	v_pk_fma_f32 v[194:195], v[130:131], v[160:161], v[194:195] op_sel_hi:[1,0,1]
	v_mfma_f32_32x32x64_f8f6f4 v[116:131], v[248:251], v[140:143], 0 cbsz:4 blgp:4
	global_load_dwordx4 v[136:139], v253, s[24:25]
	s_waitcnt lgkmcnt(0)
	v_cvt_f32_f16_e32 v254, v112
	ds_read_b32 v113, v252 offset:1560
	v_pk_fma_f32 v[196:197], v[56:57], v[254:255], v[196:197] op_sel_hi:[1,0,1]
	v_pk_fma_f32 v[198:199], v[58:59], v[254:255], v[198:199] op_sel_hi:[1,0,1]
	v_pk_fma_f32 v[200:201], v[60:61], v[254:255], v[200:201] op_sel_hi:[1,0,1]
	v_pk_fma_f32 v[202:203], v[62:63], v[254:255], v[202:203] op_sel_hi:[1,0,1]
	v_pk_fma_f32 v[204:205], v[64:65], v[254:255], v[204:205] op_sel_hi:[1,0,1]
	v_pk_fma_f32 v[206:207], v[66:67], v[254:255], v[206:207] op_sel_hi:[1,0,1]
	v_pk_fma_f32 v[208:209], v[68:69], v[254:255], v[208:209] op_sel_hi:[1,0,1]
	v_pk_fma_f32 v[210:211], v[70:71], v[254:255], v[210:211] op_sel_hi:[1,0,1]
	s_waitcnt vmcnt(6)
	v_mfma_f32_32x32x64_f8f6f4 v[56:71], v[244:247], v[144:147], 0 cbsz:4 blgp:4
	s_add_i32 s1, s13, 8
	s_nop 0
	v_readlane_b32 s4, v150, s1
	v_pk_fma_f32 v[212:213], v[116:117], v[254:255], v[212:213] op_sel_hi:[1,0,1]
	s_lshr_b32 s4, s4, 7
	v_pk_fma_f32 v[214:215], v[118:119], v[254:255], v[214:215] op_sel_hi:[1,0,1]
	s_lshl_b32 s4, s4, 10
	v_pk_fma_f32 v[216:217], v[120:121], v[254:255], v[216:217] op_sel_hi:[1,0,1]
	s_add_u32 s24, s14, s4
	v_pk_fma_f32 v[218:219], v[122:123], v[254:255], v[218:219] op_sel_hi:[1,0,1]
	s_addc_u32 s25, s15, 0
	v_pk_fma_f32 v[220:221], v[124:125], v[254:255], v[220:221] op_sel_hi:[1,0,1]
	v_pk_fma_f32 v[222:223], v[126:127], v[254:255], v[222:223] op_sel_hi:[1,0,1]
	v_pk_fma_f32 v[224:225], v[128:129], v[254:255], v[224:225] op_sel_hi:[1,0,1]
	v_pk_fma_f32 v[226:227], v[130:131], v[254:255], v[226:227] op_sel_hi:[1,0,1]
	v_mfma_f32_32x32x64_f8f6f4 v[116:131], v[248:251], v[144:147], 0 cbsz:4 blgp:4
	global_load_dwordx4 v[140:143], v253, s[24:25]
	s_waitcnt lgkmcnt(0)
	v_cvt_f32_f16_e32 v160, v113
	ds_read_b32 v112, v252 offset:28
	v_pk_fma_f32 v[32:33], v[56:57], v[160:161], v[32:33] op_sel_hi:[1,0,1]
	v_pk_fma_f32 v[34:35], v[58:59], v[160:161], v[34:35] op_sel_hi:[1,0,1]
	v_pk_fma_f32 v[36:37], v[60:61], v[160:161], v[36:37] op_sel_hi:[1,0,1]
	v_pk_fma_f32 v[38:39], v[62:63], v[160:161], v[38:39] op_sel_hi:[1,0,1]
	v_pk_fma_f32 v[40:41], v[64:65], v[160:161], v[40:41] op_sel_hi:[1,0,1]
	v_pk_fma_f32 v[42:43], v[66:67], v[160:161], v[42:43] op_sel_hi:[1,0,1]
	v_pk_fma_f32 v[44:45], v[68:69], v[160:161], v[44:45] op_sel_hi:[1,0,1]
	v_pk_fma_f32 v[46:47], v[70:71], v[160:161], v[46:47] op_sel_hi:[1,0,1]
	s_waitcnt vmcnt(6)
	v_mfma_f32_32x32x64_f8f6f4 v[56:71], v[244:247], v[72:75], 0 cbsz:4 blgp:4
	s_add_i32 s1, s13, 8
	s_nop 0
	v_readlane_b32 s4, v151, s1
	v_pk_fma_f32 v[48:49], v[116:117], v[160:161], v[48:49] op_sel_hi:[1,0,1]
	s_lshr_b32 s4, s4, 7
	v_pk_fma_f32 v[50:51], v[118:119], v[160:161], v[50:51] op_sel_hi:[1,0,1]
	s_lshl_b32 s4, s4, 10
	v_pk_fma_f32 v[52:53], v[120:121], v[160:161], v[52:53] op_sel_hi:[1,0,1]
	s_add_u32 s24, s14, s4
	v_pk_fma_f32 v[54:55], v[122:123], v[160:161], v[54:55] op_sel_hi:[1,0,1]
	s_addc_u32 s25, s15, 0
	v_pk_fma_f32 v[228:229], v[124:125], v[160:161], v[228:229] op_sel_hi:[1,0,1]
	v_pk_fma_f32 v[230:231], v[126:127], v[160:161], v[230:231] op_sel_hi:[1,0,1]
	v_pk_fma_f32 v[232:233], v[128:129], v[160:161], v[232:233] op_sel_hi:[1,0,1]
	v_pk_fma_f32 v[234:235], v[130:131], v[160:161], v[234:235] op_sel_hi:[1,0,1]
	v_mfma_f32_32x32x64_f8f6f4 v[116:131], v[248:251], v[72:75], 0 cbsz:4 blgp:4
	global_load_dwordx4 v[144:147], v253, s[24:25]
	s_waitcnt lgkmcnt(0)
	v_cvt_f32_f16_e32 v254, v112
	ds_read_b32 v113, v252 offset:540
	v_pk_fma_f32 v[0:1], v[56:57], v[254:255], v[0:1] op_sel_hi:[1,0,1]
	v_pk_fma_f32 v[2:3], v[58:59], v[254:255], v[2:3] op_sel_hi:[1,0,1]
	v_pk_fma_f32 v[4:5], v[60:61], v[254:255], v[4:5] op_sel_hi:[1,0,1]
	v_pk_fma_f32 v[6:7], v[62:63], v[254:255], v[6:7] op_sel_hi:[1,0,1]
	v_pk_fma_f32 v[8:9], v[64:65], v[254:255], v[8:9] op_sel_hi:[1,0,1]
	v_pk_fma_f32 v[10:11], v[66:67], v[254:255], v[10:11] op_sel_hi:[1,0,1]
	v_pk_fma_f32 v[12:13], v[68:69], v[254:255], v[12:13] op_sel_hi:[1,0,1]
	v_pk_fma_f32 v[14:15], v[70:71], v[254:255], v[14:15] op_sel_hi:[1,0,1]
	s_waitcnt vmcnt(6)
	v_mfma_f32_32x32x64_f8f6f4 v[56:71], v[244:247], v[156:159], 0 cbsz:4 blgp:4
	s_add_i32 s1, s13, 9
	s_nop 0
	v_readlane_b32 s4, v111, s1
	v_pk_fma_f32 v[16:17], v[116:117], v[254:255], v[16:17] op_sel_hi:[1,0,1]
	s_lshr_b32 s4, s4, 7
	v_pk_fma_f32 v[18:19], v[118:119], v[254:255], v[18:19] op_sel_hi:[1,0,1]
	s_lshl_b32 s4, s4, 10
	v_pk_fma_f32 v[20:21], v[120:121], v[254:255], v[20:21] op_sel_hi:[1,0,1]
	s_add_u32 s24, s14, s4
	v_pk_fma_f32 v[22:23], v[122:123], v[254:255], v[22:23] op_sel_hi:[1,0,1]
	s_addc_u32 s25, s15, 0
	v_pk_fma_f32 v[24:25], v[124:125], v[254:255], v[24:25] op_sel_hi:[1,0,1]
	v_pk_fma_f32 v[26:27], v[126:127], v[254:255], v[26:27] op_sel_hi:[1,0,1]
	v_pk_fma_f32 v[28:29], v[128:129], v[254:255], v[28:29] op_sel_hi:[1,0,1]
	v_pk_fma_f32 v[30:31], v[130:131], v[254:255], v[30:31] op_sel_hi:[1,0,1]
	v_mfma_f32_32x32x64_f8f6f4 v[116:131], v[248:251], v[156:159], 0 cbsz:4 blgp:4
	global_load_dwordx4 v[72:75], v253, s[24:25]
	s_waitcnt lgkmcnt(0)
	v_cvt_f32_f16_e32 v160, v113
	ds_read_b32 v112, v252 offset:1052
	v_pk_fma_f32 v[164:165], v[56:57], v[160:161], v[164:165] op_sel_hi:[1,0,1]
	v_pk_fma_f32 v[166:167], v[58:59], v[160:161], v[166:167] op_sel_hi:[1,0,1]
	v_pk_fma_f32 v[168:169], v[60:61], v[160:161], v[168:169] op_sel_hi:[1,0,1]
	v_pk_fma_f32 v[170:171], v[62:63], v[160:161], v[170:171] op_sel_hi:[1,0,1]
	v_pk_fma_f32 v[172:173], v[64:65], v[160:161], v[172:173] op_sel_hi:[1,0,1]
	v_pk_fma_f32 v[174:175], v[66:67], v[160:161], v[174:175] op_sel_hi:[1,0,1]
	v_pk_fma_f32 v[176:177], v[68:69], v[160:161], v[176:177] op_sel_hi:[1,0,1]
	v_pk_fma_f32 v[178:179], v[70:71], v[160:161], v[178:179] op_sel_hi:[1,0,1]
	s_waitcnt vmcnt(6)
	v_mfma_f32_32x32x64_f8f6f4 v[56:71], v[244:247], v[236:239], 0 cbsz:4 blgp:4
	s_add_i32 s1, s13, 9
	s_nop 0
	v_readlane_b32 s4, v115, s1
	v_pk_fma_f32 v[180:181], v[116:117], v[160:161], v[180:181] op_sel_hi:[1,0,1]
	s_lshr_b32 s4, s4, 7
	v_pk_fma_f32 v[182:183], v[118:119], v[160:161], v[182:183] op_sel_hi:[1,0,1]
	s_lshl_b32 s4, s4, 10
	v_pk_fma_f32 v[184:185], v[120:121], v[160:161], v[184:185] op_sel_hi:[1,0,1]
	s_add_u32 s24, s14, s4
	v_pk_fma_f32 v[186:187], v[122:123], v[160:161], v[186:187] op_sel_hi:[1,0,1]
	s_addc_u32 s25, s15, 0
	v_pk_fma_f32 v[188:189], v[124:125], v[160:161], v[188:189] op_sel_hi:[1,0,1]
	v_pk_fma_f32 v[190:191], v[126:127], v[160:161], v[190:191] op_sel_hi:[1,0,1]
	v_pk_fma_f32 v[192:193], v[128:129], v[160:161], v[192:193] op_sel_hi:[1,0,1]
	v_pk_fma_f32 v[194:195], v[130:131], v[160:161], v[194:195] op_sel_hi:[1,0,1]
	v_mfma_f32_32x32x64_f8f6f4 v[116:131], v[248:251], v[236:239], 0 cbsz:4 blgp:4
	global_load_dwordx4 v[156:159], v253, s[24:25]
	s_waitcnt lgkmcnt(0)
	v_cvt_f32_f16_e32 v254, v112
	ds_read_b32 v113, v252 offset:1564
	v_pk_fma_f32 v[196:197], v[56:57], v[254:255], v[196:197] op_sel_hi:[1,0,1]
	v_pk_fma_f32 v[198:199], v[58:59], v[254:255], v[198:199] op_sel_hi:[1,0,1]
	v_pk_fma_f32 v[200:201], v[60:61], v[254:255], v[200:201] op_sel_hi:[1,0,1]
	v_pk_fma_f32 v[202:203], v[62:63], v[254:255], v[202:203] op_sel_hi:[1,0,1]
	v_pk_fma_f32 v[204:205], v[64:65], v[254:255], v[204:205] op_sel_hi:[1,0,1]
	v_pk_fma_f32 v[206:207], v[66:67], v[254:255], v[206:207] op_sel_hi:[1,0,1]
	v_pk_fma_f32 v[208:209], v[68:69], v[254:255], v[208:209] op_sel_hi:[1,0,1]
	v_pk_fma_f32 v[210:211], v[70:71], v[254:255], v[210:211] op_sel_hi:[1,0,1]
	s_waitcnt vmcnt(6)
	v_mfma_f32_32x32x64_f8f6f4 v[56:71], v[244:247], v[240:243], 0 cbsz:4 blgp:4
	s_add_i32 s1, s13, 9
	s_nop 0
	v_readlane_b32 s4, v150, s1
	v_pk_fma_f32 v[212:213], v[116:117], v[254:255], v[212:213] op_sel_hi:[1,0,1]
	s_lshr_b32 s4, s4, 7
	v_pk_fma_f32 v[214:215], v[118:119], v[254:255], v[214:215] op_sel_hi:[1,0,1]
	s_lshl_b32 s4, s4, 10
	v_pk_fma_f32 v[216:217], v[120:121], v[254:255], v[216:217] op_sel_hi:[1,0,1]
	s_add_u32 s24, s14, s4
	v_pk_fma_f32 v[218:219], v[122:123], v[254:255], v[218:219] op_sel_hi:[1,0,1]
	s_addc_u32 s25, s15, 0
	v_pk_fma_f32 v[220:221], v[124:125], v[254:255], v[220:221] op_sel_hi:[1,0,1]
	v_pk_fma_f32 v[222:223], v[126:127], v[254:255], v[222:223] op_sel_hi:[1,0,1]
	v_pk_fma_f32 v[224:225], v[128:129], v[254:255], v[224:225] op_sel_hi:[1,0,1]
	v_pk_fma_f32 v[226:227], v[130:131], v[254:255], v[226:227] op_sel_hi:[1,0,1]
	v_mfma_f32_32x32x64_f8f6f4 v[116:131], v[248:251], v[240:243], 0 cbsz:4 blgp:4
	global_load_dwordx4 v[236:239], v253, s[24:25]
	s_waitcnt lgkmcnt(0)
	v_cvt_f32_f16_e32 v160, v113
	ds_read_b32 v112, v252 offset:32
	v_pk_fma_f32 v[32:33], v[56:57], v[160:161], v[32:33] op_sel_hi:[1,0,1]
	v_pk_fma_f32 v[34:35], v[58:59], v[160:161], v[34:35] op_sel_hi:[1,0,1]
	v_pk_fma_f32 v[36:37], v[60:61], v[160:161], v[36:37] op_sel_hi:[1,0,1]
	v_pk_fma_f32 v[38:39], v[62:63], v[160:161], v[38:39] op_sel_hi:[1,0,1]
	v_pk_fma_f32 v[40:41], v[64:65], v[160:161], v[40:41] op_sel_hi:[1,0,1]
	v_pk_fma_f32 v[42:43], v[66:67], v[160:161], v[42:43] op_sel_hi:[1,0,1]
	v_pk_fma_f32 v[44:45], v[68:69], v[160:161], v[44:45] op_sel_hi:[1,0,1]
	v_pk_fma_f32 v[46:47], v[70:71], v[160:161], v[46:47] op_sel_hi:[1,0,1]
	s_waitcnt vmcnt(6)
	v_mfma_f32_32x32x64_f8f6f4 v[56:71], v[244:247], v[132:135], 0 cbsz:4 blgp:4
	s_add_i32 s1, s13, 9
	s_nop 0
	v_readlane_b32 s4, v151, s1
	v_pk_fma_f32 v[48:49], v[116:117], v[160:161], v[48:49] op_sel_hi:[1,0,1]
	s_lshr_b32 s4, s4, 7
	v_pk_fma_f32 v[50:51], v[118:119], v[160:161], v[50:51] op_sel_hi:[1,0,1]
	s_lshl_b32 s4, s4, 10
	v_pk_fma_f32 v[52:53], v[120:121], v[160:161], v[52:53] op_sel_hi:[1,0,1]
	s_add_u32 s24, s14, s4
	v_pk_fma_f32 v[54:55], v[122:123], v[160:161], v[54:55] op_sel_hi:[1,0,1]
	s_addc_u32 s25, s15, 0
	v_pk_fma_f32 v[228:229], v[124:125], v[160:161], v[228:229] op_sel_hi:[1,0,1]
	v_pk_fma_f32 v[230:231], v[126:127], v[160:161], v[230:231] op_sel_hi:[1,0,1]
	v_pk_fma_f32 v[232:233], v[128:129], v[160:161], v[232:233] op_sel_hi:[1,0,1]
	v_pk_fma_f32 v[234:235], v[130:131], v[160:161], v[234:235] op_sel_hi:[1,0,1]
	v_mfma_f32_32x32x64_f8f6f4 v[116:131], v[248:251], v[132:135], 0 cbsz:4 blgp:4
	global_load_dwordx4 v[240:243], v253, s[24:25]
	s_waitcnt lgkmcnt(0)
	v_cvt_f32_f16_e32 v254, v112
	ds_read_b32 v113, v252 offset:544
	v_pk_fma_f32 v[0:1], v[56:57], v[254:255], v[0:1] op_sel_hi:[1,0,1]
	v_pk_fma_f32 v[2:3], v[58:59], v[254:255], v[2:3] op_sel_hi:[1,0,1]
	v_pk_fma_f32 v[4:5], v[60:61], v[254:255], v[4:5] op_sel_hi:[1,0,1]
	v_pk_fma_f32 v[6:7], v[62:63], v[254:255], v[6:7] op_sel_hi:[1,0,1]
	v_pk_fma_f32 v[8:9], v[64:65], v[254:255], v[8:9] op_sel_hi:[1,0,1]
	v_pk_fma_f32 v[10:11], v[66:67], v[254:255], v[10:11] op_sel_hi:[1,0,1]
	v_pk_fma_f32 v[12:13], v[68:69], v[254:255], v[12:13] op_sel_hi:[1,0,1]
	v_pk_fma_f32 v[14:15], v[70:71], v[254:255], v[14:15] op_sel_hi:[1,0,1]
	s_waitcnt vmcnt(6)
	v_mfma_f32_32x32x64_f8f6f4 v[56:71], v[244:247], v[136:139], 0 cbsz:4 blgp:4
	s_add_i32 s1, s13, 10
	s_nop 0
	v_readlane_b32 s4, v111, s1
	v_pk_fma_f32 v[16:17], v[116:117], v[254:255], v[16:17] op_sel_hi:[1,0,1]
	s_lshr_b32 s4, s4, 7
	v_pk_fma_f32 v[18:19], v[118:119], v[254:255], v[18:19] op_sel_hi:[1,0,1]
	s_lshl_b32 s4, s4, 10
	v_pk_fma_f32 v[20:21], v[120:121], v[254:255], v[20:21] op_sel_hi:[1,0,1]
	s_add_u32 s24, s14, s4
	v_pk_fma_f32 v[22:23], v[122:123], v[254:255], v[22:23] op_sel_hi:[1,0,1]
	s_addc_u32 s25, s15, 0
	v_pk_fma_f32 v[24:25], v[124:125], v[254:255], v[24:25] op_sel_hi:[1,0,1]
	v_pk_fma_f32 v[26:27], v[126:127], v[254:255], v[26:27] op_sel_hi:[1,0,1]
	v_pk_fma_f32 v[28:29], v[128:129], v[254:255], v[28:29] op_sel_hi:[1,0,1]
	v_pk_fma_f32 v[30:31], v[130:131], v[254:255], v[30:31] op_sel_hi:[1,0,1]
	v_mfma_f32_32x32x64_f8f6f4 v[116:131], v[248:251], v[136:139], 0 cbsz:4 blgp:4
	global_load_dwordx4 v[132:135], v253, s[24:25]
	s_waitcnt lgkmcnt(0)
	v_cvt_f32_f16_e32 v160, v113
	ds_read_b32 v112, v252 offset:1056
	v_pk_fma_f32 v[164:165], v[56:57], v[160:161], v[164:165] op_sel_hi:[1,0,1]
	v_pk_fma_f32 v[166:167], v[58:59], v[160:161], v[166:167] op_sel_hi:[1,0,1]
	v_pk_fma_f32 v[168:169], v[60:61], v[160:161], v[168:169] op_sel_hi:[1,0,1]
	v_pk_fma_f32 v[170:171], v[62:63], v[160:161], v[170:171] op_sel_hi:[1,0,1]
	v_pk_fma_f32 v[172:173], v[64:65], v[160:161], v[172:173] op_sel_hi:[1,0,1]
	v_pk_fma_f32 v[174:175], v[66:67], v[160:161], v[174:175] op_sel_hi:[1,0,1]
	v_pk_fma_f32 v[176:177], v[68:69], v[160:161], v[176:177] op_sel_hi:[1,0,1]
	v_pk_fma_f32 v[178:179], v[70:71], v[160:161], v[178:179] op_sel_hi:[1,0,1]
	s_waitcnt vmcnt(6)
	v_mfma_f32_32x32x64_f8f6f4 v[56:71], v[244:247], v[140:143], 0 cbsz:4 blgp:4
	s_add_i32 s1, s13, 10
	s_nop 0
	v_readlane_b32 s4, v115, s1
	v_pk_fma_f32 v[180:181], v[116:117], v[160:161], v[180:181] op_sel_hi:[1,0,1]
	s_lshr_b32 s4, s4, 7
	v_pk_fma_f32 v[182:183], v[118:119], v[160:161], v[182:183] op_sel_hi:[1,0,1]
	s_lshl_b32 s4, s4, 10
	v_pk_fma_f32 v[184:185], v[120:121], v[160:161], v[184:185] op_sel_hi:[1,0,1]
	s_add_u32 s24, s14, s4
	v_pk_fma_f32 v[186:187], v[122:123], v[160:161], v[186:187] op_sel_hi:[1,0,1]
	s_addc_u32 s25, s15, 0
	v_pk_fma_f32 v[188:189], v[124:125], v[160:161], v[188:189] op_sel_hi:[1,0,1]
	v_pk_fma_f32 v[190:191], v[126:127], v[160:161], v[190:191] op_sel_hi:[1,0,1]
	v_pk_fma_f32 v[192:193], v[128:129], v[160:161], v[192:193] op_sel_hi:[1,0,1]
	v_pk_fma_f32 v[194:195], v[130:131], v[160:161], v[194:195] op_sel_hi:[1,0,1]
	v_mfma_f32_32x32x64_f8f6f4 v[116:131], v[248:251], v[140:143], 0 cbsz:4 blgp:4
	global_load_dwordx4 v[136:139], v253, s[24:25]
	s_waitcnt lgkmcnt(0)
	v_cvt_f32_f16_e32 v254, v112
	ds_read_b32 v113, v252 offset:1568
	v_pk_fma_f32 v[196:197], v[56:57], v[254:255], v[196:197] op_sel_hi:[1,0,1]
	v_pk_fma_f32 v[198:199], v[58:59], v[254:255], v[198:199] op_sel_hi:[1,0,1]
	v_pk_fma_f32 v[200:201], v[60:61], v[254:255], v[200:201] op_sel_hi:[1,0,1]
	v_pk_fma_f32 v[202:203], v[62:63], v[254:255], v[202:203] op_sel_hi:[1,0,1]
	v_pk_fma_f32 v[204:205], v[64:65], v[254:255], v[204:205] op_sel_hi:[1,0,1]
	v_pk_fma_f32 v[206:207], v[66:67], v[254:255], v[206:207] op_sel_hi:[1,0,1]
	v_pk_fma_f32 v[208:209], v[68:69], v[254:255], v[208:209] op_sel_hi:[1,0,1]
	v_pk_fma_f32 v[210:211], v[70:71], v[254:255], v[210:211] op_sel_hi:[1,0,1]
	s_waitcnt vmcnt(6)
	v_mfma_f32_32x32x64_f8f6f4 v[56:71], v[244:247], v[144:147], 0 cbsz:4 blgp:4
	s_add_i32 s1, s13, 10
	s_nop 0
	v_readlane_b32 s4, v150, s1
	v_pk_fma_f32 v[212:213], v[116:117], v[254:255], v[212:213] op_sel_hi:[1,0,1]
	s_lshr_b32 s4, s4, 7
	v_pk_fma_f32 v[214:215], v[118:119], v[254:255], v[214:215] op_sel_hi:[1,0,1]
	s_lshl_b32 s4, s4, 10
	v_pk_fma_f32 v[216:217], v[120:121], v[254:255], v[216:217] op_sel_hi:[1,0,1]
	s_add_u32 s24, s14, s4
	v_pk_fma_f32 v[218:219], v[122:123], v[254:255], v[218:219] op_sel_hi:[1,0,1]
	s_addc_u32 s25, s15, 0
	v_pk_fma_f32 v[220:221], v[124:125], v[254:255], v[220:221] op_sel_hi:[1,0,1]
	v_pk_fma_f32 v[222:223], v[126:127], v[254:255], v[222:223] op_sel_hi:[1,0,1]
	v_pk_fma_f32 v[224:225], v[128:129], v[254:255], v[224:225] op_sel_hi:[1,0,1]
	v_pk_fma_f32 v[226:227], v[130:131], v[254:255], v[226:227] op_sel_hi:[1,0,1]
	v_mfma_f32_32x32x64_f8f6f4 v[116:131], v[248:251], v[144:147], 0 cbsz:4 blgp:4
	global_load_dwordx4 v[140:143], v253, s[24:25]
	s_waitcnt lgkmcnt(0)
	v_cvt_f32_f16_e32 v160, v113
	ds_read_b32 v112, v252 offset:36
	v_pk_fma_f32 v[32:33], v[56:57], v[160:161], v[32:33] op_sel_hi:[1,0,1]
	v_pk_fma_f32 v[34:35], v[58:59], v[160:161], v[34:35] op_sel_hi:[1,0,1]
	v_pk_fma_f32 v[36:37], v[60:61], v[160:161], v[36:37] op_sel_hi:[1,0,1]
	v_pk_fma_f32 v[38:39], v[62:63], v[160:161], v[38:39] op_sel_hi:[1,0,1]
	v_pk_fma_f32 v[40:41], v[64:65], v[160:161], v[40:41] op_sel_hi:[1,0,1]
	v_pk_fma_f32 v[42:43], v[66:67], v[160:161], v[42:43] op_sel_hi:[1,0,1]
	v_pk_fma_f32 v[44:45], v[68:69], v[160:161], v[44:45] op_sel_hi:[1,0,1]
	v_pk_fma_f32 v[46:47], v[70:71], v[160:161], v[46:47] op_sel_hi:[1,0,1]
	s_waitcnt vmcnt(6)
	v_mfma_f32_32x32x64_f8f6f4 v[56:71], v[244:247], v[72:75], 0 cbsz:4 blgp:4
	s_add_i32 s1, s13, 10
	s_nop 0
	v_readlane_b32 s4, v151, s1
	v_pk_fma_f32 v[48:49], v[116:117], v[160:161], v[48:49] op_sel_hi:[1,0,1]
	s_lshr_b32 s4, s4, 7
	v_pk_fma_f32 v[50:51], v[118:119], v[160:161], v[50:51] op_sel_hi:[1,0,1]
	s_lshl_b32 s4, s4, 10
	v_pk_fma_f32 v[52:53], v[120:121], v[160:161], v[52:53] op_sel_hi:[1,0,1]
	s_add_u32 s24, s14, s4
	v_pk_fma_f32 v[54:55], v[122:123], v[160:161], v[54:55] op_sel_hi:[1,0,1]
	s_addc_u32 s25, s15, 0
	v_pk_fma_f32 v[228:229], v[124:125], v[160:161], v[228:229] op_sel_hi:[1,0,1]
	v_pk_fma_f32 v[230:231], v[126:127], v[160:161], v[230:231] op_sel_hi:[1,0,1]
	v_pk_fma_f32 v[232:233], v[128:129], v[160:161], v[232:233] op_sel_hi:[1,0,1]
	v_pk_fma_f32 v[234:235], v[130:131], v[160:161], v[234:235] op_sel_hi:[1,0,1]
	v_mfma_f32_32x32x64_f8f6f4 v[116:131], v[248:251], v[72:75], 0 cbsz:4 blgp:4
	global_load_dwordx4 v[144:147], v253, s[24:25]
	s_waitcnt lgkmcnt(0)
	v_cvt_f32_f16_e32 v254, v112
	ds_read_b32 v113, v252 offset:548
	v_pk_fma_f32 v[0:1], v[56:57], v[254:255], v[0:1] op_sel_hi:[1,0,1]
	v_pk_fma_f32 v[2:3], v[58:59], v[254:255], v[2:3] op_sel_hi:[1,0,1]
	v_pk_fma_f32 v[4:5], v[60:61], v[254:255], v[4:5] op_sel_hi:[1,0,1]
	v_pk_fma_f32 v[6:7], v[62:63], v[254:255], v[6:7] op_sel_hi:[1,0,1]
	v_pk_fma_f32 v[8:9], v[64:65], v[254:255], v[8:9] op_sel_hi:[1,0,1]
	v_pk_fma_f32 v[10:11], v[66:67], v[254:255], v[10:11] op_sel_hi:[1,0,1]
	v_pk_fma_f32 v[12:13], v[68:69], v[254:255], v[12:13] op_sel_hi:[1,0,1]
	v_pk_fma_f32 v[14:15], v[70:71], v[254:255], v[14:15] op_sel_hi:[1,0,1]
	s_waitcnt vmcnt(6)
	v_mfma_f32_32x32x64_f8f6f4 v[56:71], v[244:247], v[156:159], 0 cbsz:4 blgp:4
	s_add_i32 s1, s13, 11
	s_nop 0
	v_readlane_b32 s4, v111, s1
	v_pk_fma_f32 v[16:17], v[116:117], v[254:255], v[16:17] op_sel_hi:[1,0,1]
	s_lshr_b32 s4, s4, 7
	v_pk_fma_f32 v[18:19], v[118:119], v[254:255], v[18:19] op_sel_hi:[1,0,1]
	s_lshl_b32 s4, s4, 10
	v_pk_fma_f32 v[20:21], v[120:121], v[254:255], v[20:21] op_sel_hi:[1,0,1]
	s_add_u32 s24, s14, s4
	v_pk_fma_f32 v[22:23], v[122:123], v[254:255], v[22:23] op_sel_hi:[1,0,1]
	s_addc_u32 s25, s15, 0
	v_pk_fma_f32 v[24:25], v[124:125], v[254:255], v[24:25] op_sel_hi:[1,0,1]
	v_pk_fma_f32 v[26:27], v[126:127], v[254:255], v[26:27] op_sel_hi:[1,0,1]
	v_pk_fma_f32 v[28:29], v[128:129], v[254:255], v[28:29] op_sel_hi:[1,0,1]
	v_pk_fma_f32 v[30:31], v[130:131], v[254:255], v[30:31] op_sel_hi:[1,0,1]
	v_mfma_f32_32x32x64_f8f6f4 v[116:131], v[248:251], v[156:159], 0 cbsz:4 blgp:4
	global_load_dwordx4 v[72:75], v253, s[24:25]
	s_waitcnt lgkmcnt(0)
	v_cvt_f32_f16_e32 v160, v113
	ds_read_b32 v112, v252 offset:1060
	v_pk_fma_f32 v[164:165], v[56:57], v[160:161], v[164:165] op_sel_hi:[1,0,1]
	v_pk_fma_f32 v[166:167], v[58:59], v[160:161], v[166:167] op_sel_hi:[1,0,1]
	v_pk_fma_f32 v[168:169], v[60:61], v[160:161], v[168:169] op_sel_hi:[1,0,1]
	v_pk_fma_f32 v[170:171], v[62:63], v[160:161], v[170:171] op_sel_hi:[1,0,1]
	v_pk_fma_f32 v[172:173], v[64:65], v[160:161], v[172:173] op_sel_hi:[1,0,1]
	v_pk_fma_f32 v[174:175], v[66:67], v[160:161], v[174:175] op_sel_hi:[1,0,1]
	v_pk_fma_f32 v[176:177], v[68:69], v[160:161], v[176:177] op_sel_hi:[1,0,1]
	v_pk_fma_f32 v[178:179], v[70:71], v[160:161], v[178:179] op_sel_hi:[1,0,1]
	s_waitcnt vmcnt(6)
	v_mfma_f32_32x32x64_f8f6f4 v[56:71], v[244:247], v[236:239], 0 cbsz:4 blgp:4
	s_add_i32 s1, s13, 11
	s_nop 0
	v_readlane_b32 s4, v115, s1
	v_pk_fma_f32 v[180:181], v[116:117], v[160:161], v[180:181] op_sel_hi:[1,0,1]
	s_lshr_b32 s4, s4, 7
	v_pk_fma_f32 v[182:183], v[118:119], v[160:161], v[182:183] op_sel_hi:[1,0,1]
	s_lshl_b32 s4, s4, 10
	v_pk_fma_f32 v[184:185], v[120:121], v[160:161], v[184:185] op_sel_hi:[1,0,1]
	s_add_u32 s24, s14, s4
	v_pk_fma_f32 v[186:187], v[122:123], v[160:161], v[186:187] op_sel_hi:[1,0,1]
	s_addc_u32 s25, s15, 0
	v_pk_fma_f32 v[188:189], v[124:125], v[160:161], v[188:189] op_sel_hi:[1,0,1]
	v_pk_fma_f32 v[190:191], v[126:127], v[160:161], v[190:191] op_sel_hi:[1,0,1]
	v_pk_fma_f32 v[192:193], v[128:129], v[160:161], v[192:193] op_sel_hi:[1,0,1]
	v_pk_fma_f32 v[194:195], v[130:131], v[160:161], v[194:195] op_sel_hi:[1,0,1]
	v_mfma_f32_32x32x64_f8f6f4 v[116:131], v[248:251], v[236:239], 0 cbsz:4 blgp:4
	global_load_dwordx4 v[156:159], v253, s[24:25]
	s_waitcnt lgkmcnt(0)
	v_cvt_f32_f16_e32 v254, v112
	ds_read_b32 v113, v252 offset:1572
	v_pk_fma_f32 v[196:197], v[56:57], v[254:255], v[196:197] op_sel_hi:[1,0,1]
	v_pk_fma_f32 v[198:199], v[58:59], v[254:255], v[198:199] op_sel_hi:[1,0,1]
	v_pk_fma_f32 v[200:201], v[60:61], v[254:255], v[200:201] op_sel_hi:[1,0,1]
	v_pk_fma_f32 v[202:203], v[62:63], v[254:255], v[202:203] op_sel_hi:[1,0,1]
	v_pk_fma_f32 v[204:205], v[64:65], v[254:255], v[204:205] op_sel_hi:[1,0,1]
	v_pk_fma_f32 v[206:207], v[66:67], v[254:255], v[206:207] op_sel_hi:[1,0,1]
	v_pk_fma_f32 v[208:209], v[68:69], v[254:255], v[208:209] op_sel_hi:[1,0,1]
	v_pk_fma_f32 v[210:211], v[70:71], v[254:255], v[210:211] op_sel_hi:[1,0,1]
	s_waitcnt vmcnt(6)
	v_mfma_f32_32x32x64_f8f6f4 v[56:71], v[244:247], v[240:243], 0 cbsz:4 blgp:4
	s_add_i32 s1, s13, 11
	s_nop 0
	v_readlane_b32 s4, v150, s1
	v_pk_fma_f32 v[212:213], v[116:117], v[254:255], v[212:213] op_sel_hi:[1,0,1]
	s_lshr_b32 s4, s4, 7
	v_pk_fma_f32 v[214:215], v[118:119], v[254:255], v[214:215] op_sel_hi:[1,0,1]
	s_lshl_b32 s4, s4, 10
	v_pk_fma_f32 v[216:217], v[120:121], v[254:255], v[216:217] op_sel_hi:[1,0,1]
	s_add_u32 s24, s14, s4
	v_pk_fma_f32 v[218:219], v[122:123], v[254:255], v[218:219] op_sel_hi:[1,0,1]
	s_addc_u32 s25, s15, 0
	v_pk_fma_f32 v[220:221], v[124:125], v[254:255], v[220:221] op_sel_hi:[1,0,1]
	v_pk_fma_f32 v[222:223], v[126:127], v[254:255], v[222:223] op_sel_hi:[1,0,1]
	v_pk_fma_f32 v[224:225], v[128:129], v[254:255], v[224:225] op_sel_hi:[1,0,1]
	v_pk_fma_f32 v[226:227], v[130:131], v[254:255], v[226:227] op_sel_hi:[1,0,1]
	v_mfma_f32_32x32x64_f8f6f4 v[116:131], v[248:251], v[240:243], 0 cbsz:4 blgp:4
	global_load_dwordx4 v[236:239], v253, s[24:25]
	s_waitcnt lgkmcnt(0)
	v_cvt_f32_f16_e32 v160, v113
	ds_read_b32 v112, v252 offset:40
	v_pk_fma_f32 v[32:33], v[56:57], v[160:161], v[32:33] op_sel_hi:[1,0,1]
	v_pk_fma_f32 v[34:35], v[58:59], v[160:161], v[34:35] op_sel_hi:[1,0,1]
	v_pk_fma_f32 v[36:37], v[60:61], v[160:161], v[36:37] op_sel_hi:[1,0,1]
	v_pk_fma_f32 v[38:39], v[62:63], v[160:161], v[38:39] op_sel_hi:[1,0,1]
	v_pk_fma_f32 v[40:41], v[64:65], v[160:161], v[40:41] op_sel_hi:[1,0,1]
	v_pk_fma_f32 v[42:43], v[66:67], v[160:161], v[42:43] op_sel_hi:[1,0,1]
	v_pk_fma_f32 v[44:45], v[68:69], v[160:161], v[44:45] op_sel_hi:[1,0,1]
	v_pk_fma_f32 v[46:47], v[70:71], v[160:161], v[46:47] op_sel_hi:[1,0,1]
	s_waitcnt vmcnt(6)
	v_mfma_f32_32x32x64_f8f6f4 v[56:71], v[244:247], v[132:135], 0 cbsz:4 blgp:4
	s_add_i32 s1, s13, 11
	s_nop 0
	v_readlane_b32 s4, v151, s1
	v_pk_fma_f32 v[48:49], v[116:117], v[160:161], v[48:49] op_sel_hi:[1,0,1]
	s_lshr_b32 s4, s4, 7
	v_pk_fma_f32 v[50:51], v[118:119], v[160:161], v[50:51] op_sel_hi:[1,0,1]
	s_lshl_b32 s4, s4, 10
	v_pk_fma_f32 v[52:53], v[120:121], v[160:161], v[52:53] op_sel_hi:[1,0,1]
	s_add_u32 s24, s14, s4
	v_pk_fma_f32 v[54:55], v[122:123], v[160:161], v[54:55] op_sel_hi:[1,0,1]
	s_addc_u32 s25, s15, 0
	v_pk_fma_f32 v[228:229], v[124:125], v[160:161], v[228:229] op_sel_hi:[1,0,1]
	v_pk_fma_f32 v[230:231], v[126:127], v[160:161], v[230:231] op_sel_hi:[1,0,1]
	v_pk_fma_f32 v[232:233], v[128:129], v[160:161], v[232:233] op_sel_hi:[1,0,1]
	v_pk_fma_f32 v[234:235], v[130:131], v[160:161], v[234:235] op_sel_hi:[1,0,1]
	v_mfma_f32_32x32x64_f8f6f4 v[116:131], v[248:251], v[132:135], 0 cbsz:4 blgp:4
	global_load_dwordx4 v[240:243], v253, s[24:25]
	s_waitcnt lgkmcnt(0)
	v_cvt_f32_f16_e32 v254, v112
	ds_read_b32 v113, v252 offset:552
	v_pk_fma_f32 v[0:1], v[56:57], v[254:255], v[0:1] op_sel_hi:[1,0,1]
	v_pk_fma_f32 v[2:3], v[58:59], v[254:255], v[2:3] op_sel_hi:[1,0,1]
	v_pk_fma_f32 v[4:5], v[60:61], v[254:255], v[4:5] op_sel_hi:[1,0,1]
	v_pk_fma_f32 v[6:7], v[62:63], v[254:255], v[6:7] op_sel_hi:[1,0,1]
	v_pk_fma_f32 v[8:9], v[64:65], v[254:255], v[8:9] op_sel_hi:[1,0,1]
	v_pk_fma_f32 v[10:11], v[66:67], v[254:255], v[10:11] op_sel_hi:[1,0,1]
	v_pk_fma_f32 v[12:13], v[68:69], v[254:255], v[12:13] op_sel_hi:[1,0,1]
	v_pk_fma_f32 v[14:15], v[70:71], v[254:255], v[14:15] op_sel_hi:[1,0,1]
	s_waitcnt vmcnt(6)
	v_mfma_f32_32x32x64_f8f6f4 v[56:71], v[244:247], v[136:139], 0 cbsz:4 blgp:4
	s_add_i32 s1, s13, 12
	s_nop 0
	v_readlane_b32 s4, v111, s1
	v_pk_fma_f32 v[16:17], v[116:117], v[254:255], v[16:17] op_sel_hi:[1,0,1]
	s_lshr_b32 s4, s4, 7
	v_pk_fma_f32 v[18:19], v[118:119], v[254:255], v[18:19] op_sel_hi:[1,0,1]
	s_lshl_b32 s4, s4, 10
	v_pk_fma_f32 v[20:21], v[120:121], v[254:255], v[20:21] op_sel_hi:[1,0,1]
	s_add_u32 s24, s14, s4
	v_pk_fma_f32 v[22:23], v[122:123], v[254:255], v[22:23] op_sel_hi:[1,0,1]
	s_addc_u32 s25, s15, 0
	v_pk_fma_f32 v[24:25], v[124:125], v[254:255], v[24:25] op_sel_hi:[1,0,1]
	v_pk_fma_f32 v[26:27], v[126:127], v[254:255], v[26:27] op_sel_hi:[1,0,1]
	v_pk_fma_f32 v[28:29], v[128:129], v[254:255], v[28:29] op_sel_hi:[1,0,1]
	v_pk_fma_f32 v[30:31], v[130:131], v[254:255], v[30:31] op_sel_hi:[1,0,1]
	v_mfma_f32_32x32x64_f8f6f4 v[116:131], v[248:251], v[136:139], 0 cbsz:4 blgp:4
	global_load_dwordx4 v[132:135], v253, s[24:25]
	s_waitcnt lgkmcnt(0)
	v_cvt_f32_f16_e32 v160, v113
	ds_read_b32 v112, v252 offset:1064
	v_pk_fma_f32 v[164:165], v[56:57], v[160:161], v[164:165] op_sel_hi:[1,0,1]
	v_pk_fma_f32 v[166:167], v[58:59], v[160:161], v[166:167] op_sel_hi:[1,0,1]
	v_pk_fma_f32 v[168:169], v[60:61], v[160:161], v[168:169] op_sel_hi:[1,0,1]
	v_pk_fma_f32 v[170:171], v[62:63], v[160:161], v[170:171] op_sel_hi:[1,0,1]
	v_pk_fma_f32 v[172:173], v[64:65], v[160:161], v[172:173] op_sel_hi:[1,0,1]
	v_pk_fma_f32 v[174:175], v[66:67], v[160:161], v[174:175] op_sel_hi:[1,0,1]
	v_pk_fma_f32 v[176:177], v[68:69], v[160:161], v[176:177] op_sel_hi:[1,0,1]
	v_pk_fma_f32 v[178:179], v[70:71], v[160:161], v[178:179] op_sel_hi:[1,0,1]
	s_waitcnt vmcnt(6)
	v_mfma_f32_32x32x64_f8f6f4 v[56:71], v[244:247], v[140:143], 0 cbsz:4 blgp:4
	s_add_i32 s1, s13, 12
	s_nop 0
	v_readlane_b32 s4, v115, s1
	v_pk_fma_f32 v[180:181], v[116:117], v[160:161], v[180:181] op_sel_hi:[1,0,1]
	s_lshr_b32 s4, s4, 7
	v_pk_fma_f32 v[182:183], v[118:119], v[160:161], v[182:183] op_sel_hi:[1,0,1]
	s_lshl_b32 s4, s4, 10
	v_pk_fma_f32 v[184:185], v[120:121], v[160:161], v[184:185] op_sel_hi:[1,0,1]
	s_add_u32 s24, s14, s4
	v_pk_fma_f32 v[186:187], v[122:123], v[160:161], v[186:187] op_sel_hi:[1,0,1]
	s_addc_u32 s25, s15, 0
	v_pk_fma_f32 v[188:189], v[124:125], v[160:161], v[188:189] op_sel_hi:[1,0,1]
	v_pk_fma_f32 v[190:191], v[126:127], v[160:161], v[190:191] op_sel_hi:[1,0,1]
	v_pk_fma_f32 v[192:193], v[128:129], v[160:161], v[192:193] op_sel_hi:[1,0,1]
	v_pk_fma_f32 v[194:195], v[130:131], v[160:161], v[194:195] op_sel_hi:[1,0,1]
	v_mfma_f32_32x32x64_f8f6f4 v[116:131], v[248:251], v[140:143], 0 cbsz:4 blgp:4
	global_load_dwordx4 v[136:139], v253, s[24:25]
	s_waitcnt lgkmcnt(0)
	v_cvt_f32_f16_e32 v254, v112
	ds_read_b32 v113, v252 offset:1576
	v_pk_fma_f32 v[196:197], v[56:57], v[254:255], v[196:197] op_sel_hi:[1,0,1]
	v_pk_fma_f32 v[198:199], v[58:59], v[254:255], v[198:199] op_sel_hi:[1,0,1]
	v_pk_fma_f32 v[200:201], v[60:61], v[254:255], v[200:201] op_sel_hi:[1,0,1]
	v_pk_fma_f32 v[202:203], v[62:63], v[254:255], v[202:203] op_sel_hi:[1,0,1]
	v_pk_fma_f32 v[204:205], v[64:65], v[254:255], v[204:205] op_sel_hi:[1,0,1]
	v_pk_fma_f32 v[206:207], v[66:67], v[254:255], v[206:207] op_sel_hi:[1,0,1]
	v_pk_fma_f32 v[208:209], v[68:69], v[254:255], v[208:209] op_sel_hi:[1,0,1]
	v_pk_fma_f32 v[210:211], v[70:71], v[254:255], v[210:211] op_sel_hi:[1,0,1]
	s_waitcnt vmcnt(6)
	v_mfma_f32_32x32x64_f8f6f4 v[56:71], v[244:247], v[144:147], 0 cbsz:4 blgp:4
	s_add_i32 s1, s13, 12
	s_nop 0
	v_readlane_b32 s4, v150, s1
	v_pk_fma_f32 v[212:213], v[116:117], v[254:255], v[212:213] op_sel_hi:[1,0,1]
	s_lshr_b32 s4, s4, 7
	v_pk_fma_f32 v[214:215], v[118:119], v[254:255], v[214:215] op_sel_hi:[1,0,1]
	s_lshl_b32 s4, s4, 10
	v_pk_fma_f32 v[216:217], v[120:121], v[254:255], v[216:217] op_sel_hi:[1,0,1]
	s_add_u32 s24, s14, s4
	v_pk_fma_f32 v[218:219], v[122:123], v[254:255], v[218:219] op_sel_hi:[1,0,1]
	s_addc_u32 s25, s15, 0
	v_pk_fma_f32 v[220:221], v[124:125], v[254:255], v[220:221] op_sel_hi:[1,0,1]
	v_pk_fma_f32 v[222:223], v[126:127], v[254:255], v[222:223] op_sel_hi:[1,0,1]
	v_pk_fma_f32 v[224:225], v[128:129], v[254:255], v[224:225] op_sel_hi:[1,0,1]
	v_pk_fma_f32 v[226:227], v[130:131], v[254:255], v[226:227] op_sel_hi:[1,0,1]
	v_mfma_f32_32x32x64_f8f6f4 v[116:131], v[248:251], v[144:147], 0 cbsz:4 blgp:4
	global_load_dwordx4 v[140:143], v253, s[24:25]
	s_waitcnt lgkmcnt(0)
	v_cvt_f32_f16_e32 v160, v113
	ds_read_b32 v112, v252 offset:44
	v_pk_fma_f32 v[32:33], v[56:57], v[160:161], v[32:33] op_sel_hi:[1,0,1]
	v_pk_fma_f32 v[34:35], v[58:59], v[160:161], v[34:35] op_sel_hi:[1,0,1]
	v_pk_fma_f32 v[36:37], v[60:61], v[160:161], v[36:37] op_sel_hi:[1,0,1]
	v_pk_fma_f32 v[38:39], v[62:63], v[160:161], v[38:39] op_sel_hi:[1,0,1]
	v_pk_fma_f32 v[40:41], v[64:65], v[160:161], v[40:41] op_sel_hi:[1,0,1]
	v_pk_fma_f32 v[42:43], v[66:67], v[160:161], v[42:43] op_sel_hi:[1,0,1]
	v_pk_fma_f32 v[44:45], v[68:69], v[160:161], v[44:45] op_sel_hi:[1,0,1]
	v_pk_fma_f32 v[46:47], v[70:71], v[160:161], v[46:47] op_sel_hi:[1,0,1]
	s_waitcnt vmcnt(6)
	v_mfma_f32_32x32x64_f8f6f4 v[56:71], v[244:247], v[72:75], 0 cbsz:4 blgp:4
	s_add_i32 s1, s13, 12
	s_nop 0
	v_readlane_b32 s4, v151, s1
	v_pk_fma_f32 v[48:49], v[116:117], v[160:161], v[48:49] op_sel_hi:[1,0,1]
	s_lshr_b32 s4, s4, 7
	v_pk_fma_f32 v[50:51], v[118:119], v[160:161], v[50:51] op_sel_hi:[1,0,1]
	s_lshl_b32 s4, s4, 10
	v_pk_fma_f32 v[52:53], v[120:121], v[160:161], v[52:53] op_sel_hi:[1,0,1]
	s_add_u32 s24, s14, s4
	v_pk_fma_f32 v[54:55], v[122:123], v[160:161], v[54:55] op_sel_hi:[1,0,1]
	s_addc_u32 s25, s15, 0
	v_pk_fma_f32 v[228:229], v[124:125], v[160:161], v[228:229] op_sel_hi:[1,0,1]
	v_pk_fma_f32 v[230:231], v[126:127], v[160:161], v[230:231] op_sel_hi:[1,0,1]
	v_pk_fma_f32 v[232:233], v[128:129], v[160:161], v[232:233] op_sel_hi:[1,0,1]
	v_pk_fma_f32 v[234:235], v[130:131], v[160:161], v[234:235] op_sel_hi:[1,0,1]
	v_mfma_f32_32x32x64_f8f6f4 v[116:131], v[248:251], v[72:75], 0 cbsz:4 blgp:4
	global_load_dwordx4 v[144:147], v253, s[24:25]
	s_waitcnt lgkmcnt(0)
	v_cvt_f32_f16_e32 v254, v112
	ds_read_b32 v113, v252 offset:556
	v_pk_fma_f32 v[0:1], v[56:57], v[254:255], v[0:1] op_sel_hi:[1,0,1]
	v_pk_fma_f32 v[2:3], v[58:59], v[254:255], v[2:3] op_sel_hi:[1,0,1]
	v_pk_fma_f32 v[4:5], v[60:61], v[254:255], v[4:5] op_sel_hi:[1,0,1]
	v_pk_fma_f32 v[6:7], v[62:63], v[254:255], v[6:7] op_sel_hi:[1,0,1]
	v_pk_fma_f32 v[8:9], v[64:65], v[254:255], v[8:9] op_sel_hi:[1,0,1]
	v_pk_fma_f32 v[10:11], v[66:67], v[254:255], v[10:11] op_sel_hi:[1,0,1]
	v_pk_fma_f32 v[12:13], v[68:69], v[254:255], v[12:13] op_sel_hi:[1,0,1]
	v_pk_fma_f32 v[14:15], v[70:71], v[254:255], v[14:15] op_sel_hi:[1,0,1]
	s_waitcnt vmcnt(6)
	v_mfma_f32_32x32x64_f8f6f4 v[56:71], v[244:247], v[156:159], 0 cbsz:4 blgp:4
	s_add_i32 s1, s13, 13
	s_nop 0
	v_readlane_b32 s4, v111, s1
	v_pk_fma_f32 v[16:17], v[116:117], v[254:255], v[16:17] op_sel_hi:[1,0,1]
	s_lshr_b32 s4, s4, 7
	v_pk_fma_f32 v[18:19], v[118:119], v[254:255], v[18:19] op_sel_hi:[1,0,1]
	s_lshl_b32 s4, s4, 10
	v_pk_fma_f32 v[20:21], v[120:121], v[254:255], v[20:21] op_sel_hi:[1,0,1]
	s_add_u32 s24, s14, s4
	v_pk_fma_f32 v[22:23], v[122:123], v[254:255], v[22:23] op_sel_hi:[1,0,1]
	s_addc_u32 s25, s15, 0
	v_pk_fma_f32 v[24:25], v[124:125], v[254:255], v[24:25] op_sel_hi:[1,0,1]
	v_pk_fma_f32 v[26:27], v[126:127], v[254:255], v[26:27] op_sel_hi:[1,0,1]
	v_pk_fma_f32 v[28:29], v[128:129], v[254:255], v[28:29] op_sel_hi:[1,0,1]
	v_pk_fma_f32 v[30:31], v[130:131], v[254:255], v[30:31] op_sel_hi:[1,0,1]
	v_mfma_f32_32x32x64_f8f6f4 v[116:131], v[248:251], v[156:159], 0 cbsz:4 blgp:4
	global_load_dwordx4 v[72:75], v253, s[24:25]
	s_waitcnt lgkmcnt(0)
	v_cvt_f32_f16_e32 v160, v113
	ds_read_b32 v112, v252 offset:1068
	v_pk_fma_f32 v[164:165], v[56:57], v[160:161], v[164:165] op_sel_hi:[1,0,1]
	v_pk_fma_f32 v[166:167], v[58:59], v[160:161], v[166:167] op_sel_hi:[1,0,1]
	v_pk_fma_f32 v[168:169], v[60:61], v[160:161], v[168:169] op_sel_hi:[1,0,1]
	v_pk_fma_f32 v[170:171], v[62:63], v[160:161], v[170:171] op_sel_hi:[1,0,1]
	v_pk_fma_f32 v[172:173], v[64:65], v[160:161], v[172:173] op_sel_hi:[1,0,1]
	v_pk_fma_f32 v[174:175], v[66:67], v[160:161], v[174:175] op_sel_hi:[1,0,1]
	v_pk_fma_f32 v[176:177], v[68:69], v[160:161], v[176:177] op_sel_hi:[1,0,1]
	v_pk_fma_f32 v[178:179], v[70:71], v[160:161], v[178:179] op_sel_hi:[1,0,1]
	s_waitcnt vmcnt(6)
	v_mfma_f32_32x32x64_f8f6f4 v[56:71], v[244:247], v[236:239], 0 cbsz:4 blgp:4
	s_add_i32 s1, s13, 13
	s_nop 0
	v_readlane_b32 s4, v115, s1
	v_pk_fma_f32 v[180:181], v[116:117], v[160:161], v[180:181] op_sel_hi:[1,0,1]
	s_lshr_b32 s4, s4, 7
	v_pk_fma_f32 v[182:183], v[118:119], v[160:161], v[182:183] op_sel_hi:[1,0,1]
	s_lshl_b32 s4, s4, 10
	v_pk_fma_f32 v[184:185], v[120:121], v[160:161], v[184:185] op_sel_hi:[1,0,1]
	s_add_u32 s24, s14, s4
	v_pk_fma_f32 v[186:187], v[122:123], v[160:161], v[186:187] op_sel_hi:[1,0,1]
	s_addc_u32 s25, s15, 0
	v_pk_fma_f32 v[188:189], v[124:125], v[160:161], v[188:189] op_sel_hi:[1,0,1]
	v_pk_fma_f32 v[190:191], v[126:127], v[160:161], v[190:191] op_sel_hi:[1,0,1]
	v_pk_fma_f32 v[192:193], v[128:129], v[160:161], v[192:193] op_sel_hi:[1,0,1]
	v_pk_fma_f32 v[194:195], v[130:131], v[160:161], v[194:195] op_sel_hi:[1,0,1]
	v_mfma_f32_32x32x64_f8f6f4 v[116:131], v[248:251], v[236:239], 0 cbsz:4 blgp:4
	global_load_dwordx4 v[156:159], v253, s[24:25]
	s_waitcnt lgkmcnt(0)
	v_cvt_f32_f16_e32 v254, v112
	ds_read_b32 v113, v252 offset:1580
	v_pk_fma_f32 v[196:197], v[56:57], v[254:255], v[196:197] op_sel_hi:[1,0,1]
	v_pk_fma_f32 v[198:199], v[58:59], v[254:255], v[198:199] op_sel_hi:[1,0,1]
	v_pk_fma_f32 v[200:201], v[60:61], v[254:255], v[200:201] op_sel_hi:[1,0,1]
	v_pk_fma_f32 v[202:203], v[62:63], v[254:255], v[202:203] op_sel_hi:[1,0,1]
	v_pk_fma_f32 v[204:205], v[64:65], v[254:255], v[204:205] op_sel_hi:[1,0,1]
	v_pk_fma_f32 v[206:207], v[66:67], v[254:255], v[206:207] op_sel_hi:[1,0,1]
	v_pk_fma_f32 v[208:209], v[68:69], v[254:255], v[208:209] op_sel_hi:[1,0,1]
	v_pk_fma_f32 v[210:211], v[70:71], v[254:255], v[210:211] op_sel_hi:[1,0,1]
	s_waitcnt vmcnt(6)
	v_mfma_f32_32x32x64_f8f6f4 v[56:71], v[244:247], v[240:243], 0 cbsz:4 blgp:4
	s_add_i32 s1, s13, 13
	s_nop 0
	v_readlane_b32 s4, v150, s1
	v_pk_fma_f32 v[212:213], v[116:117], v[254:255], v[212:213] op_sel_hi:[1,0,1]
	s_lshr_b32 s4, s4, 7
	v_pk_fma_f32 v[214:215], v[118:119], v[254:255], v[214:215] op_sel_hi:[1,0,1]
	s_lshl_b32 s4, s4, 10
	v_pk_fma_f32 v[216:217], v[120:121], v[254:255], v[216:217] op_sel_hi:[1,0,1]
	s_add_u32 s24, s14, s4
	v_pk_fma_f32 v[218:219], v[122:123], v[254:255], v[218:219] op_sel_hi:[1,0,1]
	s_addc_u32 s25, s15, 0
	v_pk_fma_f32 v[220:221], v[124:125], v[254:255], v[220:221] op_sel_hi:[1,0,1]
	v_pk_fma_f32 v[222:223], v[126:127], v[254:255], v[222:223] op_sel_hi:[1,0,1]
	v_pk_fma_f32 v[224:225], v[128:129], v[254:255], v[224:225] op_sel_hi:[1,0,1]
	v_pk_fma_f32 v[226:227], v[130:131], v[254:255], v[226:227] op_sel_hi:[1,0,1]
	v_mfma_f32_32x32x64_f8f6f4 v[116:131], v[248:251], v[240:243], 0 cbsz:4 blgp:4
	global_load_dwordx4 v[236:239], v253, s[24:25]
	s_waitcnt lgkmcnt(0)
	v_cvt_f32_f16_e32 v160, v113
	ds_read_b32 v112, v252 offset:48
	v_pk_fma_f32 v[32:33], v[56:57], v[160:161], v[32:33] op_sel_hi:[1,0,1]
	v_pk_fma_f32 v[34:35], v[58:59], v[160:161], v[34:35] op_sel_hi:[1,0,1]
	v_pk_fma_f32 v[36:37], v[60:61], v[160:161], v[36:37] op_sel_hi:[1,0,1]
	v_pk_fma_f32 v[38:39], v[62:63], v[160:161], v[38:39] op_sel_hi:[1,0,1]
	v_pk_fma_f32 v[40:41], v[64:65], v[160:161], v[40:41] op_sel_hi:[1,0,1]
	v_pk_fma_f32 v[42:43], v[66:67], v[160:161], v[42:43] op_sel_hi:[1,0,1]
	v_pk_fma_f32 v[44:45], v[68:69], v[160:161], v[44:45] op_sel_hi:[1,0,1]
	v_pk_fma_f32 v[46:47], v[70:71], v[160:161], v[46:47] op_sel_hi:[1,0,1]
	s_waitcnt vmcnt(6)
	v_mfma_f32_32x32x64_f8f6f4 v[56:71], v[244:247], v[132:135], 0 cbsz:4 blgp:4
	s_add_i32 s1, s13, 13
	s_nop 0
	v_readlane_b32 s4, v151, s1
	v_pk_fma_f32 v[48:49], v[116:117], v[160:161], v[48:49] op_sel_hi:[1,0,1]
	s_lshr_b32 s4, s4, 7
	v_pk_fma_f32 v[50:51], v[118:119], v[160:161], v[50:51] op_sel_hi:[1,0,1]
	s_lshl_b32 s4, s4, 10
	v_pk_fma_f32 v[52:53], v[120:121], v[160:161], v[52:53] op_sel_hi:[1,0,1]
	s_add_u32 s24, s14, s4
	v_pk_fma_f32 v[54:55], v[122:123], v[160:161], v[54:55] op_sel_hi:[1,0,1]
	s_addc_u32 s25, s15, 0
	v_pk_fma_f32 v[228:229], v[124:125], v[160:161], v[228:229] op_sel_hi:[1,0,1]
	v_pk_fma_f32 v[230:231], v[126:127], v[160:161], v[230:231] op_sel_hi:[1,0,1]
	v_pk_fma_f32 v[232:233], v[128:129], v[160:161], v[232:233] op_sel_hi:[1,0,1]
	v_pk_fma_f32 v[234:235], v[130:131], v[160:161], v[234:235] op_sel_hi:[1,0,1]
	v_mfma_f32_32x32x64_f8f6f4 v[116:131], v[248:251], v[132:135], 0 cbsz:4 blgp:4
	global_load_dwordx4 v[240:243], v253, s[24:25]
	s_waitcnt lgkmcnt(0)
	v_cvt_f32_f16_e32 v254, v112
	ds_read_b32 v113, v252 offset:560
	v_pk_fma_f32 v[0:1], v[56:57], v[254:255], v[0:1] op_sel_hi:[1,0,1]
	v_pk_fma_f32 v[2:3], v[58:59], v[254:255], v[2:3] op_sel_hi:[1,0,1]
	v_pk_fma_f32 v[4:5], v[60:61], v[254:255], v[4:5] op_sel_hi:[1,0,1]
	v_pk_fma_f32 v[6:7], v[62:63], v[254:255], v[6:7] op_sel_hi:[1,0,1]
	v_pk_fma_f32 v[8:9], v[64:65], v[254:255], v[8:9] op_sel_hi:[1,0,1]
	v_pk_fma_f32 v[10:11], v[66:67], v[254:255], v[10:11] op_sel_hi:[1,0,1]
	v_pk_fma_f32 v[12:13], v[68:69], v[254:255], v[12:13] op_sel_hi:[1,0,1]
	v_pk_fma_f32 v[14:15], v[70:71], v[254:255], v[14:15] op_sel_hi:[1,0,1]
	s_waitcnt vmcnt(6)
	v_mfma_f32_32x32x64_f8f6f4 v[56:71], v[244:247], v[136:139], 0 cbsz:4 blgp:4
	s_add_i32 s1, s13, 14
	s_nop 0
	v_readlane_b32 s4, v111, s1
	v_pk_fma_f32 v[16:17], v[116:117], v[254:255], v[16:17] op_sel_hi:[1,0,1]
	s_lshr_b32 s4, s4, 7
	v_pk_fma_f32 v[18:19], v[118:119], v[254:255], v[18:19] op_sel_hi:[1,0,1]
	s_lshl_b32 s4, s4, 10
	v_pk_fma_f32 v[20:21], v[120:121], v[254:255], v[20:21] op_sel_hi:[1,0,1]
	s_add_u32 s24, s14, s4
	v_pk_fma_f32 v[22:23], v[122:123], v[254:255], v[22:23] op_sel_hi:[1,0,1]
	s_addc_u32 s25, s15, 0
	v_pk_fma_f32 v[24:25], v[124:125], v[254:255], v[24:25] op_sel_hi:[1,0,1]
	v_pk_fma_f32 v[26:27], v[126:127], v[254:255], v[26:27] op_sel_hi:[1,0,1]
	v_pk_fma_f32 v[28:29], v[128:129], v[254:255], v[28:29] op_sel_hi:[1,0,1]
	v_pk_fma_f32 v[30:31], v[130:131], v[254:255], v[30:31] op_sel_hi:[1,0,1]
	v_mfma_f32_32x32x64_f8f6f4 v[116:131], v[248:251], v[136:139], 0 cbsz:4 blgp:4
	global_load_dwordx4 v[132:135], v253, s[24:25]
	s_waitcnt lgkmcnt(0)
	v_cvt_f32_f16_e32 v160, v113
	ds_read_b32 v112, v252 offset:1072
	v_pk_fma_f32 v[164:165], v[56:57], v[160:161], v[164:165] op_sel_hi:[1,0,1]
	v_pk_fma_f32 v[166:167], v[58:59], v[160:161], v[166:167] op_sel_hi:[1,0,1]
	v_pk_fma_f32 v[168:169], v[60:61], v[160:161], v[168:169] op_sel_hi:[1,0,1]
	v_pk_fma_f32 v[170:171], v[62:63], v[160:161], v[170:171] op_sel_hi:[1,0,1]
	v_pk_fma_f32 v[172:173], v[64:65], v[160:161], v[172:173] op_sel_hi:[1,0,1]
	v_pk_fma_f32 v[174:175], v[66:67], v[160:161], v[174:175] op_sel_hi:[1,0,1]
	v_pk_fma_f32 v[176:177], v[68:69], v[160:161], v[176:177] op_sel_hi:[1,0,1]
	v_pk_fma_f32 v[178:179], v[70:71], v[160:161], v[178:179] op_sel_hi:[1,0,1]
	s_waitcnt vmcnt(6)
	v_mfma_f32_32x32x64_f8f6f4 v[56:71], v[244:247], v[140:143], 0 cbsz:4 blgp:4
	s_add_i32 s1, s13, 14
	s_nop 0
	v_readlane_b32 s4, v115, s1
	v_pk_fma_f32 v[180:181], v[116:117], v[160:161], v[180:181] op_sel_hi:[1,0,1]
	s_lshr_b32 s4, s4, 7
	v_pk_fma_f32 v[182:183], v[118:119], v[160:161], v[182:183] op_sel_hi:[1,0,1]
	s_lshl_b32 s4, s4, 10
	v_pk_fma_f32 v[184:185], v[120:121], v[160:161], v[184:185] op_sel_hi:[1,0,1]
	s_add_u32 s24, s14, s4
	v_pk_fma_f32 v[186:187], v[122:123], v[160:161], v[186:187] op_sel_hi:[1,0,1]
	s_addc_u32 s25, s15, 0
	v_pk_fma_f32 v[188:189], v[124:125], v[160:161], v[188:189] op_sel_hi:[1,0,1]
	v_pk_fma_f32 v[190:191], v[126:127], v[160:161], v[190:191] op_sel_hi:[1,0,1]
	v_pk_fma_f32 v[192:193], v[128:129], v[160:161], v[192:193] op_sel_hi:[1,0,1]
	v_pk_fma_f32 v[194:195], v[130:131], v[160:161], v[194:195] op_sel_hi:[1,0,1]
	v_mfma_f32_32x32x64_f8f6f4 v[116:131], v[248:251], v[140:143], 0 cbsz:4 blgp:4
	global_load_dwordx4 v[136:139], v253, s[24:25]
	s_waitcnt lgkmcnt(0)
	v_cvt_f32_f16_e32 v254, v112
	ds_read_b32 v113, v252 offset:1584
	v_pk_fma_f32 v[196:197], v[56:57], v[254:255], v[196:197] op_sel_hi:[1,0,1]
	v_pk_fma_f32 v[198:199], v[58:59], v[254:255], v[198:199] op_sel_hi:[1,0,1]
	v_pk_fma_f32 v[200:201], v[60:61], v[254:255], v[200:201] op_sel_hi:[1,0,1]
	v_pk_fma_f32 v[202:203], v[62:63], v[254:255], v[202:203] op_sel_hi:[1,0,1]
	v_pk_fma_f32 v[204:205], v[64:65], v[254:255], v[204:205] op_sel_hi:[1,0,1]
	v_pk_fma_f32 v[206:207], v[66:67], v[254:255], v[206:207] op_sel_hi:[1,0,1]
	v_pk_fma_f32 v[208:209], v[68:69], v[254:255], v[208:209] op_sel_hi:[1,0,1]
	v_pk_fma_f32 v[210:211], v[70:71], v[254:255], v[210:211] op_sel_hi:[1,0,1]
	s_waitcnt vmcnt(6)
	v_mfma_f32_32x32x64_f8f6f4 v[56:71], v[244:247], v[144:147], 0 cbsz:4 blgp:4
	s_add_i32 s1, s13, 14
	s_nop 0
	v_readlane_b32 s4, v150, s1
	v_pk_fma_f32 v[212:213], v[116:117], v[254:255], v[212:213] op_sel_hi:[1,0,1]
	s_lshr_b32 s4, s4, 7
	v_pk_fma_f32 v[214:215], v[118:119], v[254:255], v[214:215] op_sel_hi:[1,0,1]
	s_lshl_b32 s4, s4, 10
	v_pk_fma_f32 v[216:217], v[120:121], v[254:255], v[216:217] op_sel_hi:[1,0,1]
	s_add_u32 s24, s14, s4
	v_pk_fma_f32 v[218:219], v[122:123], v[254:255], v[218:219] op_sel_hi:[1,0,1]
	s_addc_u32 s25, s15, 0
	v_pk_fma_f32 v[220:221], v[124:125], v[254:255], v[220:221] op_sel_hi:[1,0,1]
	v_pk_fma_f32 v[222:223], v[126:127], v[254:255], v[222:223] op_sel_hi:[1,0,1]
	v_pk_fma_f32 v[224:225], v[128:129], v[254:255], v[224:225] op_sel_hi:[1,0,1]
	v_pk_fma_f32 v[226:227], v[130:131], v[254:255], v[226:227] op_sel_hi:[1,0,1]
	v_mfma_f32_32x32x64_f8f6f4 v[116:131], v[248:251], v[144:147], 0 cbsz:4 blgp:4
	global_load_dwordx4 v[140:143], v253, s[24:25]
	s_waitcnt lgkmcnt(0)
	v_cvt_f32_f16_e32 v160, v113
	ds_read_b32 v112, v252 offset:52
	v_pk_fma_f32 v[32:33], v[56:57], v[160:161], v[32:33] op_sel_hi:[1,0,1]
	v_pk_fma_f32 v[34:35], v[58:59], v[160:161], v[34:35] op_sel_hi:[1,0,1]
	v_pk_fma_f32 v[36:37], v[60:61], v[160:161], v[36:37] op_sel_hi:[1,0,1]
	v_pk_fma_f32 v[38:39], v[62:63], v[160:161], v[38:39] op_sel_hi:[1,0,1]
	v_pk_fma_f32 v[40:41], v[64:65], v[160:161], v[40:41] op_sel_hi:[1,0,1]
	v_pk_fma_f32 v[42:43], v[66:67], v[160:161], v[42:43] op_sel_hi:[1,0,1]
	v_pk_fma_f32 v[44:45], v[68:69], v[160:161], v[44:45] op_sel_hi:[1,0,1]
	v_pk_fma_f32 v[46:47], v[70:71], v[160:161], v[46:47] op_sel_hi:[1,0,1]
	s_waitcnt vmcnt(6)
	v_mfma_f32_32x32x64_f8f6f4 v[56:71], v[244:247], v[72:75], 0 cbsz:4 blgp:4
	s_add_i32 s1, s13, 14
	s_nop 0
	v_readlane_b32 s4, v151, s1
	v_pk_fma_f32 v[48:49], v[116:117], v[160:161], v[48:49] op_sel_hi:[1,0,1]
	s_lshr_b32 s4, s4, 7
	v_pk_fma_f32 v[50:51], v[118:119], v[160:161], v[50:51] op_sel_hi:[1,0,1]
	s_lshl_b32 s4, s4, 10
	v_pk_fma_f32 v[52:53], v[120:121], v[160:161], v[52:53] op_sel_hi:[1,0,1]
	s_add_u32 s24, s14, s4
	v_pk_fma_f32 v[54:55], v[122:123], v[160:161], v[54:55] op_sel_hi:[1,0,1]
	s_addc_u32 s25, s15, 0
	v_pk_fma_f32 v[228:229], v[124:125], v[160:161], v[228:229] op_sel_hi:[1,0,1]
	v_pk_fma_f32 v[230:231], v[126:127], v[160:161], v[230:231] op_sel_hi:[1,0,1]
	v_pk_fma_f32 v[232:233], v[128:129], v[160:161], v[232:233] op_sel_hi:[1,0,1]
	v_pk_fma_f32 v[234:235], v[130:131], v[160:161], v[234:235] op_sel_hi:[1,0,1]
	v_mfma_f32_32x32x64_f8f6f4 v[116:131], v[248:251], v[72:75], 0 cbsz:4 blgp:4
	global_load_dwordx4 v[144:147], v253, s[24:25]
	s_waitcnt lgkmcnt(0)
	v_cvt_f32_f16_e32 v254, v112
	ds_read_b32 v113, v252 offset:564
	v_pk_fma_f32 v[0:1], v[56:57], v[254:255], v[0:1] op_sel_hi:[1,0,1]
	v_pk_fma_f32 v[2:3], v[58:59], v[254:255], v[2:3] op_sel_hi:[1,0,1]
	v_pk_fma_f32 v[4:5], v[60:61], v[254:255], v[4:5] op_sel_hi:[1,0,1]
	v_pk_fma_f32 v[6:7], v[62:63], v[254:255], v[6:7] op_sel_hi:[1,0,1]
	v_pk_fma_f32 v[8:9], v[64:65], v[254:255], v[8:9] op_sel_hi:[1,0,1]
	v_pk_fma_f32 v[10:11], v[66:67], v[254:255], v[10:11] op_sel_hi:[1,0,1]
	v_pk_fma_f32 v[12:13], v[68:69], v[254:255], v[12:13] op_sel_hi:[1,0,1]
	v_pk_fma_f32 v[14:15], v[70:71], v[254:255], v[14:15] op_sel_hi:[1,0,1]
	s_waitcnt vmcnt(6)
	v_mfma_f32_32x32x64_f8f6f4 v[56:71], v[244:247], v[156:159], 0 cbsz:4 blgp:4
	s_add_i32 s1, s13, 15
	s_nop 0
	v_readlane_b32 s4, v111, s1
	v_pk_fma_f32 v[16:17], v[116:117], v[254:255], v[16:17] op_sel_hi:[1,0,1]
	s_lshr_b32 s4, s4, 7
	v_pk_fma_f32 v[18:19], v[118:119], v[254:255], v[18:19] op_sel_hi:[1,0,1]
	s_lshl_b32 s4, s4, 10
	v_pk_fma_f32 v[20:21], v[120:121], v[254:255], v[20:21] op_sel_hi:[1,0,1]
	s_add_u32 s24, s14, s4
	v_pk_fma_f32 v[22:23], v[122:123], v[254:255], v[22:23] op_sel_hi:[1,0,1]
	s_addc_u32 s25, s15, 0
	v_pk_fma_f32 v[24:25], v[124:125], v[254:255], v[24:25] op_sel_hi:[1,0,1]
	v_pk_fma_f32 v[26:27], v[126:127], v[254:255], v[26:27] op_sel_hi:[1,0,1]
	v_pk_fma_f32 v[28:29], v[128:129], v[254:255], v[28:29] op_sel_hi:[1,0,1]
	v_pk_fma_f32 v[30:31], v[130:131], v[254:255], v[30:31] op_sel_hi:[1,0,1]
	v_mfma_f32_32x32x64_f8f6f4 v[116:131], v[248:251], v[156:159], 0 cbsz:4 blgp:4
	global_load_dwordx4 v[72:75], v253, s[24:25]
	s_waitcnt lgkmcnt(0)
	v_cvt_f32_f16_e32 v160, v113
	ds_read_b32 v112, v252 offset:1076
	v_pk_fma_f32 v[164:165], v[56:57], v[160:161], v[164:165] op_sel_hi:[1,0,1]
	v_pk_fma_f32 v[166:167], v[58:59], v[160:161], v[166:167] op_sel_hi:[1,0,1]
	v_pk_fma_f32 v[168:169], v[60:61], v[160:161], v[168:169] op_sel_hi:[1,0,1]
	v_pk_fma_f32 v[170:171], v[62:63], v[160:161], v[170:171] op_sel_hi:[1,0,1]
	v_pk_fma_f32 v[172:173], v[64:65], v[160:161], v[172:173] op_sel_hi:[1,0,1]
	v_pk_fma_f32 v[174:175], v[66:67], v[160:161], v[174:175] op_sel_hi:[1,0,1]
	v_pk_fma_f32 v[176:177], v[68:69], v[160:161], v[176:177] op_sel_hi:[1,0,1]
	v_pk_fma_f32 v[178:179], v[70:71], v[160:161], v[178:179] op_sel_hi:[1,0,1]
	s_waitcnt vmcnt(6)
	v_mfma_f32_32x32x64_f8f6f4 v[56:71], v[244:247], v[236:239], 0 cbsz:4 blgp:4
	s_add_i32 s1, s13, 15
	s_nop 0
	v_readlane_b32 s4, v115, s1
	v_pk_fma_f32 v[180:181], v[116:117], v[160:161], v[180:181] op_sel_hi:[1,0,1]
	s_lshr_b32 s4, s4, 7
	v_pk_fma_f32 v[182:183], v[118:119], v[160:161], v[182:183] op_sel_hi:[1,0,1]
	s_lshl_b32 s4, s4, 10
	v_pk_fma_f32 v[184:185], v[120:121], v[160:161], v[184:185] op_sel_hi:[1,0,1]
	s_add_u32 s24, s14, s4
	v_pk_fma_f32 v[186:187], v[122:123], v[160:161], v[186:187] op_sel_hi:[1,0,1]
	s_addc_u32 s25, s15, 0
	v_pk_fma_f32 v[188:189], v[124:125], v[160:161], v[188:189] op_sel_hi:[1,0,1]
	v_pk_fma_f32 v[190:191], v[126:127], v[160:161], v[190:191] op_sel_hi:[1,0,1]
	v_pk_fma_f32 v[192:193], v[128:129], v[160:161], v[192:193] op_sel_hi:[1,0,1]
	v_pk_fma_f32 v[194:195], v[130:131], v[160:161], v[194:195] op_sel_hi:[1,0,1]
	v_mfma_f32_32x32x64_f8f6f4 v[116:131], v[248:251], v[236:239], 0 cbsz:4 blgp:4
	global_load_dwordx4 v[156:159], v253, s[24:25]
	s_waitcnt lgkmcnt(0)
	v_cvt_f32_f16_e32 v254, v112
	ds_read_b32 v113, v252 offset:1588
	v_pk_fma_f32 v[196:197], v[56:57], v[254:255], v[196:197] op_sel_hi:[1,0,1]
	v_pk_fma_f32 v[198:199], v[58:59], v[254:255], v[198:199] op_sel_hi:[1,0,1]
	v_pk_fma_f32 v[200:201], v[60:61], v[254:255], v[200:201] op_sel_hi:[1,0,1]
	v_pk_fma_f32 v[202:203], v[62:63], v[254:255], v[202:203] op_sel_hi:[1,0,1]
	v_pk_fma_f32 v[204:205], v[64:65], v[254:255], v[204:205] op_sel_hi:[1,0,1]
	v_pk_fma_f32 v[206:207], v[66:67], v[254:255], v[206:207] op_sel_hi:[1,0,1]
	v_pk_fma_f32 v[208:209], v[68:69], v[254:255], v[208:209] op_sel_hi:[1,0,1]
	v_pk_fma_f32 v[210:211], v[70:71], v[254:255], v[210:211] op_sel_hi:[1,0,1]
	s_waitcnt vmcnt(6)
	v_mfma_f32_32x32x64_f8f6f4 v[56:71], v[244:247], v[240:243], 0 cbsz:4 blgp:4
	s_add_i32 s1, s13, 15
	s_nop 0
	v_readlane_b32 s4, v150, s1
	v_pk_fma_f32 v[212:213], v[116:117], v[254:255], v[212:213] op_sel_hi:[1,0,1]
	s_lshr_b32 s4, s4, 7
	v_pk_fma_f32 v[214:215], v[118:119], v[254:255], v[214:215] op_sel_hi:[1,0,1]
	s_lshl_b32 s4, s4, 10
	v_pk_fma_f32 v[216:217], v[120:121], v[254:255], v[216:217] op_sel_hi:[1,0,1]
	s_add_u32 s24, s14, s4
	v_pk_fma_f32 v[218:219], v[122:123], v[254:255], v[218:219] op_sel_hi:[1,0,1]
	s_addc_u32 s25, s15, 0
	v_pk_fma_f32 v[220:221], v[124:125], v[254:255], v[220:221] op_sel_hi:[1,0,1]
	v_pk_fma_f32 v[222:223], v[126:127], v[254:255], v[222:223] op_sel_hi:[1,0,1]
	v_pk_fma_f32 v[224:225], v[128:129], v[254:255], v[224:225] op_sel_hi:[1,0,1]
	v_pk_fma_f32 v[226:227], v[130:131], v[254:255], v[226:227] op_sel_hi:[1,0,1]
	v_mfma_f32_32x32x64_f8f6f4 v[116:131], v[248:251], v[240:243], 0 cbsz:4 blgp:4
	global_load_dwordx4 v[236:239], v253, s[24:25]
	s_waitcnt lgkmcnt(0)
	v_cvt_f32_f16_e32 v160, v113
	ds_read_b32 v112, v252 offset:56
	v_pk_fma_f32 v[32:33], v[56:57], v[160:161], v[32:33] op_sel_hi:[1,0,1]
	v_pk_fma_f32 v[34:35], v[58:59], v[160:161], v[34:35] op_sel_hi:[1,0,1]
	v_pk_fma_f32 v[36:37], v[60:61], v[160:161], v[36:37] op_sel_hi:[1,0,1]
	v_pk_fma_f32 v[38:39], v[62:63], v[160:161], v[38:39] op_sel_hi:[1,0,1]
	v_pk_fma_f32 v[40:41], v[64:65], v[160:161], v[40:41] op_sel_hi:[1,0,1]
	v_pk_fma_f32 v[42:43], v[66:67], v[160:161], v[42:43] op_sel_hi:[1,0,1]
	v_pk_fma_f32 v[44:45], v[68:69], v[160:161], v[44:45] op_sel_hi:[1,0,1]
	v_pk_fma_f32 v[46:47], v[70:71], v[160:161], v[46:47] op_sel_hi:[1,0,1]
	s_waitcnt vmcnt(6)
	v_mfma_f32_32x32x64_f8f6f4 v[56:71], v[244:247], v[132:135], 0 cbsz:4 blgp:4
	s_add_i32 s1, s13, 15
	s_nop 0
	v_readlane_b32 s4, v151, s1
	v_pk_fma_f32 v[48:49], v[116:117], v[160:161], v[48:49] op_sel_hi:[1,0,1]
	s_lshr_b32 s4, s4, 7
	v_pk_fma_f32 v[50:51], v[118:119], v[160:161], v[50:51] op_sel_hi:[1,0,1]
	s_lshl_b32 s4, s4, 10
	v_pk_fma_f32 v[52:53], v[120:121], v[160:161], v[52:53] op_sel_hi:[1,0,1]
	s_add_u32 s24, s14, s4
	v_pk_fma_f32 v[54:55], v[122:123], v[160:161], v[54:55] op_sel_hi:[1,0,1]
	s_addc_u32 s25, s15, 0
	v_pk_fma_f32 v[228:229], v[124:125], v[160:161], v[228:229] op_sel_hi:[1,0,1]
	v_pk_fma_f32 v[230:231], v[126:127], v[160:161], v[230:231] op_sel_hi:[1,0,1]
	v_pk_fma_f32 v[232:233], v[128:129], v[160:161], v[232:233] op_sel_hi:[1,0,1]
	v_pk_fma_f32 v[234:235], v[130:131], v[160:161], v[234:235] op_sel_hi:[1,0,1]
	v_mfma_f32_32x32x64_f8f6f4 v[116:131], v[248:251], v[132:135], 0 cbsz:4 blgp:4
	global_load_dwordx4 v[240:243], v253, s[24:25]
	s_waitcnt lgkmcnt(0)
	v_cvt_f32_f16_e32 v254, v112
	ds_read_b32 v113, v252 offset:568
	v_pk_fma_f32 v[0:1], v[56:57], v[254:255], v[0:1] op_sel_hi:[1,0,1]
	v_pk_fma_f32 v[2:3], v[58:59], v[254:255], v[2:3] op_sel_hi:[1,0,1]
	v_pk_fma_f32 v[4:5], v[60:61], v[254:255], v[4:5] op_sel_hi:[1,0,1]
	v_pk_fma_f32 v[6:7], v[62:63], v[254:255], v[6:7] op_sel_hi:[1,0,1]
	v_pk_fma_f32 v[8:9], v[64:65], v[254:255], v[8:9] op_sel_hi:[1,0,1]
	v_pk_fma_f32 v[10:11], v[66:67], v[254:255], v[10:11] op_sel_hi:[1,0,1]
	v_pk_fma_f32 v[12:13], v[68:69], v[254:255], v[12:13] op_sel_hi:[1,0,1]
	v_pk_fma_f32 v[14:15], v[70:71], v[254:255], v[14:15] op_sel_hi:[1,0,1]
	s_waitcnt vmcnt(6)
	v_mfma_f32_32x32x64_f8f6f4 v[56:71], v[244:247], v[136:139], 0 cbsz:4 blgp:4
	s_add_i32 s1, s23, 0
	s_nop 0
	v_readlane_b32 s4, v152, s1
	v_pk_fma_f32 v[16:17], v[116:117], v[254:255], v[16:17] op_sel_hi:[1,0,1]
	s_lshr_b32 s4, s4, 7
	v_pk_fma_f32 v[18:19], v[118:119], v[254:255], v[18:19] op_sel_hi:[1,0,1]
	s_lshl_b32 s4, s4, 10
	v_pk_fma_f32 v[20:21], v[120:121], v[254:255], v[20:21] op_sel_hi:[1,0,1]
	s_add_u32 s24, s14, s4
	v_pk_fma_f32 v[22:23], v[122:123], v[254:255], v[22:23] op_sel_hi:[1,0,1]
	s_addc_u32 s25, s15, 0
	v_pk_fma_f32 v[24:25], v[124:125], v[254:255], v[24:25] op_sel_hi:[1,0,1]
	v_pk_fma_f32 v[26:27], v[126:127], v[254:255], v[26:27] op_sel_hi:[1,0,1]
	v_pk_fma_f32 v[28:29], v[128:129], v[254:255], v[28:29] op_sel_hi:[1,0,1]
	v_pk_fma_f32 v[30:31], v[130:131], v[254:255], v[30:31] op_sel_hi:[1,0,1]
	v_mfma_f32_32x32x64_f8f6f4 v[116:131], v[248:251], v[136:139], 0 cbsz:4 blgp:4
	global_load_dwordx4 v[132:135], v253, s[24:25]
	s_waitcnt lgkmcnt(0)
	v_cvt_f32_f16_e32 v160, v113
	ds_read_b32 v112, v252 offset:1080
	v_pk_fma_f32 v[164:165], v[56:57], v[160:161], v[164:165] op_sel_hi:[1,0,1]
	v_pk_fma_f32 v[166:167], v[58:59], v[160:161], v[166:167] op_sel_hi:[1,0,1]
	v_pk_fma_f32 v[168:169], v[60:61], v[160:161], v[168:169] op_sel_hi:[1,0,1]
	v_pk_fma_f32 v[170:171], v[62:63], v[160:161], v[170:171] op_sel_hi:[1,0,1]
	v_pk_fma_f32 v[172:173], v[64:65], v[160:161], v[172:173] op_sel_hi:[1,0,1]
	v_pk_fma_f32 v[174:175], v[66:67], v[160:161], v[174:175] op_sel_hi:[1,0,1]
	v_pk_fma_f32 v[176:177], v[68:69], v[160:161], v[176:177] op_sel_hi:[1,0,1]
	v_pk_fma_f32 v[178:179], v[70:71], v[160:161], v[178:179] op_sel_hi:[1,0,1]
	s_waitcnt vmcnt(6)
	v_mfma_f32_32x32x64_f8f6f4 v[56:71], v[244:247], v[140:143], 0 cbsz:4 blgp:4
	s_add_i32 s1, s23, 0
	s_nop 0
	v_readlane_b32 s4, v153, s1
	v_pk_fma_f32 v[180:181], v[116:117], v[160:161], v[180:181] op_sel_hi:[1,0,1]
	s_lshr_b32 s4, s4, 7
	v_pk_fma_f32 v[182:183], v[118:119], v[160:161], v[182:183] op_sel_hi:[1,0,1]
	s_lshl_b32 s4, s4, 10
	v_pk_fma_f32 v[184:185], v[120:121], v[160:161], v[184:185] op_sel_hi:[1,0,1]
	s_add_u32 s24, s14, s4
	v_pk_fma_f32 v[186:187], v[122:123], v[160:161], v[186:187] op_sel_hi:[1,0,1]
	s_addc_u32 s25, s15, 0
	v_pk_fma_f32 v[188:189], v[124:125], v[160:161], v[188:189] op_sel_hi:[1,0,1]
	v_pk_fma_f32 v[190:191], v[126:127], v[160:161], v[190:191] op_sel_hi:[1,0,1]
	v_pk_fma_f32 v[192:193], v[128:129], v[160:161], v[192:193] op_sel_hi:[1,0,1]
	v_pk_fma_f32 v[194:195], v[130:131], v[160:161], v[194:195] op_sel_hi:[1,0,1]
	v_mfma_f32_32x32x64_f8f6f4 v[116:131], v[248:251], v[140:143], 0 cbsz:4 blgp:4
	global_load_dwordx4 v[136:139], v253, s[24:25]
	s_waitcnt lgkmcnt(0)
	v_cvt_f32_f16_e32 v254, v112
	ds_read_b32 v113, v252 offset:1592
	v_pk_fma_f32 v[196:197], v[56:57], v[254:255], v[196:197] op_sel_hi:[1,0,1]
	v_pk_fma_f32 v[198:199], v[58:59], v[254:255], v[198:199] op_sel_hi:[1,0,1]
	v_pk_fma_f32 v[200:201], v[60:61], v[254:255], v[200:201] op_sel_hi:[1,0,1]
	v_pk_fma_f32 v[202:203], v[62:63], v[254:255], v[202:203] op_sel_hi:[1,0,1]
	v_pk_fma_f32 v[204:205], v[64:65], v[254:255], v[204:205] op_sel_hi:[1,0,1]
	v_pk_fma_f32 v[206:207], v[66:67], v[254:255], v[206:207] op_sel_hi:[1,0,1]
	v_pk_fma_f32 v[208:209], v[68:69], v[254:255], v[208:209] op_sel_hi:[1,0,1]
	v_pk_fma_f32 v[210:211], v[70:71], v[254:255], v[210:211] op_sel_hi:[1,0,1]
	s_waitcnt vmcnt(6)
	v_mfma_f32_32x32x64_f8f6f4 v[56:71], v[244:247], v[144:147], 0 cbsz:4 blgp:4
	s_add_i32 s1, s23, 0
	s_nop 0
	v_readlane_b32 s4, v154, s1
	v_pk_fma_f32 v[212:213], v[116:117], v[254:255], v[212:213] op_sel_hi:[1,0,1]
	s_lshr_b32 s4, s4, 7
	v_pk_fma_f32 v[214:215], v[118:119], v[254:255], v[214:215] op_sel_hi:[1,0,1]
	s_lshl_b32 s4, s4, 10
	v_pk_fma_f32 v[216:217], v[120:121], v[254:255], v[216:217] op_sel_hi:[1,0,1]
	s_add_u32 s24, s14, s4
	v_pk_fma_f32 v[218:219], v[122:123], v[254:255], v[218:219] op_sel_hi:[1,0,1]
	s_addc_u32 s25, s15, 0
	v_pk_fma_f32 v[220:221], v[124:125], v[254:255], v[220:221] op_sel_hi:[1,0,1]
	v_pk_fma_f32 v[222:223], v[126:127], v[254:255], v[222:223] op_sel_hi:[1,0,1]
	v_pk_fma_f32 v[224:225], v[128:129], v[254:255], v[224:225] op_sel_hi:[1,0,1]
	v_pk_fma_f32 v[226:227], v[130:131], v[254:255], v[226:227] op_sel_hi:[1,0,1]
	v_mfma_f32_32x32x64_f8f6f4 v[116:131], v[248:251], v[144:147], 0 cbsz:4 blgp:4
	global_load_dwordx4 v[140:143], v253, s[24:25]
	s_waitcnt lgkmcnt(0)
	v_cvt_f32_f16_e32 v160, v113
	ds_read_b32 v112, v252 offset:60
	v_pk_fma_f32 v[32:33], v[56:57], v[160:161], v[32:33] op_sel_hi:[1,0,1]
	v_pk_fma_f32 v[34:35], v[58:59], v[160:161], v[34:35] op_sel_hi:[1,0,1]
	v_pk_fma_f32 v[36:37], v[60:61], v[160:161], v[36:37] op_sel_hi:[1,0,1]
	v_pk_fma_f32 v[38:39], v[62:63], v[160:161], v[38:39] op_sel_hi:[1,0,1]
	v_pk_fma_f32 v[40:41], v[64:65], v[160:161], v[40:41] op_sel_hi:[1,0,1]
	v_pk_fma_f32 v[42:43], v[66:67], v[160:161], v[42:43] op_sel_hi:[1,0,1]
	v_pk_fma_f32 v[44:45], v[68:69], v[160:161], v[44:45] op_sel_hi:[1,0,1]
	v_pk_fma_f32 v[46:47], v[70:71], v[160:161], v[46:47] op_sel_hi:[1,0,1]
	s_waitcnt vmcnt(6)
	v_mfma_f32_32x32x64_f8f6f4 v[56:71], v[244:247], v[72:75], 0 cbsz:4 blgp:4
	s_add_i32 s1, s23, 0
	s_nop 0
	v_readlane_b32 s4, v155, s1
	v_pk_fma_f32 v[48:49], v[116:117], v[160:161], v[48:49] op_sel_hi:[1,0,1]
	s_lshr_b32 s4, s4, 7
	v_pk_fma_f32 v[50:51], v[118:119], v[160:161], v[50:51] op_sel_hi:[1,0,1]
	s_lshl_b32 s4, s4, 10
	v_pk_fma_f32 v[52:53], v[120:121], v[160:161], v[52:53] op_sel_hi:[1,0,1]
	s_add_u32 s24, s14, s4
	v_pk_fma_f32 v[54:55], v[122:123], v[160:161], v[54:55] op_sel_hi:[1,0,1]
	s_addc_u32 s25, s15, 0
	v_pk_fma_f32 v[228:229], v[124:125], v[160:161], v[228:229] op_sel_hi:[1,0,1]
	v_pk_fma_f32 v[230:231], v[126:127], v[160:161], v[230:231] op_sel_hi:[1,0,1]
	v_pk_fma_f32 v[232:233], v[128:129], v[160:161], v[232:233] op_sel_hi:[1,0,1]
	v_pk_fma_f32 v[234:235], v[130:131], v[160:161], v[234:235] op_sel_hi:[1,0,1]
	v_mfma_f32_32x32x64_f8f6f4 v[116:131], v[248:251], v[72:75], 0 cbsz:4 blgp:4
	global_load_dwordx4 v[144:147], v253, s[24:25]
	s_waitcnt lgkmcnt(0)
	v_cvt_f32_f16_e32 v254, v112
	ds_read_b32 v113, v252 offset:572
	v_pk_fma_f32 v[0:1], v[56:57], v[254:255], v[0:1] op_sel_hi:[1,0,1]
	v_pk_fma_f32 v[2:3], v[58:59], v[254:255], v[2:3] op_sel_hi:[1,0,1]
	v_pk_fma_f32 v[4:5], v[60:61], v[254:255], v[4:5] op_sel_hi:[1,0,1]
	v_pk_fma_f32 v[6:7], v[62:63], v[254:255], v[6:7] op_sel_hi:[1,0,1]
	v_pk_fma_f32 v[8:9], v[64:65], v[254:255], v[8:9] op_sel_hi:[1,0,1]
	v_pk_fma_f32 v[10:11], v[66:67], v[254:255], v[10:11] op_sel_hi:[1,0,1]
	v_pk_fma_f32 v[12:13], v[68:69], v[254:255], v[12:13] op_sel_hi:[1,0,1]
	v_pk_fma_f32 v[14:15], v[70:71], v[254:255], v[14:15] op_sel_hi:[1,0,1]
	s_waitcnt vmcnt(6)
	v_mfma_f32_32x32x64_f8f6f4 v[56:71], v[244:247], v[156:159], 0 cbsz:4 blgp:4
	s_add_i32 s1, s23, 1
	s_nop 0
	v_readlane_b32 s4, v152, s1
	v_pk_fma_f32 v[16:17], v[116:117], v[254:255], v[16:17] op_sel_hi:[1,0,1]
	s_lshr_b32 s4, s4, 7
	v_pk_fma_f32 v[18:19], v[118:119], v[254:255], v[18:19] op_sel_hi:[1,0,1]
	s_lshl_b32 s4, s4, 10
	v_pk_fma_f32 v[20:21], v[120:121], v[254:255], v[20:21] op_sel_hi:[1,0,1]
	s_add_u32 s24, s14, s4
	v_pk_fma_f32 v[22:23], v[122:123], v[254:255], v[22:23] op_sel_hi:[1,0,1]
	s_addc_u32 s25, s15, 0
	v_pk_fma_f32 v[24:25], v[124:125], v[254:255], v[24:25] op_sel_hi:[1,0,1]
	v_pk_fma_f32 v[26:27], v[126:127], v[254:255], v[26:27] op_sel_hi:[1,0,1]
	v_pk_fma_f32 v[28:29], v[128:129], v[254:255], v[28:29] op_sel_hi:[1,0,1]
	v_pk_fma_f32 v[30:31], v[130:131], v[254:255], v[30:31] op_sel_hi:[1,0,1]
	v_mfma_f32_32x32x64_f8f6f4 v[116:131], v[248:251], v[156:159], 0 cbsz:4 blgp:4
	global_load_dwordx4 v[72:75], v253, s[24:25]
	s_waitcnt lgkmcnt(0)
	v_cvt_f32_f16_e32 v160, v113
	ds_read_b32 v112, v252 offset:1084
	v_pk_fma_f32 v[164:165], v[56:57], v[160:161], v[164:165] op_sel_hi:[1,0,1]
	v_pk_fma_f32 v[166:167], v[58:59], v[160:161], v[166:167] op_sel_hi:[1,0,1]
	v_pk_fma_f32 v[168:169], v[60:61], v[160:161], v[168:169] op_sel_hi:[1,0,1]
	v_pk_fma_f32 v[170:171], v[62:63], v[160:161], v[170:171] op_sel_hi:[1,0,1]
	v_pk_fma_f32 v[172:173], v[64:65], v[160:161], v[172:173] op_sel_hi:[1,0,1]
	v_pk_fma_f32 v[174:175], v[66:67], v[160:161], v[174:175] op_sel_hi:[1,0,1]
	v_pk_fma_f32 v[176:177], v[68:69], v[160:161], v[176:177] op_sel_hi:[1,0,1]
	v_pk_fma_f32 v[178:179], v[70:71], v[160:161], v[178:179] op_sel_hi:[1,0,1]
	s_waitcnt vmcnt(6)
	v_mfma_f32_32x32x64_f8f6f4 v[56:71], v[244:247], v[236:239], 0 cbsz:4 blgp:4
	s_add_i32 s1, s23, 1
	s_nop 0
	v_readlane_b32 s4, v153, s1
	v_pk_fma_f32 v[180:181], v[116:117], v[160:161], v[180:181] op_sel_hi:[1,0,1]
	s_lshr_b32 s4, s4, 7
	v_pk_fma_f32 v[182:183], v[118:119], v[160:161], v[182:183] op_sel_hi:[1,0,1]
	s_lshl_b32 s4, s4, 10
	v_pk_fma_f32 v[184:185], v[120:121], v[160:161], v[184:185] op_sel_hi:[1,0,1]
	s_add_u32 s24, s14, s4
	v_pk_fma_f32 v[186:187], v[122:123], v[160:161], v[186:187] op_sel_hi:[1,0,1]
	s_addc_u32 s25, s15, 0
	v_pk_fma_f32 v[188:189], v[124:125], v[160:161], v[188:189] op_sel_hi:[1,0,1]
	v_pk_fma_f32 v[190:191], v[126:127], v[160:161], v[190:191] op_sel_hi:[1,0,1]
	v_pk_fma_f32 v[192:193], v[128:129], v[160:161], v[192:193] op_sel_hi:[1,0,1]
	v_pk_fma_f32 v[194:195], v[130:131], v[160:161], v[194:195] op_sel_hi:[1,0,1]
	v_mfma_f32_32x32x64_f8f6f4 v[116:131], v[248:251], v[236:239], 0 cbsz:4 blgp:4
	global_load_dwordx4 v[156:159], v253, s[24:25]
	s_waitcnt lgkmcnt(0)
	v_cvt_f32_f16_e32 v254, v112
	ds_read_b32 v113, v252 offset:1596
	v_pk_fma_f32 v[196:197], v[56:57], v[254:255], v[196:197] op_sel_hi:[1,0,1]
	v_pk_fma_f32 v[198:199], v[58:59], v[254:255], v[198:199] op_sel_hi:[1,0,1]
	v_pk_fma_f32 v[200:201], v[60:61], v[254:255], v[200:201] op_sel_hi:[1,0,1]
	v_pk_fma_f32 v[202:203], v[62:63], v[254:255], v[202:203] op_sel_hi:[1,0,1]
	v_pk_fma_f32 v[204:205], v[64:65], v[254:255], v[204:205] op_sel_hi:[1,0,1]
	v_pk_fma_f32 v[206:207], v[66:67], v[254:255], v[206:207] op_sel_hi:[1,0,1]
	v_pk_fma_f32 v[208:209], v[68:69], v[254:255], v[208:209] op_sel_hi:[1,0,1]
	v_pk_fma_f32 v[210:211], v[70:71], v[254:255], v[210:211] op_sel_hi:[1,0,1]
	s_waitcnt vmcnt(6)
	v_mfma_f32_32x32x64_f8f6f4 v[56:71], v[244:247], v[240:243], 0 cbsz:4 blgp:4
	s_add_i32 s1, s23, 1
	s_nop 0
	v_readlane_b32 s4, v154, s1
	v_pk_fma_f32 v[212:213], v[116:117], v[254:255], v[212:213] op_sel_hi:[1,0,1]
	s_lshr_b32 s4, s4, 7
	v_pk_fma_f32 v[214:215], v[118:119], v[254:255], v[214:215] op_sel_hi:[1,0,1]
	s_lshl_b32 s4, s4, 10
	v_pk_fma_f32 v[216:217], v[120:121], v[254:255], v[216:217] op_sel_hi:[1,0,1]
	s_add_u32 s24, s14, s4
	v_pk_fma_f32 v[218:219], v[122:123], v[254:255], v[218:219] op_sel_hi:[1,0,1]
	s_addc_u32 s25, s15, 0
	v_pk_fma_f32 v[220:221], v[124:125], v[254:255], v[220:221] op_sel_hi:[1,0,1]
	v_pk_fma_f32 v[222:223], v[126:127], v[254:255], v[222:223] op_sel_hi:[1,0,1]
	v_pk_fma_f32 v[224:225], v[128:129], v[254:255], v[224:225] op_sel_hi:[1,0,1]
	v_pk_fma_f32 v[226:227], v[130:131], v[254:255], v[226:227] op_sel_hi:[1,0,1]
	v_mfma_f32_32x32x64_f8f6f4 v[116:131], v[248:251], v[240:243], 0 cbsz:4 blgp:4
	global_load_dwordx4 v[236:239], v253, s[24:25]
	s_waitcnt lgkmcnt(0)
	v_cvt_f32_f16_e32 v160, v113
	ds_read_b32 v112, v252 offset:64
	v_pk_fma_f32 v[32:33], v[56:57], v[160:161], v[32:33] op_sel_hi:[1,0,1]
	v_pk_fma_f32 v[34:35], v[58:59], v[160:161], v[34:35] op_sel_hi:[1,0,1]
	v_pk_fma_f32 v[36:37], v[60:61], v[160:161], v[36:37] op_sel_hi:[1,0,1]
	v_pk_fma_f32 v[38:39], v[62:63], v[160:161], v[38:39] op_sel_hi:[1,0,1]
	v_pk_fma_f32 v[40:41], v[64:65], v[160:161], v[40:41] op_sel_hi:[1,0,1]
	v_pk_fma_f32 v[42:43], v[66:67], v[160:161], v[42:43] op_sel_hi:[1,0,1]
	v_pk_fma_f32 v[44:45], v[68:69], v[160:161], v[44:45] op_sel_hi:[1,0,1]
	v_pk_fma_f32 v[46:47], v[70:71], v[160:161], v[46:47] op_sel_hi:[1,0,1]
	s_add_i32 s11, s11, 1
	v_add_u32_e32 v252, 64, v252
	s_cmp_eq_u32 s11, 8
	s_cbranch_scc0 .Lmy_vloop
	s_nop 7
	v_pk_fma_f32 v[48:49], v[116:117], v[160:161], v[48:49] op_sel_hi:[1,0,1]
	v_pk_fma_f32 v[50:51], v[118:119], v[160:161], v[50:51] op_sel_hi:[1,0,1]
	v_pk_fma_f32 v[52:53], v[120:121], v[160:161], v[52:53] op_sel_hi:[1,0,1]
	v_pk_fma_f32 v[54:55], v[122:123], v[160:161], v[54:55] op_sel_hi:[1,0,1]
	v_pk_fma_f32 v[228:229], v[124:125], v[160:161], v[228:229] op_sel_hi:[1,0,1]
	v_pk_fma_f32 v[230:231], v[126:127], v[160:161], v[230:231] op_sel_hi:[1,0,1]
	v_pk_fma_f32 v[232:233], v[128:129], v[160:161], v[232:233] op_sel_hi:[1,0,1]
	v_pk_fma_f32 v[234:235], v[130:131], v[160:161], v[234:235] op_sel_hi:[1,0,1]
	s_waitcnt vmcnt(0) lgkmcnt(0)
	v_cvt_pk_f16_f32 v139, v0, v1
	v_cvt_pk_f16_f32 v130, v16, v17
	v_cvt_pk_f16_f32 v138, v2, v3
	v_cvt_pk_f16_f32 v129, v18, v19
	v_cvt_pk_f16_f32 v136, v4, v5
	v_cvt_pk_f16_f32 v128, v20, v21
	v_cvt_pk_f16_f32 v135, v6, v7
	v_cvt_pk_f16_f32 v127, v22, v23
	v_cvt_pk_f16_f32 v134, v8, v9
	v_cvt_pk_f16_f32 v126, v24, v25
	v_cvt_pk_f16_f32 v133, v10, v11
	v_cvt_pk_f16_f32 v114, v26, v27
	v_cvt_pk_f16_f32 v132, v12, v13
	v_cvt_pk_f16_f32 v140, v28, v29
	v_cvt_pk_f16_f32 v131, v14, v15
	v_cvt_pk_f16_f32 v137, v30, v31
	s_nop 1
	v_permlane32_swap_b32_e32 v139, v130
	v_permlane32_swap_b32_e32 v138, v129
	v_permlane32_swap_b32_e32 v136, v128
	v_permlane32_swap_b32_e32 v135, v127
	v_permlane32_swap_b32_e32 v134, v126
	v_permlane32_swap_b32_e32 v133, v114
	v_permlane32_swap_b32_e32 v132, v140
	v_permlane32_swap_b32_e32 v131, v137
	v_cvt_pk_f16_f32 v124, v164, v165
	v_cvt_pk_f16_f32 v113, v180, v181
	v_cvt_pk_f16_f32 v123, v166, v167
	v_cvt_pk_f16_f32 v112, v182, v183
	v_cvt_pk_f16_f32 v121, v168, v169
	v_cvt_pk_f16_f32 v67, v184, v185
	v_cvt_pk_f16_f32 v120, v170, v171
	v_cvt_pk_f16_f32 v66, v186, v187
	v_cvt_pk_f16_f32 v119, v172, v173
	v_cvt_pk_f16_f32 v65, v188, v189
	v_cvt_pk_f16_f32 v118, v174, v175
	v_cvt_pk_f16_f32 v64, v190, v191
	v_cvt_pk_f16_f32 v117, v176, v177
	v_cvt_pk_f16_f32 v125, v192, v193
	v_cvt_pk_f16_f32 v116, v178, v179
	v_cvt_pk_f16_f32 v122, v194, v195
	s_nop 1
	v_permlane32_swap_b32_e32 v124, v113
	v_permlane32_swap_b32_e32 v123, v112
	v_permlane32_swap_b32_e32 v121, v67
	v_permlane32_swap_b32_e32 v120, v66
	v_permlane32_swap_b32_e32 v119, v65
	v_permlane32_swap_b32_e32 v118, v64
	v_permlane32_swap_b32_e32 v117, v125
	v_permlane32_swap_b32_e32 v116, v122
	v_cvt_pk_f16_f32 v74, v196, v197
	v_cvt_pk_f16_f32 v61, v212, v213
	v_cvt_pk_f16_f32 v73, v198, v199
	v_cvt_pk_f16_f32 v60, v214, v215
	v_cvt_pk_f16_f32 v71, v200, v201
	v_cvt_pk_f16_f32 v59, v216, v217
	v_cvt_pk_f16_f32 v70, v202, v203
	v_cvt_pk_f16_f32 v58, v218, v219
	v_cvt_pk_f16_f32 v69, v204, v205
	v_cvt_pk_f16_f32 v57, v220, v221
	v_cvt_pk_f16_f32 v68, v206, v207
	v_cvt_pk_f16_f32 v56, v222, v223
	v_cvt_pk_f16_f32 v63, v208, v209
	v_cvt_pk_f16_f32 v75, v224, v225
	v_cvt_pk_f16_f32 v62, v210, v211
	v_cvt_pk_f16_f32 v72, v226, v227
	s_nop 1
	v_permlane32_swap_b32_e32 v74, v61
	v_permlane32_swap_b32_e32 v73, v60
	v_permlane32_swap_b32_e32 v71, v59
	v_permlane32_swap_b32_e32 v70, v58
	v_permlane32_swap_b32_e32 v69, v57
	v_permlane32_swap_b32_e32 v68, v56
	v_permlane32_swap_b32_e32 v63, v75
	v_permlane32_swap_b32_e32 v62, v72
	v_cvt_pk_f16_f32 v162, v32, v33
	v_cvt_pk_f16_f32 v146, v48, v49
	v_cvt_pk_f16_f32 v161, v34, v35
	v_cvt_pk_f16_f32 v145, v50, v51
	v_cvt_pk_f16_f32 v160, v36, v37
	v_cvt_pk_f16_f32 v144, v52, v53
	v_cvt_pk_f16_f32 v159, v38, v39
	v_cvt_pk_f16_f32 v143, v54, v55
	v_cvt_pk_f16_f32 v158, v40, v41
	v_cvt_pk_f16_f32 v142, v228, v229
	v_cvt_pk_f16_f32 v157, v42, v43
	v_cvt_pk_f16_f32 v141, v230, v231
	v_cvt_pk_f16_f32 v156, v44, v45
	v_cvt_pk_f16_f32 v149, v232, v233
	v_cvt_pk_f16_f32 v147, v46, v47
	v_cvt_pk_f16_f32 v148, v234, v235
	s_nop 1
	v_permlane32_swap_b32_e32 v162, v146
	v_permlane32_swap_b32_e32 v161, v145
	v_permlane32_swap_b32_e32 v160, v144
	v_permlane32_swap_b32_e32 v159, v143
	v_permlane32_swap_b32_e32 v158, v142
	v_permlane32_swap_b32_e32 v157, v141
	v_permlane32_swap_b32_e32 v156, v149
	v_permlane32_swap_b32_e32 v147, v148
	s_nop 1
	v_lshlrev_b32_e32 v236, 6, v78
	v_add_u32_e32 v237, 0x1000, v236
	global_load_dwordx4 v[172:175], v236, s[16:17] offset:0
	global_load_dwordx4 v[204:207], v236, s[18:19] offset:0
	global_load_dwordx4 v[176:179], v236, s[16:17] offset:16
	global_load_dwordx4 v[208:211], v236, s[18:19] offset:16
	global_load_dwordx4 v[180:183], v236, s[16:17] offset:32
	global_load_dwordx4 v[212:215], v236, s[18:19] offset:32
	global_load_dwordx4 v[184:187], v236, s[16:17] offset:48
	global_load_dwordx4 v[216:219], v236, s[18:19] offset:48
	global_load_dwordx4 v[188:191], v237, s[16:17] offset:0
	global_load_dwordx4 v[220:223], v237, s[18:19] offset:0
	global_load_dwordx4 v[192:195], v237, s[16:17] offset:16
	global_load_dwordx4 v[224:227], v237, s[18:19] offset:16
	global_load_dwordx4 v[196:199], v237, s[16:17] offset:32
	global_load_dwordx4 v[228:231], v237, s[18:19] offset:32
	global_load_dwordx4 v[200:203], v237, s[16:17] offset:48
	global_load_dwordx4 v[232:235], v237, s[18:19] offset:48
	s_lshl_b32 s0, s10, 2
	s_waitcnt vmcnt(11)
	v_mov_b32_e32 v0, v78
	s_or_b32 s10, s0, s22
	s_waitcnt vmcnt(0) lgkmcnt(0)
	s_ashr_i32 s11, s10, 31
	s_waitcnt vmcnt(2)
	v_lshlrev_b32_e32 v42, 4, v0
	v_ashrrev_i32_e32 v43, 31, v42
	s_lshl_b64 s[0:1], s[10:11], 11
	v_lshl_add_u64 v[0:1], s[0:1], 0, v[42:43]
	v_lshlrev_b64 v[0:1], 1, v[0:1]
	v_lshl_add_u64 v[28:29], s[70:71], 0, v[0:1]
	global_load_dwordx4 v[4:7], v[28:29], off offset:2064
	v_lshl_add_u64 v[24:25], s[2:3], 0, v[0:1]
	global_load_dwordx4 v[0:3], v[24:25], off offset:2064
	global_load_dwordx4 v[8:11], v[28:29], off
	global_load_dwordx4 v[12:15], v[24:25], off
	global_load_dwordx4 v[16:19], v[28:29], off offset:16
	global_load_dwordx4 v[20:23], v[24:25], off offset:16
	s_nop 0
	global_load_dwordx4 v[24:27], v[24:25], off offset:2048
	s_nop 0
	global_load_dwordx4 v[28:31], v[28:29], off offset:2048
	v_cvt_f32_f16_sdwa v35, v139 dst_sel:DWORD dst_unused:UNUSED_PAD src0_sel:WORD_1
	v_cvt_f32_f16_e32 v34, v139
	v_cvt_f32_f16_sdwa v41, v136 dst_sel:DWORD dst_unused:UNUSED_PAD src0_sel:WORD_1
	v_cvt_f32_f16_e32 v40, v136
	v_cvt_f32_f16_sdwa v37, v138 dst_sel:DWORD dst_unused:UNUSED_PAD src0_sel:WORD_1
	v_cvt_f32_f16_e32 v36, v138
	s_waitcnt vmcnt(9)
	v_cvt_f32_f16_sdwa v45, v135 dst_sel:DWORD dst_unused:UNUSED_PAD src0_sel:WORD_1
	v_cvt_f32_f16_e32 v44, v135
	v_cvt_f32_f16_sdwa v47, v134 dst_sel:DWORD dst_unused:UNUSED_PAD src0_sel:WORD_1
	v_cvt_f32_f16_e32 v46, v134
	v_cvt_f32_f16_sdwa v49, v133 dst_sel:DWORD dst_unused:UNUSED_PAD src0_sel:WORD_1
	v_cvt_f32_f16_e32 v48, v133
	v_cvt_f32_f16_sdwa v51, v132 dst_sel:DWORD dst_unused:UNUSED_PAD src0_sel:WORD_1
	v_cvt_f32_f16_e32 v50, v132
	v_cvt_f32_f16_sdwa v39, v137 dst_sel:DWORD dst_unused:UNUSED_PAD src0_sel:WORD_1
	v_cvt_f32_f16_e32 v38, v137
	v_cvt_f32_f16_sdwa v33, v140 dst_sel:DWORD dst_unused:UNUSED_PAD src0_sel:WORD_1
	v_cvt_f32_f16_e32 v32, v140
	s_lshl_b64 s[14:15], s[10:11], 13
	s_waitcnt vmcnt(6)
	v_and_b32_e32 v55, 0xffff0000, v2
	v_lshlrev_b32_e32 v54, 16, v2
	v_and_b32_e32 v53, 0xffff0000, v6
	v_lshlrev_b32_e32 v52, 16, v6
	s_waitcnt vmcnt(5)
	v_lshlrev_b32_e32 v104, 16, v8
	v_and_b32_e32 v105, 0xffff0000, v8
	s_waitcnt vmcnt(4)
	v_lshlrev_b32_e32 v106, 16, v12
	v_and_b32_e32 v107, 0xffff0000, v12
	v_and_b32_e32 v109, 0xffff0000, v7
	v_lshlrev_b32_e32 v108, 16, v7
	v_and_b32_e32 v7, 0xffff0000, v3
	v_lshlrev_b32_e32 v6, 16, v3
	v_lshlrev_b32_e32 v2, 16, v10
	v_and_b32_e32 v3, 0xffff0000, v10
	v_lshlrev_b32_e32 v110, 16, v14
	v_and_b32_e32 v111, 0xffff0000, v14
	v_lshlrev_b32_e32 v10, 16, v11
	v_and_b32_e32 v11, 0xffff0000, v11
	v_lshlrev_b32_e32 v14, 16, v15
	v_and_b32_e32 v15, 0xffff0000, v15
	s_waitcnt vmcnt(3)
	v_lshlrev_b32_e32 v132, 16, v16
	v_and_b32_e32 v133, 0xffff0000, v16
	s_waitcnt vmcnt(2)
	v_lshlrev_b32_e32 v134, 16, v20
	v_and_b32_e32 v135, 0xffff0000, v20
	v_lshlrev_b32_e32 v16, 16, v17
	v_and_b32_e32 v17, 0xffff0000, v17
	v_lshlrev_b32_e32 v20, 16, v21
	v_and_b32_e32 v21, 0xffff0000, v21
	v_pk_fma_f32 v[52:53], v[52:53], s[6:7], v[54:55] op_sel_hi:[1,0,1]
	v_pk_fma_f32 v[54:55], v[104:105], s[6:7], v[106:107] op_sel_hi:[1,0,1]
	v_lshlrev_b32_e32 v8, 16, v9
	v_and_b32_e32 v9, 0xffff0000, v9
	v_lshlrev_b32_e32 v12, 16, v13
	v_and_b32_e32 v13, 0xffff0000, v13
	v_pk_fma_f32 v[2:3], v[2:3], s[6:7], v[110:111] op_sel_hi:[1,0,1]
	v_pk_fma_f32 v[10:11], v[10:11], s[6:7], v[14:15] op_sel_hi:[1,0,1]
	v_pk_fma_f32 v[14:15], v[16:17], s[6:7], v[20:21] op_sel_hi:[1,0,1]
	v_pk_add_f32 v[20:21], v[54:55], v[34:35]
	v_pk_fma_f32 v[8:9], v[8:9], s[6:7], v[12:13] op_sel_hi:[1,0,1]
	v_pk_add_f32 v[40:41], v[2:3], v[40:41]
	v_add_f32_e32 v2, 0, v20
	v_pk_add_f32 v[8:9], v[8:9], v[36:37]
	v_add_f32_e32 v2, v21, v2
	v_add_f32_e32 v2, v8, v2
	v_add_f32_e32 v2, v9, v2
	v_add_f32_e32 v2, v40, v2
	v_pk_add_f32 v[10:11], v[10:11], v[44:45]
	v_add_f32_e32 v2, v41, v2
	v_pk_fma_f32 v[12:13], v[132:133], s[6:7], v[134:135] op_sel_hi:[1,0,1]
	v_add_f32_e32 v2, v10, v2
	v_pk_add_f32 v[12:13], v[12:13], v[46:47]
	v_add_f32_e32 v2, v11, v2
	v_add_f32_e32 v2, v12, v2
	v_pk_add_f32 v[14:15], v[14:15], v[48:49]
	v_add_f32_e32 v2, v13, v2
	v_lshlrev_b32_e32 v136, 16, v18
	v_and_b32_e32 v137, 0xffff0000, v18
	v_lshlrev_b32_e32 v138, 16, v22
	v_pk_fma_f32 v[6:7], v[108:109], s[6:7], v[6:7] op_sel_hi:[1,0,1]
	v_add_f32_e32 v2, v14, v2
	v_and_b32_e32 v139, 0xffff0000, v22
	v_pk_add_f32 v[38:39], v[6:7], v[38:39]
	v_add_f32_e32 v6, v15, v2
	v_pk_fma_f32 v[2:3], v[136:137], s[6:7], v[138:139] op_sel_hi:[1,0,1]
	v_and_b32_e32 v7, 0xffff0000, v19
	v_pk_add_f32 v[44:45], v[2:3], v[50:51]
	v_cvt_f32_f16_sdwa v3, v131 dst_sel:DWORD dst_unused:UNUSED_PAD src0_sel:WORD_1
	v_add_f32_e32 v2, v44, v6
	v_add_f32_e32 v22, v45, v2
	v_cvt_f32_f16_e32 v2, v131
	v_lshlrev_b32_e32 v6, 16, v19
	v_lshlrev_b32_e32 v18, 16, v23
	v_and_b32_e32 v19, 0xffff0000, v23
	v_pk_fma_f32 v[6:7], v[6:7], s[6:7], v[18:19] op_sel_hi:[1,0,1]
	v_pk_add_f32 v[16:17], v[52:53], v[32:33]
	v_pk_add_f32 v[18:19], v[6:7], v[2:3]
	v_cvt_f32_f16_sdwa v3, v130 dst_sel:DWORD dst_unused:UNUSED_PAD src0_sel:WORD_1
	v_add_f32_e32 v2, v18, v22
	v_add_f32_e32 v32, v19, v2
	v_cvt_f32_f16_e32 v2, v130
	s_waitcnt vmcnt(0)
	v_lshlrev_b32_e32 v6, 16, v28
	v_and_b32_e32 v7, 0xffff0000, v28
	v_lshlrev_b32_e32 v22, 16, v24
	v_and_b32_e32 v23, 0xffff0000, v24
	v_pk_fma_f32 v[6:7], v[6:7], s[6:7], v[22:23] op_sel_hi:[1,0,1]
	v_lshlrev_b32_e32 v24, 16, v25
	v_pk_add_f32 v[22:23], v[6:7], v[2:3]
	v_cvt_f32_f16_sdwa v3, v129 dst_sel:DWORD dst_unused:UNUSED_PAD src0_sel:WORD_1
	v_add_f32_e32 v2, v22, v32
	v_add_f32_e32 v28, v23, v2
	v_cvt_f32_f16_e32 v2, v129
	v_lshlrev_b32_e32 v6, 16, v29
	v_and_b32_e32 v7, 0xffff0000, v29
	v_and_b32_e32 v25, 0xffff0000, v25
	v_pk_fma_f32 v[6:7], v[6:7], s[6:7], v[24:25] op_sel_hi:[1,0,1]
	v_and_b32_e32 v29, 0xffff0000, v26
	v_pk_add_f32 v[24:25], v[6:7], v[2:3]
	v_cvt_f32_f16_sdwa v3, v128 dst_sel:DWORD dst_unused:UNUSED_PAD src0_sel:WORD_1
	v_add_f32_e32 v2, v24, v28
	v_add_f32_e32 v32, v25, v2
	v_cvt_f32_f16_e32 v2, v128
	v_lshlrev_b32_e32 v6, 16, v30
	v_and_b32_e32 v7, 0xffff0000, v30
	v_lshlrev_b32_e32 v28, 16, v26
	v_pk_fma_f32 v[6:7], v[6:7], s[6:7], v[28:29] op_sel_hi:[1,0,1]
	v_lshlrev_b32_e32 v26, 16, v27
	v_pk_add_f32 v[28:29], v[6:7], v[2:3]
	v_cvt_f32_f16_sdwa v3, v127 dst_sel:DWORD dst_unused:UNUSED_PAD src0_sel:WORD_1
	v_add_f32_e32 v2, v28, v32
	v_add_f32_e32 v30, v29, v2
	v_cvt_f32_f16_e32 v2, v127
	v_lshlrev_b32_e32 v6, 16, v31
	v_and_b32_e32 v7, 0xffff0000, v31
	v_and_b32_e32 v27, 0xffff0000, v27
	v_pk_fma_f32 v[6:7], v[6:7], s[6:7], v[26:27] op_sel_hi:[1,0,1]
	v_and_b32_e32 v31, 0xffff0000, v0
	v_pk_add_f32 v[26:27], v[6:7], v[2:3]
	v_cvt_f32_f16_sdwa v3, v126 dst_sel:DWORD dst_unused:UNUSED_PAD src0_sel:WORD_1
	v_add_f32_e32 v2, v26, v30
	v_add_f32_e32 v32, v27, v2
	v_cvt_f32_f16_e32 v2, v126
	v_lshlrev_b32_e32 v6, 16, v4
	v_and_b32_e32 v7, 0xffff0000, v4
	v_lshlrev_b32_e32 v30, 16, v0
	v_pk_fma_f32 v[6:7], v[6:7], s[6:7], v[30:31] op_sel_hi:[1,0,1]
	v_lshlrev_b32_e32 v4, 16, v5
	v_pk_add_f32 v[30:31], v[6:7], v[2:3]
	v_cvt_f32_f16_sdwa v3, v114 dst_sel:DWORD dst_unused:UNUSED_PAD src0_sel:WORD_1
	v_cvt_f32_f16_e32 v2, v114
	v_add_f32_e32 v0, v30, v32
	v_add_f32_e32 v6, v31, v0
	v_and_b32_e32 v5, 0xffff0000, v5
	v_lshlrev_b32_e32 v0, 16, v1
	v_and_b32_e32 v1, 0xffff0000, v1
	v_pk_fma_f32 v[0:1], v[4:5], s[6:7], v[0:1] op_sel_hi:[1,0,1]
	v_lshlrev_b64 v[36:37], 2, v[42:43]
	v_pk_add_f32 v[46:47], v[0:1], v[2:3]
	v_lshl_add_u64 v[32:33], s[16:17], 0, v[36:37]
	v_add_f32_e32 v0, v46, v6
	v_add_f32_e32 v0, v47, v0
	v_add_f32_e32 v0, v16, v0
	v_add_f32_e32 v0, v17, v0
	v_add_f32_e32 v0, v38, v0
	v_add_f32_e32 v0, v39, v0
	ds_bpermute_b32 v1, v79, v0
	v_lshl_add_u64 v[34:35], s[18:19], 0, v[36:37]
	s_waitcnt lgkmcnt(0)
	v_add_f32_e32 v0, v0, v1
	ds_bpermute_b32 v1, v80, v0
	s_waitcnt lgkmcnt(0)
	v_add_f32_e32 v0, v0, v1
	ds_bpermute_b32 v1, v81, v0
	s_waitcnt lgkmcnt(0)
	v_add_f32_e32 v0, v0, v1
	ds_bpermute_b32 v1, v82, v0
	s_waitcnt lgkmcnt(0)
	v_add_f32_e32 v0, v0, v1
	ds_bpermute_b32 v1, v83, v0
	s_waitcnt lgkmcnt(0)
	v_add_f32_e32 v48, v0, v1
	ds_bpermute_b32 v49, v84, v48
	s_waitcnt lgkmcnt(0)
	v_add_f32_e32 v48, v48, v49
	v_mul_f32_e32 v48, 0x3a000000, v48
	v_pk_add_f32 v[20:21], v[20:21], v[48:49] op_sel_hi:[1,0] neg_lo:[0,1] neg_hi:[0,1]
	v_pk_add_f32 v[8:9], v[8:9], v[48:49] op_sel_hi:[1,0] neg_lo:[0,1] neg_hi:[0,1]
	v_pk_mul_f32 v[50:51], v[20:21], v[20:21]
	v_pk_mul_f32 v[52:53], v[8:9], v[8:9]
	v_add_f32_e32 v50, v50, v51
	v_pk_add_f32 v[40:41], v[40:41], v[48:49] op_sel_hi:[1,0] neg_lo:[0,1] neg_hi:[0,1]
	v_add_f32_e32 v50, v52, v50
	v_pk_mul_f32 v[54:55], v[40:41], v[40:41]
	v_add_f32_e32 v50, v53, v50
	v_pk_add_f32 v[10:11], v[10:11], v[48:49] op_sel_hi:[1,0] neg_lo:[0,1] neg_hi:[0,1]
	v_add_f32_e32 v50, v54, v50
	v_pk_mul_f32 v[104:105], v[10:11], v[10:11]
	v_add_f32_e32 v50, v55, v50
	v_pk_add_f32 v[12:13], v[12:13], v[48:49] op_sel_hi:[1,0] neg_lo:[0,1] neg_hi:[0,1]
	v_add_f32_e32 v50, v104, v50
	v_pk_mul_f32 v[106:107], v[12:13], v[12:13]
	v_add_f32_e32 v50, v105, v50
	v_pk_add_f32 v[14:15], v[14:15], v[48:49] op_sel_hi:[1,0] neg_lo:[0,1] neg_hi:[0,1]
	v_add_f32_e32 v50, v106, v50
	v_pk_mul_f32 v[108:109], v[14:15], v[14:15]
	v_add_f32_e32 v50, v107, v50
	v_pk_add_f32 v[44:45], v[44:45], v[48:49] op_sel_hi:[1,0] neg_lo:[0,1] neg_hi:[0,1]
	v_add_f32_e32 v50, v108, v50
	v_pk_mul_f32 v[110:111], v[44:45], v[44:45]
	v_add_f32_e32 v50, v109, v50
	v_pk_add_f32 v[18:19], v[18:19], v[48:49] op_sel_hi:[1,0] neg_lo:[0,1] neg_hi:[0,1]
	v_add_f32_e32 v50, v110, v50
	v_pk_mul_f32 v[114:115], v[18:19], v[18:19]
	v_add_f32_e32 v50, v111, v50
	v_pk_add_f32 v[22:23], v[22:23], v[48:49] op_sel_hi:[1,0] neg_lo:[0,1] neg_hi:[0,1]
	v_add_f32_e32 v50, v114, v50
	v_pk_mul_f32 v[126:127], v[22:23], v[22:23]
	v_add_f32_e32 v50, v115, v50
	v_pk_add_f32 v[24:25], v[24:25], v[48:49] op_sel_hi:[1,0] neg_lo:[0,1] neg_hi:[0,1]
	v_add_f32_e32 v50, v126, v50
	v_pk_mul_f32 v[128:129], v[24:25], v[24:25]
	v_add_f32_e32 v50, v127, v50
	v_pk_add_f32 v[28:29], v[28:29], v[48:49] op_sel_hi:[1,0] neg_lo:[0,1] neg_hi:[0,1]
	v_add_f32_e32 v50, v128, v50
	v_pk_mul_f32 v[130:131], v[28:29], v[28:29]
	v_add_f32_e32 v50, v129, v50
	v_pk_add_f32 v[26:27], v[26:27], v[48:49] op_sel_hi:[1,0] neg_lo:[0,1] neg_hi:[0,1]
	v_add_f32_e32 v50, v130, v50
	v_pk_mul_f32 v[132:133], v[26:27], v[26:27]
	v_add_f32_e32 v50, v131, v50
	v_pk_add_f32 v[30:31], v[30:31], v[48:49] op_sel_hi:[1,0] neg_lo:[0,1] neg_hi:[0,1]
	v_add_f32_e32 v50, v132, v50
	v_pk_mul_f32 v[134:135], v[30:31], v[30:31]
	v_add_f32_e32 v50, v133, v50
	v_pk_add_f32 v[46:47], v[46:47], v[48:49] op_sel_hi:[1,0] neg_lo:[0,1] neg_hi:[0,1]
	v_add_f32_e32 v50, v134, v50
	v_pk_mul_f32 v[136:137], v[46:47], v[46:47]
	v_add_f32_e32 v50, v135, v50
	v_pk_add_f32 v[16:17], v[16:17], v[48:49] op_sel_hi:[1,0] neg_lo:[0,1] neg_hi:[0,1]
	v_add_f32_e32 v50, v136, v50
	v_pk_add_f32 v[138:139], v[38:39], v[48:49] op_sel_hi:[1,0] neg_lo:[0,1] neg_hi:[0,1]
	v_pk_mul_f32 v[48:49], v[16:17], v[16:17]
	v_add_f32_e32 v50, v137, v50
	v_add_f32_e32 v48, v48, v50
	v_pk_mul_f32 v[38:39], v[138:139], v[138:139]
	v_add_f32_e32 v48, v49, v48
	v_add_f32_e32 v38, v38, v48
	v_add_f32_e32 v38, v39, v38
	ds_bpermute_b32 v39, v79, v38
	v_cvt_f32_f16_sdwa v105, v119 dst_sel:DWORD dst_unused:UNUSED_PAD src0_sel:WORD_1
	v_cvt_f32_f16_e32 v104, v119
	v_cvt_f32_f16_sdwa v107, v118 dst_sel:DWORD dst_unused:UNUSED_PAD src0_sel:WORD_1
	v_cvt_f32_f16_e32 v106, v118
	s_waitcnt lgkmcnt(0)
	v_add_f32_e32 v38, v38, v39
	ds_bpermute_b32 v39, v80, v38
	v_cvt_f32_f16_sdwa v119, v65 dst_sel:DWORD dst_unused:UNUSED_PAD src0_sel:WORD_1
	v_cvt_f32_f16_e32 v118, v65
	v_cvt_f32_f16_sdwa v65, v64 dst_sel:DWORD dst_unused:UNUSED_PAD src0_sel:WORD_1
	v_cvt_f32_f16_e32 v64, v64
	s_waitcnt lgkmcnt(0)
	v_add_f32_e32 v38, v38, v39
	ds_bpermute_b32 v39, v81, v38
	v_cvt_f32_f16_sdwa v55, v120 dst_sel:DWORD dst_unused:UNUSED_PAD src0_sel:WORD_1
	v_cvt_f32_f16_e32 v54, v120
	v_cvt_f32_f16_sdwa v109, v117 dst_sel:DWORD dst_unused:UNUSED_PAD src0_sel:WORD_1
	v_cvt_f32_f16_e32 v108, v117
	s_waitcnt lgkmcnt(0)
	v_add_f32_e32 v38, v38, v39
	ds_bpermute_b32 v39, v82, v38
	v_cvt_f32_f16_sdwa v111, v116 dst_sel:DWORD dst_unused:UNUSED_PAD src0_sel:WORD_1
	v_cvt_f32_f16_e32 v110, v116
	v_cvt_f32_f16_sdwa v115, v113 dst_sel:DWORD dst_unused:UNUSED_PAD src0_sel:WORD_1
	v_cvt_f32_f16_e32 v114, v113
	s_waitcnt lgkmcnt(0)
	v_add_f32_e32 v38, v38, v39
	ds_bpermute_b32 v39, v83, v38
	v_cvt_f32_f16_sdwa v113, v112 dst_sel:DWORD dst_unused:UNUSED_PAD src0_sel:WORD_1
	v_cvt_f32_f16_e32 v112, v112
	v_cvt_f32_f16_sdwa v117, v67 dst_sel:DWORD dst_unused:UNUSED_PAD src0_sel:WORD_1
	v_cvt_f32_f16_e32 v116, v67
	s_waitcnt lgkmcnt(0)
	v_add_f32_e32 v38, v38, v39
	ds_bpermute_b32 v39, v84, v38
	v_cvt_f32_f16_sdwa v67, v66 dst_sel:DWORD dst_unused:UNUSED_PAD src0_sel:WORD_1
	v_cvt_f32_f16_e32 v66, v66
	s_waitcnt lgkmcnt(0)
	v_add_f32_e32 v38, v38, v39
	v_fmamk_f32 v38, v38, 0x3a000000, v101
	v_mul_f32_e32 v39, 0x4f800000, v38
	v_cmp_gt_f32_e32 vcc, s7, v38
	s_nop 1
	v_cndmask_b32_e32 v38, v38, v39, vcc
	v_sqrt_f32_e32 v39, v38
	s_nop 0
	v_add_u32_e32 v48, -1, v39
	v_fma_f32 v49, -v48, v39, v38
	v_cmp_ge_f32_e64 s[0:1], 0, v49
	v_add_u32_e32 v49, 1, v39
	s_nop 0
	v_cndmask_b32_e64 v48, v39, v48, s[0:1]
	v_fma_f32 v39, -v49, v39, v38
	v_cmp_lt_f32_e64 s[0:1], 0, v39
	s_nop 1
	v_cndmask_b32_e64 v39, v48, v49, s[0:1]
	v_mul_f32_e32 v48, 0x37800000, v39
	v_cndmask_b32_e32 v39, v39, v48, vcc
	v_cmp_class_f32_e32 vcc, v38, v102
	s_nop 1
	v_cndmask_b32_e32 v38, v39, v38, vcc
	v_div_scale_f32 v39, s[0:1], v38, v38, 1.0
	v_rcp_f32_e32 v50, v39
	s_add_u32 s0, s20, s14
	s_addc_u32 s1, s21, s15
	v_lshl_add_u64 v[48:49], s[0:1], 0, v[36:37]
	v_fma_f32 v51, -v39, v50, 1.0
	v_fmac_f32_e32 v50, v51, v50
	v_div_scale_f32 v51, vcc, 1.0, v38, 1.0
	v_mul_f32_e32 v52, v51, v50
	v_fma_f32 v53, -v39, v52, v51
	v_fmac_f32_e32 v52, v53, v50
	v_fma_f32 v39, -v39, v52, v51
	v_div_fmas_f32 v39, v39, v50, v52
	v_div_fixup_f32 v50, v39, v38, 1.0
	v_pk_mul_f32 v[20:21], v[20:21], v[50:51] op_sel_hi:[1,0]
	v_pk_mul_f32 v[8:9], v[8:9], v[50:51] op_sel_hi:[1,0]
	v_pk_fma_f32 v[0:1], v[172:173], v[20:21], v[204:205]
	v_pk_fma_f32 v[2:3], v[174:175], v[8:9], v[206:207]
	global_store_dwordx4 v[48:49], v[0:3], off
	s_nop 1
	s_nop 0
	v_pk_mul_f32 v[8:9], v[10:11], v[50:51] op_sel_hi:[1,0]
	v_pk_mul_f32 v[10:11], v[40:41], v[50:51] op_sel_hi:[1,0]
	v_add_co_u32_e32 v38, vcc, s12, v32
	s_or_b32 s0, s10, 1
	s_nop 0
	v_addc_co_u32_e32 v39, vcc, 0, v33, vcc
	v_add_co_u32_e32 v40, vcc, s12, v34
	s_ashr_i32 s1, s0, 31
	s_nop 0
	v_addc_co_u32_e32 v41, vcc, 0, v35, vcc
	s_lshl_b64 s[14:15], s[0:1], 11
	v_cvt_f32_f16_sdwa v53, v121 dst_sel:DWORD dst_unused:UNUSED_PAD src0_sel:WORD_1
	v_cvt_f32_f16_e32 v52, v121
	s_lshl_b64 s[0:1], s[0:1], 13
	v_pk_fma_f32 v[0:1], v[176:177], v[10:11], v[208:209]
	v_pk_fma_f32 v[2:3], v[178:179], v[8:9], v[210:211]
	global_store_dwordx4 v[48:49], v[0:3], off offset:16
	s_nop 1
	s_nop 0
	v_pk_mul_f32 v[8:9], v[14:15], v[50:51] op_sel_hi:[1,0]
	v_pk_mul_f32 v[10:11], v[12:13], v[50:51] op_sel_hi:[1,0]
	v_pk_mul_f32 v[12:13], v[22:23], v[50:51] op_sel_hi:[1,0]
	v_pk_mul_f32 v[14:15], v[16:17], v[50:51] op_sel_hi:[1,0]
	v_pk_fma_f32 v[0:1], v[180:181], v[10:11], v[212:213]
	v_pk_fma_f32 v[2:3], v[182:183], v[8:9], v[214:215]
	global_store_dwordx4 v[48:49], v[0:3], off offset:32
	s_nop 1
	s_nop 0
	v_pk_mul_f32 v[8:9], v[18:19], v[50:51] op_sel_hi:[1,0]
	v_pk_mul_f32 v[10:11], v[44:45], v[50:51] op_sel_hi:[1,0]
	v_pk_fma_f32 v[2:3], v[186:187], v[8:9], v[218:219]
	v_pk_fma_f32 v[0:1], v[184:185], v[10:11], v[216:217]
	global_store_dwordx4 v[48:49], v[0:3], off offset:48
	s_nop 1
	s_nop 0
	v_add_co_u32_e32 v8, vcc, s12, v48
	v_pk_mul_f32 v[10:11], v[24:25], v[50:51] op_sel_hi:[1,0]
	s_nop 0
	v_addc_co_u32_e32 v9, vcc, 0, v49, vcc
	v_cvt_f32_f16_sdwa v49, v123 dst_sel:DWORD dst_unused:UNUSED_PAD src0_sel:WORD_1
	v_cvt_f32_f16_e32 v48, v123
	v_pk_fma_f32 v[0:1], v[188:189], v[12:13], v[220:221]
	v_pk_fma_f32 v[2:3], v[190:191], v[10:11], v[222:223]
	global_store_dwordx4 v[8:9], v[0:3], off
	s_nop 1
	s_nop 0
	v_pk_mul_f32 v[10:11], v[26:27], v[50:51] op_sel_hi:[1,0]
	v_pk_mul_f32 v[12:13], v[28:29], v[50:51] op_sel_hi:[1,0]
	v_pk_fma_f32 v[2:3], v[194:195], v[10:11], v[226:227]
	v_pk_fma_f32 v[0:1], v[192:193], v[12:13], v[224:225]
	global_store_dwordx4 v[8:9], v[0:3], off offset:16
	s_nop 1
	s_nop 0
	v_pk_mul_f32 v[10:11], v[46:47], v[50:51] op_sel_hi:[1,0]
	v_pk_mul_f32 v[12:13], v[30:31], v[50:51] op_sel_hi:[1,0]
	v_pk_fma_f32 v[2:3], v[198:199], v[10:11], v[230:231]
	v_pk_fma_f32 v[0:1], v[196:197], v[12:13], v[228:229]
	global_store_dwordx4 v[8:9], v[0:3], off offset:32
	s_nop 1
	s_nop 0
	v_lshl_add_u64 v[10:11], s[14:15], 0, v[42:43]
	v_pk_mul_f32 v[12:13], v[138:139], v[50:51] op_sel_hi:[1,0]
	v_lshlrev_b64 v[10:11], 1, v[10:11]
	v_lshl_add_u64 v[44:45], s[70:71], 0, v[10:11]
	v_lshl_add_u64 v[46:47], s[2:3], 0, v[10:11]
	v_cvt_f32_f16_sdwa v51, v122 dst_sel:DWORD dst_unused:UNUSED_PAD src0_sel:WORD_1
	v_cvt_f32_f16_e32 v50, v122
	s_add_u32 s14, s20, s0
	s_addc_u32 s15, s21, s1
	v_pk_fma_f32 v[0:1], v[200:201], v[14:15], v[232:233]
	v_pk_fma_f32 v[2:3], v[202:203], v[12:13], v[234:235]
	global_store_dwordx4 v[8:9], v[0:3], off offset:48
	s_nop 1
	global_load_dwordx4 v[4:7], v[44:45], off offset:2064
	s_nop 0
	global_load_dwordx4 v[0:3], v[46:47], off offset:2064
	global_load_dwordx4 v[28:31], v[44:45], off
	global_load_dwordx4 v[24:27], v[46:47], off
	global_load_dwordx4 v[20:23], v[44:45], off offset:16
	global_load_dwordx4 v[16:19], v[46:47], off offset:16
	global_load_dwordx4 v[12:15], v[44:45], off offset:2048
	global_load_dwordx4 v[8:11], v[46:47], off offset:2048
	v_cvt_f32_f16_sdwa v45, v125 dst_sel:DWORD dst_unused:UNUSED_PAD src0_sel:WORD_1
	v_cvt_f32_f16_e32 v44, v125
	v_cvt_f32_f16_sdwa v47, v124 dst_sel:DWORD dst_unused:UNUSED_PAD src0_sel:WORD_1
	v_cvt_f32_f16_e32 v46, v124
	s_waitcnt vmcnt(6)
	v_and_b32_e32 v123, 0xffff0000, v2
	v_lshlrev_b32_e32 v122, 16, v2
	s_waitcnt vmcnt(5)
	v_lshlrev_b32_e32 v124, 16, v28
	v_and_b32_e32 v125, 0xffff0000, v28
	s_waitcnt vmcnt(4)
	v_lshlrev_b32_e32 v126, 16, v24
	v_and_b32_e32 v121, 0xffff0000, v6
	v_lshlrev_b32_e32 v120, 16, v6
	v_and_b32_e32 v127, 0xffff0000, v24
	v_and_b32_e32 v129, 0xffff0000, v7
	v_lshlrev_b32_e32 v128, 16, v7
	v_and_b32_e32 v7, 0xffff0000, v3
	v_lshlrev_b32_e32 v6, 16, v3
	v_lshlrev_b32_e32 v2, 16, v30
	v_and_b32_e32 v3, 0xffff0000, v30
	v_lshlrev_b32_e32 v130, 16, v26
	v_and_b32_e32 v131, 0xffff0000, v26
	v_lshlrev_b32_e32 v30, 16, v31
	v_and_b32_e32 v31, 0xffff0000, v31
	v_lshlrev_b32_e32 v26, 16, v27
	v_and_b32_e32 v27, 0xffff0000, v27
	v_lshlrev_b32_e32 v166, 16, v4
	v_and_b32_e32 v167, 0xffff0000, v4
	v_lshlrev_b32_e32 v168, 16, v0
	v_and_b32_e32 v169, 0xffff0000, v0
	v_lshlrev_b32_e32 v4, 16, v5
	v_and_b32_e32 v5, 0xffff0000, v5
	v_lshlrev_b32_e32 v0, 16, v1
	v_and_b32_e32 v1, 0xffff0000, v1
	v_pk_fma_f32 v[120:121], v[120:121], s[6:7], v[122:123] op_sel_hi:[1,0,1]
	v_pk_fma_f32 v[122:123], v[124:125], s[6:7], v[126:127] op_sel_hi:[1,0,1]
	v_lshlrev_b32_e32 v28, 16, v29
	v_and_b32_e32 v29, 0xffff0000, v29
	v_lshlrev_b32_e32 v24, 16, v25
	v_and_b32_e32 v25, 0xffff0000, v25
	v_pk_fma_f32 v[6:7], v[128:129], s[6:7], v[6:7] op_sel_hi:[1,0,1]
	v_pk_fma_f32 v[26:27], v[30:31], s[6:7], v[26:27] op_sel_hi:[1,0,1]
	v_pk_fma_f32 v[0:1], v[4:5], s[6:7], v[0:1] op_sel_hi:[1,0,1]
	v_pk_add_f32 v[30:31], v[120:121], v[44:45]
	v_pk_add_f32 v[44:45], v[122:123], v[46:47]
	v_pk_fma_f32 v[24:25], v[28:29], s[6:7], v[24:25] op_sel_hi:[1,0,1]
	v_pk_add_f32 v[46:47], v[6:7], v[50:51]
	v_pk_add_f32 v[50:51], v[0:1], v[64:65]
	v_add_f32_e32 v0, 0, v44
	v_pk_add_f32 v[24:25], v[24:25], v[48:49]
	v_add_f32_e32 v0, v45, v0
	v_pk_fma_f32 v[2:3], v[2:3], s[6:7], v[130:131] op_sel_hi:[1,0,1]
	v_add_f32_e32 v0, v24, v0
	v_pk_add_f32 v[48:49], v[2:3], v[52:53]
	v_add_f32_e32 v0, v25, v0
	v_add_f32_e32 v0, v48, v0
	s_waitcnt vmcnt(3)
	v_lshlrev_b32_e32 v132, 16, v20
	v_and_b32_e32 v133, 0xffff0000, v20
	s_waitcnt vmcnt(2)
	v_lshlrev_b32_e32 v134, 16, v16
	v_and_b32_e32 v135, 0xffff0000, v16
	v_pk_add_f32 v[26:27], v[26:27], v[54:55]
	v_add_f32_e32 v0, v49, v0
	v_pk_fma_f32 v[28:29], v[132:133], s[6:7], v[134:135] op_sel_hi:[1,0,1]
	v_add_f32_e32 v0, v26, v0
	v_lshlrev_b32_e32 v20, 16, v21
	v_and_b32_e32 v21, 0xffff0000, v21
	v_lshlrev_b32_e32 v16, 16, v17
	v_and_b32_e32 v17, 0xffff0000, v17
	v_pk_add_f32 v[28:29], v[28:29], v[104:105]
	v_add_f32_e32 v0, v27, v0
	v_pk_fma_f32 v[16:17], v[20:21], s[6:7], v[16:17] op_sel_hi:[1,0,1]
	v_add_f32_e32 v0, v28, v0
	v_lshlrev_b32_e32 v136, 16, v22
	v_and_b32_e32 v137, 0xffff0000, v22
	v_lshlrev_b32_e32 v138, 16, v18
	v_and_b32_e32 v139, 0xffff0000, v18
	v_pk_add_f32 v[16:17], v[16:17], v[106:107]
	v_add_f32_e32 v0, v29, v0
	v_pk_fma_f32 v[20:21], v[136:137], s[6:7], v[138:139] op_sel_hi:[1,0,1]
	v_add_f32_e32 v0, v16, v0
	v_lshlrev_b32_e32 v22, 16, v23
	v_and_b32_e32 v23, 0xffff0000, v23
	v_lshlrev_b32_e32 v18, 16, v19
	v_and_b32_e32 v19, 0xffff0000, v19
	v_pk_add_f32 v[20:21], v[20:21], v[108:109]
	v_add_f32_e32 v0, v17, v0
	v_pk_fma_f32 v[18:19], v[22:23], s[6:7], v[18:19] op_sel_hi:[1,0,1]
	v_add_f32_e32 v0, v20, v0
	s_waitcnt vmcnt(1)
	v_lshlrev_b32_e32 v150, 16, v12
	v_and_b32_e32 v151, 0xffff0000, v12
	s_waitcnt vmcnt(0)
	v_lshlrev_b32_e32 v152, 16, v8
	v_and_b32_e32 v153, 0xffff0000, v8
	v_pk_add_f32 v[18:19], v[18:19], v[110:111]
	v_add_f32_e32 v0, v21, v0
	v_pk_fma_f32 v[22:23], v[150:151], s[6:7], v[152:153] op_sel_hi:[1,0,1]
	v_add_f32_e32 v0, v18, v0
	v_lshlrev_b32_e32 v12, 16, v13
	v_and_b32_e32 v13, 0xffff0000, v13
	v_lshlrev_b32_e32 v8, 16, v9
	v_and_b32_e32 v9, 0xffff0000, v9
	v_pk_add_f32 v[22:23], v[22:23], v[114:115]
	v_add_f32_e32 v0, v19, v0
	v_pk_fma_f32 v[8:9], v[12:13], s[6:7], v[8:9] op_sel_hi:[1,0,1]
	v_add_f32_e32 v0, v22, v0
	v_lshlrev_b32_e32 v154, 16, v14
	v_and_b32_e32 v155, 0xffff0000, v14
	v_lshlrev_b32_e32 v164, 16, v10
	v_and_b32_e32 v165, 0xffff0000, v10
	v_pk_add_f32 v[8:9], v[8:9], v[112:113]
	v_add_f32_e32 v0, v23, v0
	v_pk_fma_f32 v[12:13], v[154:155], s[6:7], v[164:165] op_sel_hi:[1,0,1]
	v_add_f32_e32 v0, v8, v0
	v_lshlrev_b32_e32 v14, 16, v15
	v_and_b32_e32 v15, 0xffff0000, v15
	v_lshlrev_b32_e32 v10, 16, v11
	v_and_b32_e32 v11, 0xffff0000, v11
	v_pk_add_f32 v[12:13], v[12:13], v[116:117]
	v_add_f32_e32 v0, v9, v0
	v_pk_fma_f32 v[10:11], v[14:15], s[6:7], v[10:11] op_sel_hi:[1,0,1]
	v_add_f32_e32 v0, v12, v0
	v_pk_add_f32 v[10:11], v[10:11], v[66:67]
	v_add_f32_e32 v0, v13, v0
	v_pk_fma_f32 v[14:15], v[166:167], s[6:7], v[168:169] op_sel_hi:[1,0,1]
	v_add_f32_e32 v0, v10, v0
	v_pk_add_f32 v[14:15], v[14:15], v[118:119]
	v_add_f32_e32 v0, v11, v0
	v_add_f32_e32 v0, v14, v0
	v_add_f32_e32 v0, v15, v0
	v_add_f32_e32 v0, v50, v0
	v_add_f32_e32 v0, v51, v0
	v_add_f32_e32 v0, v30, v0
	v_add_f32_e32 v0, v31, v0
	v_add_f32_e32 v0, v46, v0
	v_add_f32_e32 v0, v47, v0
	ds_bpermute_b32 v1, v79, v0
	s_waitcnt lgkmcnt(0)
	v_add_f32_e32 v0, v0, v1
	ds_bpermute_b32 v1, v80, v0
	s_waitcnt lgkmcnt(0)
	v_add_f32_e32 v0, v0, v1
	ds_bpermute_b32 v1, v81, v0
	s_waitcnt lgkmcnt(0)
	v_add_f32_e32 v0, v0, v1
	ds_bpermute_b32 v1, v82, v0
	s_waitcnt lgkmcnt(0)
	v_add_f32_e32 v0, v0, v1
	ds_bpermute_b32 v1, v83, v0
	s_waitcnt lgkmcnt(0)
	v_add_f32_e32 v52, v0, v1
	ds_bpermute_b32 v53, v84, v52
	s_waitcnt lgkmcnt(0)
	v_add_f32_e32 v52, v52, v53
	v_mul_f32_e32 v52, 0x3a000000, v52
	v_pk_add_f32 v[44:45], v[44:45], v[52:53] op_sel_hi:[1,0] neg_lo:[0,1] neg_hi:[0,1]
	v_pk_add_f32 v[24:25], v[24:25], v[52:53] op_sel_hi:[1,0] neg_lo:[0,1] neg_hi:[0,1]
	v_pk_add_f32 v[48:49], v[48:49], v[52:53] op_sel_hi:[1,0] neg_lo:[0,1] neg_hi:[0,1]
	v_pk_add_f32 v[26:27], v[26:27], v[52:53] op_sel_hi:[1,0] neg_lo:[0,1] neg_hi:[0,1]
	v_pk_add_f32 v[28:29], v[28:29], v[52:53] op_sel_hi:[1,0] neg_lo:[0,1] neg_hi:[0,1]
	v_pk_add_f32 v[16:17], v[16:17], v[52:53] op_sel_hi:[1,0] neg_lo:[0,1] neg_hi:[0,1]
	v_pk_add_f32 v[20:21], v[20:21], v[52:53] op_sel_hi:[1,0] neg_lo:[0,1] neg_hi:[0,1]
	v_pk_add_f32 v[18:19], v[18:19], v[52:53] op_sel_hi:[1,0] neg_lo:[0,1] neg_hi:[0,1]
	v_pk_add_f32 v[22:23], v[22:23], v[52:53] op_sel_hi:[1,0] neg_lo:[0,1] neg_hi:[0,1]
	v_pk_add_f32 v[8:9], v[8:9], v[52:53] op_sel_hi:[1,0] neg_lo:[0,1] neg_hi:[0,1]
	v_pk_add_f32 v[12:13], v[12:13], v[52:53] op_sel_hi:[1,0] neg_lo:[0,1] neg_hi:[0,1]
	v_pk_add_f32 v[10:11], v[10:11], v[52:53] op_sel_hi:[1,0] neg_lo:[0,1] neg_hi:[0,1]
	v_pk_add_f32 v[14:15], v[14:15], v[52:53] op_sel_hi:[1,0] neg_lo:[0,1] neg_hi:[0,1]
	v_pk_add_f32 v[50:51], v[50:51], v[52:53] op_sel_hi:[1,0] neg_lo:[0,1] neg_hi:[0,1]
	v_pk_add_f32 v[46:47], v[46:47], v[52:53] op_sel_hi:[1,0] neg_lo:[0,1] neg_hi:[0,1]
	v_pk_add_f32 v[30:31], v[30:31], v[52:53] op_sel_hi:[1,0] neg_lo:[0,1] neg_hi:[0,1]
	v_pk_mul_f32 v[52:53], v[44:45], v[44:45]
	v_pk_mul_f32 v[54:55], v[24:25], v[24:25]
	v_add_f32_e32 v52, v52, v53
	v_add_f32_e32 v52, v54, v52
	v_pk_mul_f32 v[64:65], v[48:49], v[48:49]
	v_add_f32_e32 v52, v55, v52
	v_add_f32_e32 v52, v64, v52
	v_pk_mul_f32 v[66:67], v[26:27], v[26:27]
	v_add_f32_e32 v52, v65, v52
	v_add_f32_e32 v52, v66, v52
	v_pk_mul_f32 v[104:105], v[28:29], v[28:29]
	v_add_f32_e32 v52, v67, v52
	v_add_f32_e32 v52, v104, v52
	v_pk_mul_f32 v[106:107], v[16:17], v[16:17]
	v_add_f32_e32 v52, v105, v52
	v_add_f32_e32 v52, v106, v52
	v_pk_mul_f32 v[108:109], v[20:21], v[20:21]
	v_add_f32_e32 v52, v107, v52
	v_add_f32_e32 v52, v108, v52
	v_pk_mul_f32 v[110:111], v[18:19], v[18:19]
	v_add_f32_e32 v52, v109, v52
	v_add_f32_e32 v52, v110, v52
	v_pk_mul_f32 v[112:113], v[22:23], v[22:23]
	v_add_f32_e32 v52, v111, v52
	v_add_f32_e32 v52, v112, v52
	v_pk_mul_f32 v[114:115], v[8:9], v[8:9]
	v_add_f32_e32 v52, v113, v52
	v_add_f32_e32 v52, v114, v52
	v_pk_mul_f32 v[116:117], v[12:13], v[12:13]
	v_add_f32_e32 v52, v115, v52
	v_add_f32_e32 v52, v116, v52
	v_pk_mul_f32 v[118:119], v[10:11], v[10:11]
	v_add_f32_e32 v52, v117, v52
	v_add_f32_e32 v52, v118, v52
	v_pk_mul_f32 v[120:121], v[14:15], v[14:15]
	v_add_f32_e32 v52, v119, v52
	v_add_f32_e32 v52, v120, v52
	v_pk_mul_f32 v[122:123], v[50:51], v[50:51]
	v_add_f32_e32 v52, v121, v52
	v_add_f32_e32 v52, v122, v52
	v_pk_mul_f32 v[126:127], v[30:31], v[30:31]
	v_add_f32_e32 v52, v123, v52
	v_add_f32_e32 v52, v126, v52
	v_pk_mul_f32 v[124:125], v[46:47], v[46:47]
	v_add_f32_e32 v52, v127, v52
	v_add_f32_e32 v52, v124, v52
	v_add_f32_e32 v52, v125, v52
	ds_bpermute_b32 v53, v79, v52
	s_waitcnt lgkmcnt(0)
	v_add_f32_e32 v52, v52, v53
	ds_bpermute_b32 v53, v80, v52
	s_waitcnt lgkmcnt(0)
	v_add_f32_e32 v52, v52, v53
	ds_bpermute_b32 v53, v81, v52
	s_waitcnt lgkmcnt(0)
	v_add_f32_e32 v52, v52, v53
	ds_bpermute_b32 v53, v82, v52
	s_waitcnt lgkmcnt(0)
	v_add_f32_e32 v52, v52, v53
	ds_bpermute_b32 v53, v83, v52
	s_waitcnt lgkmcnt(0)
	v_add_f32_e32 v52, v52, v53
	ds_bpermute_b32 v53, v84, v52
	s_waitcnt lgkmcnt(0)
	v_add_f32_e32 v52, v52, v53
	v_fmamk_f32 v52, v52, 0x3a000000, v101
	v_mul_f32_e32 v53, 0x4f800000, v52
	v_cmp_gt_f32_e32 vcc, s7, v52
	s_nop 1
	v_cndmask_b32_e32 v52, v52, v53, vcc
	v_sqrt_f32_e32 v53, v52
	s_nop 0
	v_add_u32_e32 v54, -1, v53
	v_add_u32_e32 v55, 1, v53
	v_fma_f32 v64, -v54, v53, v52
	v_fma_f32 v65, -v55, v53, v52
	v_cmp_ge_f32_e64 s[0:1], 0, v64
	s_nop 1
	v_cndmask_b32_e64 v53, v53, v54, s[0:1]
	v_cmp_lt_f32_e64 s[0:1], 0, v65
	s_nop 1
	v_cndmask_b32_e64 v53, v53, v55, s[0:1]
	v_mul_f32_e32 v54, 0x37800000, v53
	v_cndmask_b32_e32 v53, v53, v54, vcc
	v_cmp_class_f32_e32 vcc, v52, v102
	s_nop 1
	v_cndmask_b32_e32 v54, v53, v52, vcc
	v_div_scale_f32 v55, s[0:1], v54, v54, 1.0
	v_rcp_f32_e32 v64, v55
	v_div_scale_f32 v65, vcc, 1.0, v54, 1.0
	v_lshl_add_u64 v[52:53], s[14:15], 0, v[36:37]
	v_fma_f32 v66, -v55, v64, 1.0
	v_fmac_f32_e32 v64, v66, v64
	v_mul_f32_e32 v66, v65, v64
	v_fma_f32 v67, -v55, v66, v65
	v_fmac_f32_e32 v66, v67, v64
	v_fma_f32 v55, -v55, v66, v65
	v_div_fmas_f32 v55, v55, v64, v66
	v_div_fixup_f32 v54, v55, v54, 1.0
	v_pk_mul_f32 v[44:45], v[44:45], v[54:55] op_sel_hi:[1,0]
	v_pk_mul_f32 v[24:25], v[24:25], v[54:55] op_sel_hi:[1,0]
	v_pk_fma_f32 v[0:1], v[172:173], v[44:45], v[204:205]
	v_pk_fma_f32 v[2:3], v[174:175], v[24:25], v[206:207]
	global_store_dwordx4 v[52:53], v[0:3], off
	s_nop 1
	s_nop 0
	v_pk_mul_f32 v[24:25], v[26:27], v[54:55] op_sel_hi:[1,0]
	v_pk_mul_f32 v[26:27], v[48:49], v[54:55] op_sel_hi:[1,0]
	v_pk_mul_f32 v[16:17], v[16:17], v[54:55] op_sel_hi:[1,0]
	v_pk_mul_f32 v[8:9], v[8:9], v[54:55] op_sel_hi:[1,0]
	s_or_b32 s0, s10, 2
	s_ashr_i32 s1, s0, 31
	s_lshl_b64 s[14:15], s[0:1], 11
	v_cvt_f32_f16_sdwa v49, v73 dst_sel:DWORD dst_unused:UNUSED_PAD src0_sel:WORD_1
	v_cvt_f32_f16_e32 v48, v73
	v_cvt_f32_f16_sdwa v65, v69 dst_sel:DWORD dst_unused:UNUSED_PAD src0_sel:WORD_1
	v_cvt_f32_f16_e32 v64, v69
	v_cvt_f32_f16_sdwa v67, v68 dst_sel:DWORD dst_unused:UNUSED_PAD src0_sel:WORD_1
	v_cvt_f32_f16_e32 v66, v68
	v_cvt_f32_f16_sdwa v69, v63 dst_sel:DWORD dst_unused:UNUSED_PAD src0_sel:WORD_1
	v_cvt_f32_f16_e32 v68, v63
	v_cvt_f32_f16_sdwa v63, v62 dst_sel:DWORD dst_unused:UNUSED_PAD src0_sel:WORD_1
	v_cvt_f32_f16_e32 v62, v62
	v_cvt_f32_f16_sdwa v73, v59 dst_sel:DWORD dst_unused:UNUSED_PAD src0_sel:WORD_1
	s_lshl_b64 s[0:1], s[0:1], 13
	v_pk_fma_f32 v[0:1], v[176:177], v[26:27], v[208:209]
	v_pk_fma_f32 v[2:3], v[178:179], v[24:25], v[210:211]
	global_store_dwordx4 v[52:53], v[0:3], off offset:16
	s_nop 1
	s_nop 0
	v_pk_mul_f32 v[24:25], v[28:29], v[54:55] op_sel_hi:[1,0]
	v_pk_fma_f32 v[2:3], v[182:183], v[16:17], v[214:215]
	v_pk_fma_f32 v[0:1], v[180:181], v[24:25], v[212:213]
	global_store_dwordx4 v[52:53], v[0:3], off offset:32
	s_nop 1
	s_nop 0
	v_pk_mul_f32 v[16:17], v[18:19], v[54:55] op_sel_hi:[1,0]
	v_pk_mul_f32 v[18:19], v[20:21], v[54:55] op_sel_hi:[1,0]
	v_pk_fma_f32 v[2:3], v[186:187], v[16:17], v[218:219]
	v_pk_fma_f32 v[0:1], v[184:185], v[18:19], v[216:217]
	global_store_dwordx4 v[52:53], v[0:3], off offset:48
	s_nop 1
	s_nop 0
	v_add_co_u32_e32 v16, vcc, s12, v52
	v_pk_mul_f32 v[18:19], v[22:23], v[54:55] op_sel_hi:[1,0]
	s_nop 0
	v_addc_co_u32_e32 v17, vcc, 0, v53, vcc
	v_cvt_f32_f16_sdwa v53, v71 dst_sel:DWORD dst_unused:UNUSED_PAD src0_sel:WORD_1
	v_cvt_f32_f16_e32 v52, v71
	v_cvt_f32_f16_sdwa v71, v61 dst_sel:DWORD dst_unused:UNUSED_PAD src0_sel:WORD_1
	v_pk_fma_f32 v[0:1], v[188:189], v[18:19], v[220:221]
	v_pk_fma_f32 v[2:3], v[190:191], v[8:9], v[222:223]
	global_store_dwordx4 v[16:17], v[0:3], off
	s_nop 1
	s_nop 0
	v_pk_mul_f32 v[8:9], v[10:11], v[54:55] op_sel_hi:[1,0]
	v_pk_mul_f32 v[10:11], v[12:13], v[54:55] op_sel_hi:[1,0]
	v_pk_mul_f32 v[12:13], v[30:31], v[54:55] op_sel_hi:[1,0]
	v_pk_fma_f32 v[0:1], v[192:193], v[10:11], v[224:225]
	v_pk_fma_f32 v[2:3], v[194:195], v[8:9], v[226:227]
	global_store_dwordx4 v[16:17], v[0:3], off offset:16
	s_nop 1
	s_nop 0
	v_pk_mul_f32 v[8:9], v[50:51], v[54:55] op_sel_hi:[1,0]
	v_pk_mul_f32 v[10:11], v[14:15], v[54:55] op_sel_hi:[1,0]
	v_cvt_f32_f16_sdwa v51, v72 dst_sel:DWORD dst_unused:UNUSED_PAD src0_sel:WORD_1
	v_cvt_f32_f16_e32 v50, v72
	v_cvt_f32_f16_e32 v72, v59
	v_cvt_f32_f16_sdwa v59, v58 dst_sel:DWORD dst_unused:UNUSED_PAD src0_sel:WORD_1
	v_cvt_f32_f16_e32 v58, v58
	v_pk_fma_f32 v[0:1], v[196:197], v[10:11], v[228:229]
	v_pk_fma_f32 v[2:3], v[198:199], v[8:9], v[230:231]
	global_store_dwordx4 v[16:17], v[0:3], off offset:32
	s_nop 1
	s_nop 0
	v_lshl_add_u64 v[8:9], s[14:15], 0, v[42:43]
	v_pk_mul_f32 v[10:11], v[46:47], v[54:55] op_sel_hi:[1,0]
	v_lshlrev_b64 v[8:9], 1, v[8:9]
	v_lshl_add_u64 v[44:45], s[70:71], 0, v[8:9]
	v_lshl_add_u64 v[46:47], s[2:3], 0, v[8:9]
	v_cvt_f32_f16_sdwa v55, v70 dst_sel:DWORD dst_unused:UNUSED_PAD src0_sel:WORD_1
	v_cvt_f32_f16_e32 v54, v70
	v_cvt_f32_f16_e32 v70, v61
	v_cvt_f32_f16_sdwa v61, v60 dst_sel:DWORD dst_unused:UNUSED_PAD src0_sel:WORD_1
	v_cvt_f32_f16_e32 v60, v60
	s_add_u32 s14, s20, s0
	s_addc_u32 s15, s21, s1
	v_pk_fma_f32 v[0:1], v[200:201], v[12:13], v[232:233]
	v_pk_fma_f32 v[2:3], v[202:203], v[10:11], v[234:235]
	global_store_dwordx4 v[16:17], v[0:3], off offset:48
	s_nop 1
	global_load_dwordx4 v[4:7], v[44:45], off offset:2064
	s_nop 0
	global_load_dwordx4 v[0:3], v[46:47], off offset:2064
	global_load_dwordx4 v[28:31], v[44:45], off
	global_load_dwordx4 v[24:27], v[46:47], off
	global_load_dwordx4 v[20:23], v[44:45], off offset:16
	global_load_dwordx4 v[16:19], v[46:47], off offset:16
	global_load_dwordx4 v[12:15], v[44:45], off offset:2048
	global_load_dwordx4 v[8:11], v[46:47], off offset:2048
	v_cvt_f32_f16_sdwa v45, v75 dst_sel:DWORD dst_unused:UNUSED_PAD src0_sel:WORD_1
	v_cvt_f32_f16_e32 v44, v75
	v_cvt_f32_f16_sdwa v47, v74 dst_sel:DWORD dst_unused:UNUSED_PAD src0_sel:WORD_1
	v_cvt_f32_f16_e32 v46, v74
	v_cvt_f32_f16_sdwa v75, v57 dst_sel:DWORD dst_unused:UNUSED_PAD src0_sel:WORD_1
	v_cvt_f32_f16_e32 v74, v57
	v_cvt_f32_f16_sdwa v57, v56 dst_sel:DWORD dst_unused:UNUSED_PAD src0_sel:WORD_1
	v_cvt_f32_f16_e32 v56, v56
	s_waitcnt vmcnt(6)
	v_and_b32_e32 v107, 0xffff0000, v2
	v_lshlrev_b32_e32 v106, 16, v2
	s_waitcnt vmcnt(5)
	v_lshlrev_b32_e32 v108, 16, v28
	v_and_b32_e32 v109, 0xffff0000, v28
	s_waitcnt vmcnt(4)
	v_lshlrev_b32_e32 v110, 16, v24
	v_and_b32_e32 v105, 0xffff0000, v6
	v_lshlrev_b32_e32 v104, 16, v6
	v_and_b32_e32 v111, 0xffff0000, v24
	v_and_b32_e32 v113, 0xffff0000, v7
	v_lshlrev_b32_e32 v112, 16, v7
	v_and_b32_e32 v7, 0xffff0000, v3
	v_lshlrev_b32_e32 v6, 16, v3
	v_lshlrev_b32_e32 v2, 16, v30
	v_and_b32_e32 v3, 0xffff0000, v30
	v_lshlrev_b32_e32 v114, 16, v26
	v_and_b32_e32 v115, 0xffff0000, v26
	v_lshlrev_b32_e32 v30, 16, v31
	v_and_b32_e32 v31, 0xffff0000, v31
	v_lshlrev_b32_e32 v26, 16, v27
	v_and_b32_e32 v27, 0xffff0000, v27
	v_lshlrev_b32_e32 v132, 16, v4
	v_and_b32_e32 v133, 0xffff0000, v4
	v_lshlrev_b32_e32 v134, 16, v0
	v_and_b32_e32 v135, 0xffff0000, v0
	v_lshlrev_b32_e32 v4, 16, v5
	v_and_b32_e32 v5, 0xffff0000, v5
	v_lshlrev_b32_e32 v0, 16, v1
	v_and_b32_e32 v1, 0xffff0000, v1
	v_pk_fma_f32 v[104:105], v[104:105], s[6:7], v[106:107] op_sel_hi:[1,0,1]
	v_pk_fma_f32 v[106:107], v[108:109], s[6:7], v[110:111] op_sel_hi:[1,0,1]
	v_lshlrev_b32_e32 v28, 16, v29
	v_and_b32_e32 v29, 0xffff0000, v29
	v_lshlrev_b32_e32 v24, 16, v25
	v_and_b32_e32 v25, 0xffff0000, v25
	v_pk_fma_f32 v[6:7], v[112:113], s[6:7], v[6:7] op_sel_hi:[1,0,1]
	v_pk_fma_f32 v[26:27], v[30:31], s[6:7], v[26:27] op_sel_hi:[1,0,1]
	v_pk_fma_f32 v[0:1], v[4:5], s[6:7], v[0:1] op_sel_hi:[1,0,1]
	v_pk_add_f32 v[30:31], v[104:105], v[44:45]
	v_pk_add_f32 v[44:45], v[106:107], v[46:47]
	v_pk_fma_f32 v[24:25], v[28:29], s[6:7], v[24:25] op_sel_hi:[1,0,1]
	v_pk_add_f32 v[46:47], v[6:7], v[50:51]
	v_pk_add_f32 v[50:51], v[0:1], v[56:57]
	v_add_f32_e32 v0, 0, v44
	v_pk_add_f32 v[24:25], v[24:25], v[48:49]
	v_add_f32_e32 v0, v45, v0
	v_pk_fma_f32 v[2:3], v[2:3], s[6:7], v[114:115] op_sel_hi:[1,0,1]
	v_add_f32_e32 v0, v24, v0
	v_pk_add_f32 v[48:49], v[2:3], v[52:53]
	v_add_f32_e32 v0, v25, v0
	v_add_f32_e32 v0, v48, v0
	s_waitcnt vmcnt(3)
	v_lshlrev_b32_e32 v116, 16, v20
	v_and_b32_e32 v117, 0xffff0000, v20
	s_waitcnt vmcnt(2)
	v_lshlrev_b32_e32 v118, 16, v16
	v_and_b32_e32 v119, 0xffff0000, v16
	v_pk_add_f32 v[26:27], v[26:27], v[54:55]
	v_add_f32_e32 v0, v49, v0
	v_pk_fma_f32 v[28:29], v[116:117], s[6:7], v[118:119] op_sel_hi:[1,0,1]
	v_add_f32_e32 v0, v26, v0
	v_lshlrev_b32_e32 v20, 16, v21
	v_and_b32_e32 v21, 0xffff0000, v21
	v_lshlrev_b32_e32 v16, 16, v17
	v_and_b32_e32 v17, 0xffff0000, v17
	v_pk_add_f32 v[28:29], v[28:29], v[64:65]
	v_add_f32_e32 v0, v27, v0
	v_pk_fma_f32 v[16:17], v[20:21], s[6:7], v[16:17] op_sel_hi:[1,0,1]
	v_add_f32_e32 v0, v28, v0
	v_lshlrev_b32_e32 v120, 16, v22
	v_and_b32_e32 v121, 0xffff0000, v22
	v_lshlrev_b32_e32 v122, 16, v18
	v_and_b32_e32 v123, 0xffff0000, v18
	v_pk_add_f32 v[16:17], v[16:17], v[66:67]
	v_add_f32_e32 v0, v29, v0
	v_pk_fma_f32 v[20:21], v[120:121], s[6:7], v[122:123] op_sel_hi:[1,0,1]
	v_add_f32_e32 v0, v16, v0
	v_lshlrev_b32_e32 v22, 16, v23
	v_and_b32_e32 v23, 0xffff0000, v23
	v_lshlrev_b32_e32 v18, 16, v19
	v_and_b32_e32 v19, 0xffff0000, v19
	v_pk_add_f32 v[20:21], v[20:21], v[68:69]
	v_add_f32_e32 v0, v17, v0
	v_pk_fma_f32 v[18:19], v[22:23], s[6:7], v[18:19] op_sel_hi:[1,0,1]
	v_add_f32_e32 v0, v20, v0
	s_waitcnt vmcnt(1)
	v_lshlrev_b32_e32 v124, 16, v12
	v_and_b32_e32 v125, 0xffff0000, v12
	s_waitcnt vmcnt(0)
	v_lshlrev_b32_e32 v126, 16, v8
	v_and_b32_e32 v127, 0xffff0000, v8
	v_pk_add_f32 v[18:19], v[18:19], v[62:63]
	v_add_f32_e32 v0, v21, v0
	v_pk_fma_f32 v[22:23], v[124:125], s[6:7], v[126:127] op_sel_hi:[1,0,1]
	v_add_f32_e32 v0, v18, v0
	v_lshlrev_b32_e32 v12, 16, v13
	v_and_b32_e32 v13, 0xffff0000, v13
	v_lshlrev_b32_e32 v8, 16, v9
	v_and_b32_e32 v9, 0xffff0000, v9
	v_pk_add_f32 v[22:23], v[22:23], v[70:71]
	v_add_f32_e32 v0, v19, v0
	v_pk_fma_f32 v[8:9], v[12:13], s[6:7], v[8:9] op_sel_hi:[1,0,1]
	v_add_f32_e32 v0, v22, v0
	v_lshlrev_b32_e32 v128, 16, v14
	v_and_b32_e32 v129, 0xffff0000, v14
	v_lshlrev_b32_e32 v130, 16, v10
	v_and_b32_e32 v131, 0xffff0000, v10
	v_pk_add_f32 v[8:9], v[8:9], v[60:61]
	v_add_f32_e32 v0, v23, v0
	v_pk_fma_f32 v[12:13], v[128:129], s[6:7], v[130:131] op_sel_hi:[1,0,1]
	v_add_f32_e32 v0, v8, v0
	v_lshlrev_b32_e32 v14, 16, v15
	v_and_b32_e32 v15, 0xffff0000, v15
	v_lshlrev_b32_e32 v10, 16, v11
	v_and_b32_e32 v11, 0xffff0000, v11
	v_pk_add_f32 v[12:13], v[12:13], v[72:73]
	v_add_f32_e32 v0, v9, v0
	v_pk_fma_f32 v[10:11], v[14:15], s[6:7], v[10:11] op_sel_hi:[1,0,1]
	v_add_f32_e32 v0, v12, v0
	v_pk_add_f32 v[10:11], v[10:11], v[58:59]
	v_add_f32_e32 v0, v13, v0
	v_pk_fma_f32 v[14:15], v[132:133], s[6:7], v[134:135] op_sel_hi:[1,0,1]
	v_add_f32_e32 v0, v10, v0
	v_pk_add_f32 v[14:15], v[14:15], v[74:75]
	v_add_f32_e32 v0, v11, v0
	v_add_f32_e32 v0, v14, v0
	v_add_f32_e32 v0, v15, v0
	v_add_f32_e32 v0, v50, v0
	v_add_f32_e32 v0, v51, v0
	v_add_f32_e32 v0, v30, v0
	v_add_f32_e32 v0, v31, v0
	v_add_f32_e32 v0, v46, v0
	v_add_f32_e32 v0, v47, v0
	ds_bpermute_b32 v1, v79, v0
	s_waitcnt lgkmcnt(0)
	v_add_f32_e32 v0, v0, v1
	ds_bpermute_b32 v1, v80, v0
	s_waitcnt lgkmcnt(0)
	v_add_f32_e32 v0, v0, v1
	ds_bpermute_b32 v1, v81, v0
	s_waitcnt lgkmcnt(0)
	v_add_f32_e32 v0, v0, v1
	ds_bpermute_b32 v1, v82, v0
	s_waitcnt lgkmcnt(0)
	v_add_f32_e32 v0, v0, v1
	ds_bpermute_b32 v1, v83, v0
	s_waitcnt lgkmcnt(0)
	v_add_f32_e32 v52, v0, v1
	ds_bpermute_b32 v53, v84, v52
	s_waitcnt lgkmcnt(0)
	v_add_f32_e32 v52, v52, v53
	v_mul_f32_e32 v52, 0x3a000000, v52
	v_pk_add_f32 v[44:45], v[44:45], v[52:53] op_sel_hi:[1,0] neg_lo:[0,1] neg_hi:[0,1]
	v_pk_add_f32 v[24:25], v[24:25], v[52:53] op_sel_hi:[1,0] neg_lo:[0,1] neg_hi:[0,1]
	v_pk_add_f32 v[48:49], v[48:49], v[52:53] op_sel_hi:[1,0] neg_lo:[0,1] neg_hi:[0,1]
	v_pk_add_f32 v[26:27], v[26:27], v[52:53] op_sel_hi:[1,0] neg_lo:[0,1] neg_hi:[0,1]
	v_pk_add_f32 v[28:29], v[28:29], v[52:53] op_sel_hi:[1,0] neg_lo:[0,1] neg_hi:[0,1]
	v_pk_add_f32 v[16:17], v[16:17], v[52:53] op_sel_hi:[1,0] neg_lo:[0,1] neg_hi:[0,1]
	v_pk_add_f32 v[20:21], v[20:21], v[52:53] op_sel_hi:[1,0] neg_lo:[0,1] neg_hi:[0,1]
	v_pk_add_f32 v[18:19], v[18:19], v[52:53] op_sel_hi:[1,0] neg_lo:[0,1] neg_hi:[0,1]
	v_pk_add_f32 v[22:23], v[22:23], v[52:53] op_sel_hi:[1,0] neg_lo:[0,1] neg_hi:[0,1]
	v_pk_add_f32 v[8:9], v[8:9], v[52:53] op_sel_hi:[1,0] neg_lo:[0,1] neg_hi:[0,1]
	v_pk_add_f32 v[12:13], v[12:13], v[52:53] op_sel_hi:[1,0] neg_lo:[0,1] neg_hi:[0,1]
	v_pk_add_f32 v[10:11], v[10:11], v[52:53] op_sel_hi:[1,0] neg_lo:[0,1] neg_hi:[0,1]
	v_pk_add_f32 v[14:15], v[14:15], v[52:53] op_sel_hi:[1,0] neg_lo:[0,1] neg_hi:[0,1]
	v_pk_add_f32 v[50:51], v[50:51], v[52:53] op_sel_hi:[1,0] neg_lo:[0,1] neg_hi:[0,1]
	v_pk_add_f32 v[46:47], v[46:47], v[52:53] op_sel_hi:[1,0] neg_lo:[0,1] neg_hi:[0,1]
	v_pk_add_f32 v[30:31], v[30:31], v[52:53] op_sel_hi:[1,0] neg_lo:[0,1] neg_hi:[0,1]
	v_pk_mul_f32 v[52:53], v[44:45], v[44:45]
	v_pk_mul_f32 v[54:55], v[24:25], v[24:25]
	v_add_f32_e32 v52, v52, v53
	v_add_f32_e32 v52, v54, v52
	v_pk_mul_f32 v[56:57], v[48:49], v[48:49]
	v_add_f32_e32 v52, v55, v52
	v_add_f32_e32 v52, v56, v52
	v_pk_mul_f32 v[58:59], v[26:27], v[26:27]
	v_add_f32_e32 v52, v57, v52
	v_add_f32_e32 v52, v58, v52
	v_pk_mul_f32 v[60:61], v[28:29], v[28:29]
	v_add_f32_e32 v52, v59, v52
	v_add_f32_e32 v52, v60, v52
	v_pk_mul_f32 v[62:63], v[16:17], v[16:17]
	v_add_f32_e32 v52, v61, v52
	v_add_f32_e32 v52, v62, v52
	v_pk_mul_f32 v[64:65], v[20:21], v[20:21]
	v_add_f32_e32 v52, v63, v52
	v_add_f32_e32 v52, v64, v52
	v_pk_mul_f32 v[66:67], v[18:19], v[18:19]
	v_add_f32_e32 v52, v65, v52
	v_add_f32_e32 v52, v66, v52
	v_pk_mul_f32 v[68:69], v[22:23], v[22:23]
	v_add_f32_e32 v52, v67, v52
	v_add_f32_e32 v52, v68, v52
	v_pk_mul_f32 v[70:71], v[8:9], v[8:9]
	v_add_f32_e32 v52, v69, v52
	v_add_f32_e32 v52, v70, v52
	v_pk_mul_f32 v[72:73], v[12:13], v[12:13]
	v_add_f32_e32 v52, v71, v52
	v_add_f32_e32 v52, v72, v52
	v_pk_mul_f32 v[74:75], v[10:11], v[10:11]
	v_add_f32_e32 v52, v73, v52
	v_add_f32_e32 v52, v74, v52
	v_pk_mul_f32 v[104:105], v[14:15], v[14:15]
	v_add_f32_e32 v52, v75, v52
	v_add_f32_e32 v52, v104, v52
	v_pk_mul_f32 v[106:107], v[50:51], v[50:51]
	v_add_f32_e32 v52, v105, v52
	v_add_f32_e32 v52, v106, v52
	v_pk_mul_f32 v[110:111], v[30:31], v[30:31]
	v_add_f32_e32 v52, v107, v52
	v_add_f32_e32 v52, v110, v52
	v_pk_mul_f32 v[108:109], v[46:47], v[46:47]
	v_add_f32_e32 v52, v111, v52
	v_add_f32_e32 v52, v108, v52
	v_add_f32_e32 v52, v109, v52
	ds_bpermute_b32 v53, v79, v52
	v_cvt_f32_f16_sdwa v73, v141 dst_sel:DWORD dst_unused:UNUSED_PAD src0_sel:WORD_1
	v_cvt_f32_f16_e32 v72, v141
	v_cvt_f32_f16_sdwa v61, v147 dst_sel:DWORD dst_unused:UNUSED_PAD src0_sel:WORD_1
	v_cvt_f32_f16_e32 v60, v147
	s_waitcnt lgkmcnt(0)
	v_add_f32_e32 v52, v52, v53
	ds_bpermute_b32 v53, v80, v52
	v_cvt_f32_f16_sdwa v63, v146 dst_sel:DWORD dst_unused:UNUSED_PAD src0_sel:WORD_1
	v_cvt_f32_f16_e32 v62, v146
	v_cvt_f32_f16_sdwa v65, v145 dst_sel:DWORD dst_unused:UNUSED_PAD src0_sel:WORD_1
	v_cvt_f32_f16_e32 v64, v145
	s_waitcnt lgkmcnt(0)
	v_add_f32_e32 v52, v52, v53
	ds_bpermute_b32 v53, v81, v52
	v_cvt_f32_f16_sdwa v67, v144 dst_sel:DWORD dst_unused:UNUSED_PAD src0_sel:WORD_1
	v_cvt_f32_f16_e32 v66, v144
	v_cvt_f32_f16_sdwa v69, v143 dst_sel:DWORD dst_unused:UNUSED_PAD src0_sel:WORD_1
	v_cvt_f32_f16_e32 v68, v143
	s_waitcnt lgkmcnt(0)
	v_add_f32_e32 v52, v52, v53
	ds_bpermute_b32 v53, v82, v52
	v_cvt_f32_f16_sdwa v71, v142 dst_sel:DWORD dst_unused:UNUSED_PAD src0_sel:WORD_1
	v_cvt_f32_f16_e32 v70, v142
	s_waitcnt lgkmcnt(0)
	v_add_f32_e32 v52, v52, v53
	ds_bpermute_b32 v53, v83, v52
	s_waitcnt lgkmcnt(0)
	v_add_f32_e32 v52, v52, v53
	ds_bpermute_b32 v53, v84, v52
	s_waitcnt lgkmcnt(0)
	v_add_f32_e32 v52, v52, v53
	v_fmamk_f32 v52, v52, 0x3a000000, v101
	v_mul_f32_e32 v53, 0x4f800000, v52
	v_cmp_gt_f32_e32 vcc, s7, v52
	s_nop 1
	v_cndmask_b32_e32 v52, v52, v53, vcc
	v_sqrt_f32_e32 v53, v52
	s_nop 0
	v_add_u32_e32 v54, -1, v53
	v_add_u32_e32 v55, 1, v53
	v_fma_f32 v56, -v54, v53, v52
	v_fma_f32 v57, -v55, v53, v52
	v_cmp_ge_f32_e64 s[0:1], 0, v56
	s_nop 1
	v_cndmask_b32_e64 v53, v53, v54, s[0:1]
	v_cmp_lt_f32_e64 s[0:1], 0, v57
	s_nop 1
	v_cndmask_b32_e64 v53, v53, v55, s[0:1]
	v_mul_f32_e32 v54, 0x37800000, v53
	v_cndmask_b32_e32 v53, v53, v54, vcc
	v_cmp_class_f32_e32 vcc, v52, v102
	s_nop 1
	v_cndmask_b32_e32 v54, v53, v52, vcc
	v_div_scale_f32 v55, s[0:1], v54, v54, 1.0
	v_rcp_f32_e32 v56, v55
	v_div_scale_f32 v57, vcc, 1.0, v54, 1.0
	v_lshl_add_u64 v[52:53], s[14:15], 0, v[36:37]
	v_fma_f32 v58, -v55, v56, 1.0
	v_fmac_f32_e32 v56, v58, v56
	v_mul_f32_e32 v58, v57, v56
	v_fma_f32 v59, -v55, v58, v57
	v_fmac_f32_e32 v58, v59, v56
	v_fma_f32 v55, -v55, v58, v57
	v_div_fmas_f32 v55, v55, v56, v58
	v_div_fixup_f32 v54, v55, v54, 1.0
	v_pk_mul_f32 v[44:45], v[44:45], v[54:55] op_sel_hi:[1,0]
	v_pk_mul_f32 v[24:25], v[24:25], v[54:55] op_sel_hi:[1,0]
	v_pk_fma_f32 v[0:1], v[172:173], v[44:45], v[204:205]
	v_pk_fma_f32 v[2:3], v[174:175], v[24:25], v[206:207]
	global_store_dwordx4 v[52:53], v[0:3], off
	s_nop 1
	s_nop 0
	v_pk_mul_f32 v[24:25], v[26:27], v[54:55] op_sel_hi:[1,0]
	v_pk_mul_f32 v[26:27], v[48:49], v[54:55] op_sel_hi:[1,0]
	v_pk_mul_f32 v[16:17], v[16:17], v[54:55] op_sel_hi:[1,0]
	v_pk_mul_f32 v[8:9], v[8:9], v[54:55] op_sel_hi:[1,0]
	s_or_b32 s0, s10, 3
	s_ashr_i32 s1, s0, 31
	s_lshl_b64 s[10:11], s[0:1], 11
	v_cvt_f32_f16_sdwa v49, v148 dst_sel:DWORD dst_unused:UNUSED_PAD src0_sel:WORD_1
	v_cvt_f32_f16_e32 v48, v148
	v_cvt_f32_f16_sdwa v57, v157 dst_sel:DWORD dst_unused:UNUSED_PAD src0_sel:WORD_1
	v_cvt_f32_f16_e32 v56, v157
	v_cvt_f32_f16_sdwa v59, v156 dst_sel:DWORD dst_unused:UNUSED_PAD src0_sel:WORD_1
	v_cvt_f32_f16_e32 v58, v156
	s_lshl_b64 s[0:1], s[0:1], 13
	v_pk_fma_f32 v[0:1], v[176:177], v[26:27], v[208:209]
	v_pk_fma_f32 v[2:3], v[178:179], v[24:25], v[210:211]
	global_store_dwordx4 v[52:53], v[0:3], off offset:16
	s_nop 1
	s_nop 0
	v_pk_mul_f32 v[24:25], v[28:29], v[54:55] op_sel_hi:[1,0]
	v_pk_fma_f32 v[2:3], v[182:183], v[16:17], v[214:215]
	v_pk_fma_f32 v[0:1], v[180:181], v[24:25], v[212:213]
	global_store_dwordx4 v[52:53], v[0:3], off offset:32
	s_nop 1
	s_nop 0
	v_pk_mul_f32 v[16:17], v[18:19], v[54:55] op_sel_hi:[1,0]
	v_pk_mul_f32 v[18:19], v[20:21], v[54:55] op_sel_hi:[1,0]
	v_pk_fma_f32 v[2:3], v[186:187], v[16:17], v[218:219]
	v_pk_fma_f32 v[0:1], v[184:185], v[18:19], v[216:217]
	global_store_dwordx4 v[52:53], v[0:3], off offset:48
	s_nop 1
	s_nop 0
	v_add_co_u32_e32 v16, vcc, s12, v52
	v_pk_mul_f32 v[18:19], v[22:23], v[54:55] op_sel_hi:[1,0]
	s_nop 0
	v_addc_co_u32_e32 v17, vcc, 0, v53, vcc
	v_cvt_f32_f16_sdwa v53, v159 dst_sel:DWORD dst_unused:UNUSED_PAD src0_sel:WORD_1
	v_cvt_f32_f16_e32 v52, v159
	v_pk_fma_f32 v[0:1], v[188:189], v[18:19], v[220:221]
	v_pk_fma_f32 v[2:3], v[190:191], v[8:9], v[222:223]
	global_store_dwordx4 v[16:17], v[0:3], off
	s_nop 1
	s_nop 0
	v_pk_mul_f32 v[8:9], v[10:11], v[54:55] op_sel_hi:[1,0]
	v_pk_mul_f32 v[10:11], v[12:13], v[54:55] op_sel_hi:[1,0]
	v_pk_mul_f32 v[12:13], v[30:31], v[54:55] op_sel_hi:[1,0]
	v_pk_fma_f32 v[0:1], v[192:193], v[10:11], v[224:225]
	v_pk_fma_f32 v[2:3], v[194:195], v[8:9], v[226:227]
	global_store_dwordx4 v[16:17], v[0:3], off offset:16
	s_nop 1
	s_nop 0
	v_pk_mul_f32 v[8:9], v[50:51], v[54:55] op_sel_hi:[1,0]
	v_pk_mul_f32 v[10:11], v[14:15], v[54:55] op_sel_hi:[1,0]
	v_cvt_f32_f16_sdwa v51, v160 dst_sel:DWORD dst_unused:UNUSED_PAD src0_sel:WORD_1
	v_cvt_f32_f16_e32 v50, v160
	v_pk_fma_f32 v[0:1], v[196:197], v[10:11], v[228:229]
	v_pk_fma_f32 v[2:3], v[198:199], v[8:9], v[230:231]
	global_store_dwordx4 v[16:17], v[0:3], off offset:32
	s_nop 1
	s_nop 0
	v_lshl_add_u64 v[8:9], s[10:11], 0, v[42:43]
	v_pk_mul_f32 v[10:11], v[46:47], v[54:55] op_sel_hi:[1,0]
	v_lshlrev_b64 v[8:9], 1, v[8:9]
	v_lshl_add_u64 v[42:43], s[70:71], 0, v[8:9]
	v_lshl_add_u64 v[44:45], s[2:3], 0, v[8:9]
	v_cvt_f32_f16_sdwa v47, v161 dst_sel:DWORD dst_unused:UNUSED_PAD src0_sel:WORD_1
	v_cvt_f32_f16_e32 v46, v161
	v_cvt_f32_f16_sdwa v55, v158 dst_sel:DWORD dst_unused:UNUSED_PAD src0_sel:WORD_1
	v_cvt_f32_f16_e32 v54, v158
	s_add_u32 s10, s20, s0
	s_addc_u32 s11, s21, s1
	v_lshl_add_u64 v[36:37], s[10:11], 0, v[36:37]
	s_mov_b32 s10, 1
	v_pk_fma_f32 v[0:1], v[200:201], v[12:13], v[232:233]
	v_pk_fma_f32 v[2:3], v[202:203], v[10:11], v[234:235]
	global_store_dwordx4 v[16:17], v[0:3], off offset:48
	s_nop 1
	global_load_dwordx4 v[4:7], v[42:43], off offset:2064
	s_nop 0
	global_load_dwordx4 v[0:3], v[44:45], off offset:2064
	global_load_dwordx4 v[28:31], v[42:43], off
	global_load_dwordx4 v[24:27], v[44:45], off
	global_load_dwordx4 v[20:23], v[42:43], off offset:16
	global_load_dwordx4 v[16:19], v[44:45], off offset:16
	global_load_dwordx4 v[12:15], v[42:43], off offset:2048
	global_load_dwordx4 v[8:11], v[44:45], off offset:2048
	v_cvt_f32_f16_sdwa v43, v149 dst_sel:DWORD dst_unused:UNUSED_PAD src0_sel:WORD_1
	v_cvt_f32_f16_e32 v42, v149
	v_cvt_f32_f16_sdwa v45, v162 dst_sel:DWORD dst_unused:UNUSED_PAD src0_sel:WORD_1
	v_cvt_f32_f16_e32 v44, v162
	s_waitcnt vmcnt(6)
	v_and_b32_e32 v105, 0xffff0000, v2
	v_lshlrev_b32_e32 v104, 16, v2
	s_waitcnt vmcnt(5)
	v_lshlrev_b32_e32 v106, 16, v28
	v_and_b32_e32 v107, 0xffff0000, v28
	s_waitcnt vmcnt(4)
	v_lshlrev_b32_e32 v108, 16, v24
	v_and_b32_e32 v75, 0xffff0000, v6
	v_lshlrev_b32_e32 v74, 16, v6
	v_and_b32_e32 v109, 0xffff0000, v24
	v_and_b32_e32 v111, 0xffff0000, v7
	v_lshlrev_b32_e32 v110, 16, v7
	v_and_b32_e32 v7, 0xffff0000, v3
	v_lshlrev_b32_e32 v6, 16, v3
	v_lshlrev_b32_e32 v2, 16, v30
	v_and_b32_e32 v3, 0xffff0000, v30
	v_lshlrev_b32_e32 v112, 16, v26
	v_and_b32_e32 v113, 0xffff0000, v26
	v_lshlrev_b32_e32 v30, 16, v31
	v_and_b32_e32 v31, 0xffff0000, v31
	v_lshlrev_b32_e32 v26, 16, v27
	v_and_b32_e32 v27, 0xffff0000, v27
	v_lshlrev_b32_e32 v130, 16, v4
	v_and_b32_e32 v131, 0xffff0000, v4
	v_lshlrev_b32_e32 v132, 16, v0
	v_and_b32_e32 v133, 0xffff0000, v0
	v_lshlrev_b32_e32 v4, 16, v5
	v_and_b32_e32 v5, 0xffff0000, v5
	v_lshlrev_b32_e32 v0, 16, v1
	v_and_b32_e32 v1, 0xffff0000, v1
	v_pk_fma_f32 v[74:75], v[74:75], s[6:7], v[104:105] op_sel_hi:[1,0,1]
	v_pk_fma_f32 v[104:105], v[106:107], s[6:7], v[108:109] op_sel_hi:[1,0,1]
	v_lshlrev_b32_e32 v28, 16, v29
	v_and_b32_e32 v29, 0xffff0000, v29
	v_lshlrev_b32_e32 v24, 16, v25
	v_and_b32_e32 v25, 0xffff0000, v25
	v_pk_fma_f32 v[6:7], v[110:111], s[6:7], v[6:7] op_sel_hi:[1,0,1]
	v_pk_fma_f32 v[26:27], v[30:31], s[6:7], v[26:27] op_sel_hi:[1,0,1]
	v_pk_fma_f32 v[0:1], v[4:5], s[6:7], v[0:1] op_sel_hi:[1,0,1]
	v_pk_add_f32 v[30:31], v[74:75], v[42:43]
	v_pk_add_f32 v[42:43], v[104:105], v[44:45]
	v_pk_fma_f32 v[24:25], v[28:29], s[6:7], v[24:25] op_sel_hi:[1,0,1]
	v_pk_add_f32 v[44:45], v[6:7], v[48:49]
	v_pk_add_f32 v[48:49], v[0:1], v[72:73]
	v_add_f32_e32 v0, 0, v42
	v_pk_add_f32 v[24:25], v[24:25], v[46:47]
	v_add_f32_e32 v0, v43, v0
	v_pk_fma_f32 v[2:3], v[2:3], s[6:7], v[112:113] op_sel_hi:[1,0,1]
	v_add_f32_e32 v0, v24, v0
	v_pk_add_f32 v[46:47], v[2:3], v[50:51]
	v_add_f32_e32 v0, v25, v0
	v_add_f32_e32 v0, v46, v0
	s_waitcnt vmcnt(3)
	v_lshlrev_b32_e32 v114, 16, v20
	v_and_b32_e32 v115, 0xffff0000, v20
	s_waitcnt vmcnt(2)
	v_lshlrev_b32_e32 v116, 16, v16
	v_and_b32_e32 v117, 0xffff0000, v16
	v_pk_add_f32 v[26:27], v[26:27], v[52:53]
	v_add_f32_e32 v0, v47, v0
	v_pk_fma_f32 v[28:29], v[114:115], s[6:7], v[116:117] op_sel_hi:[1,0,1]
	v_add_f32_e32 v0, v26, v0
	v_lshlrev_b32_e32 v20, 16, v21
	v_and_b32_e32 v21, 0xffff0000, v21
	v_lshlrev_b32_e32 v16, 16, v17
	v_and_b32_e32 v17, 0xffff0000, v17
	v_pk_add_f32 v[28:29], v[28:29], v[54:55]
	v_add_f32_e32 v0, v27, v0
	v_pk_fma_f32 v[16:17], v[20:21], s[6:7], v[16:17] op_sel_hi:[1,0,1]
	v_add_f32_e32 v0, v28, v0
	v_lshlrev_b32_e32 v118, 16, v22
	v_and_b32_e32 v119, 0xffff0000, v22
	v_lshlrev_b32_e32 v120, 16, v18
	v_and_b32_e32 v121, 0xffff0000, v18
	v_pk_add_f32 v[16:17], v[16:17], v[56:57]
	v_add_f32_e32 v0, v29, v0
	v_pk_fma_f32 v[20:21], v[118:119], s[6:7], v[120:121] op_sel_hi:[1,0,1]
	v_add_f32_e32 v0, v16, v0
	v_lshlrev_b32_e32 v22, 16, v23
	v_and_b32_e32 v23, 0xffff0000, v23
	v_lshlrev_b32_e32 v18, 16, v19
	v_and_b32_e32 v19, 0xffff0000, v19
	v_pk_add_f32 v[20:21], v[20:21], v[58:59]
	v_add_f32_e32 v0, v17, v0
	v_pk_fma_f32 v[18:19], v[22:23], s[6:7], v[18:19] op_sel_hi:[1,0,1]
	v_add_f32_e32 v0, v20, v0
	s_waitcnt vmcnt(1)
	v_lshlrev_b32_e32 v122, 16, v12
	v_and_b32_e32 v123, 0xffff0000, v12
	s_waitcnt vmcnt(0)
	v_lshlrev_b32_e32 v124, 16, v8
	v_and_b32_e32 v125, 0xffff0000, v8
	v_pk_add_f32 v[18:19], v[18:19], v[60:61]
	v_add_f32_e32 v0, v21, v0
	v_pk_fma_f32 v[22:23], v[122:123], s[6:7], v[124:125] op_sel_hi:[1,0,1]
	v_add_f32_e32 v0, v18, v0
	v_lshlrev_b32_e32 v12, 16, v13
	v_and_b32_e32 v13, 0xffff0000, v13
	v_lshlrev_b32_e32 v8, 16, v9
	v_and_b32_e32 v9, 0xffff0000, v9
	v_pk_add_f32 v[22:23], v[22:23], v[62:63]
	v_add_f32_e32 v0, v19, v0
	v_pk_fma_f32 v[8:9], v[12:13], s[6:7], v[8:9] op_sel_hi:[1,0,1]
	v_add_f32_e32 v0, v22, v0
	v_lshlrev_b32_e32 v126, 16, v14
	v_and_b32_e32 v127, 0xffff0000, v14
	v_lshlrev_b32_e32 v128, 16, v10
	v_and_b32_e32 v129, 0xffff0000, v10
	v_pk_add_f32 v[8:9], v[8:9], v[64:65]
	v_add_f32_e32 v0, v23, v0
	v_pk_fma_f32 v[12:13], v[126:127], s[6:7], v[128:129] op_sel_hi:[1,0,1]
	v_add_f32_e32 v0, v8, v0
	v_lshlrev_b32_e32 v14, 16, v15
	v_and_b32_e32 v15, 0xffff0000, v15
	v_lshlrev_b32_e32 v10, 16, v11
	v_and_b32_e32 v11, 0xffff0000, v11
	v_pk_add_f32 v[12:13], v[12:13], v[66:67]
	v_add_f32_e32 v0, v9, v0
	v_pk_fma_f32 v[10:11], v[14:15], s[6:7], v[10:11] op_sel_hi:[1,0,1]
	v_add_f32_e32 v0, v12, v0
	v_pk_add_f32 v[10:11], v[10:11], v[68:69]
	v_add_f32_e32 v0, v13, v0
	v_pk_fma_f32 v[14:15], v[130:131], s[6:7], v[132:133] op_sel_hi:[1,0,1]
	v_add_f32_e32 v0, v10, v0
	v_pk_add_f32 v[14:15], v[14:15], v[70:71]
	v_add_f32_e32 v0, v11, v0
	v_add_f32_e32 v0, v14, v0
	v_add_f32_e32 v0, v15, v0
	v_add_f32_e32 v0, v48, v0
	v_add_f32_e32 v0, v49, v0
	v_add_f32_e32 v0, v30, v0
	v_add_f32_e32 v0, v31, v0
	v_add_f32_e32 v0, v44, v0
	v_add_f32_e32 v0, v45, v0
	ds_bpermute_b32 v1, v79, v0
	s_waitcnt lgkmcnt(0)
	v_add_f32_e32 v0, v0, v1
	ds_bpermute_b32 v1, v80, v0
	s_waitcnt lgkmcnt(0)
	v_add_f32_e32 v0, v0, v1
	ds_bpermute_b32 v1, v81, v0
	s_waitcnt lgkmcnt(0)
	v_add_f32_e32 v0, v0, v1
	ds_bpermute_b32 v1, v82, v0
	s_waitcnt lgkmcnt(0)
	v_add_f32_e32 v0, v0, v1
	ds_bpermute_b32 v1, v83, v0
	s_waitcnt lgkmcnt(0)
	v_add_f32_e32 v50, v0, v1
	ds_bpermute_b32 v51, v84, v50
	s_waitcnt lgkmcnt(0)
	v_add_f32_e32 v50, v50, v51
	v_mul_f32_e32 v50, 0x3a000000, v50
	v_pk_add_f32 v[42:43], v[42:43], v[50:51] op_sel_hi:[1,0] neg_lo:[0,1] neg_hi:[0,1]
	v_pk_add_f32 v[24:25], v[24:25], v[50:51] op_sel_hi:[1,0] neg_lo:[0,1] neg_hi:[0,1]
	v_pk_add_f32 v[46:47], v[46:47], v[50:51] op_sel_hi:[1,0] neg_lo:[0,1] neg_hi:[0,1]
	v_pk_add_f32 v[26:27], v[26:27], v[50:51] op_sel_hi:[1,0] neg_lo:[0,1] neg_hi:[0,1]
	v_pk_add_f32 v[28:29], v[28:29], v[50:51] op_sel_hi:[1,0] neg_lo:[0,1] neg_hi:[0,1]
	v_pk_add_f32 v[16:17], v[16:17], v[50:51] op_sel_hi:[1,0] neg_lo:[0,1] neg_hi:[0,1]
	v_pk_add_f32 v[20:21], v[20:21], v[50:51] op_sel_hi:[1,0] neg_lo:[0,1] neg_hi:[0,1]
	v_pk_add_f32 v[18:19], v[18:19], v[50:51] op_sel_hi:[1,0] neg_lo:[0,1] neg_hi:[0,1]
	v_pk_add_f32 v[22:23], v[22:23], v[50:51] op_sel_hi:[1,0] neg_lo:[0,1] neg_hi:[0,1]
	v_pk_add_f32 v[8:9], v[8:9], v[50:51] op_sel_hi:[1,0] neg_lo:[0,1] neg_hi:[0,1]
	v_pk_add_f32 v[12:13], v[12:13], v[50:51] op_sel_hi:[1,0] neg_lo:[0,1] neg_hi:[0,1]
	v_pk_add_f32 v[10:11], v[10:11], v[50:51] op_sel_hi:[1,0] neg_lo:[0,1] neg_hi:[0,1]
	v_pk_add_f32 v[14:15], v[14:15], v[50:51] op_sel_hi:[1,0] neg_lo:[0,1] neg_hi:[0,1]
	v_pk_add_f32 v[48:49], v[48:49], v[50:51] op_sel_hi:[1,0] neg_lo:[0,1] neg_hi:[0,1]
	v_pk_add_f32 v[44:45], v[44:45], v[50:51] op_sel_hi:[1,0] neg_lo:[0,1] neg_hi:[0,1]
	v_pk_add_f32 v[30:31], v[30:31], v[50:51] op_sel_hi:[1,0] neg_lo:[0,1] neg_hi:[0,1]
	v_pk_mul_f32 v[50:51], v[42:43], v[42:43]
	v_pk_mul_f32 v[52:53], v[24:25], v[24:25]
	v_add_f32_e32 v50, v50, v51
	v_add_f32_e32 v50, v52, v50
	v_pk_mul_f32 v[54:55], v[46:47], v[46:47]
	v_add_f32_e32 v50, v53, v50
	v_add_f32_e32 v50, v54, v50
	v_pk_mul_f32 v[56:57], v[26:27], v[26:27]
	v_add_f32_e32 v50, v55, v50
	v_add_f32_e32 v50, v56, v50
	v_pk_mul_f32 v[58:59], v[28:29], v[28:29]
	v_add_f32_e32 v50, v57, v50
	v_add_f32_e32 v50, v58, v50
	v_pk_mul_f32 v[60:61], v[16:17], v[16:17]
	v_add_f32_e32 v50, v59, v50
	v_add_f32_e32 v50, v60, v50
	v_pk_mul_f32 v[62:63], v[20:21], v[20:21]
	v_add_f32_e32 v50, v61, v50
	v_add_f32_e32 v50, v62, v50
	v_pk_mul_f32 v[64:65], v[18:19], v[18:19]
	v_add_f32_e32 v50, v63, v50
	v_add_f32_e32 v50, v64, v50
	v_pk_mul_f32 v[66:67], v[22:23], v[22:23]
	v_add_f32_e32 v50, v65, v50
	v_add_f32_e32 v50, v66, v50
	v_pk_mul_f32 v[68:69], v[8:9], v[8:9]
	v_add_f32_e32 v50, v67, v50
	v_add_f32_e32 v50, v68, v50
	v_pk_mul_f32 v[70:71], v[12:13], v[12:13]
	v_add_f32_e32 v50, v69, v50
	v_add_f32_e32 v50, v70, v50
	v_pk_mul_f32 v[72:73], v[10:11], v[10:11]
	v_add_f32_e32 v50, v71, v50
	v_add_f32_e32 v50, v72, v50
	v_pk_mul_f32 v[74:75], v[14:15], v[14:15]
	v_add_f32_e32 v50, v73, v50
	v_add_f32_e32 v50, v74, v50
	v_pk_mul_f32 v[104:105], v[48:49], v[48:49]
	v_add_f32_e32 v50, v75, v50
	v_add_f32_e32 v50, v104, v50
	v_pk_mul_f32 v[108:109], v[30:31], v[30:31]
	v_add_f32_e32 v50, v105, v50
	v_add_f32_e32 v50, v108, v50
	v_pk_mul_f32 v[106:107], v[44:45], v[44:45]
	v_add_f32_e32 v50, v109, v50
	v_add_f32_e32 v50, v106, v50
	v_add_f32_e32 v50, v107, v50
	ds_bpermute_b32 v51, v79, v50
	s_waitcnt lgkmcnt(0)
	v_add_f32_e32 v50, v50, v51
	ds_bpermute_b32 v51, v80, v50
	s_waitcnt lgkmcnt(0)
	v_add_f32_e32 v50, v50, v51
	ds_bpermute_b32 v51, v81, v50
	s_waitcnt lgkmcnt(0)
	v_add_f32_e32 v50, v50, v51
	ds_bpermute_b32 v51, v82, v50
	s_waitcnt lgkmcnt(0)
	v_add_f32_e32 v50, v50, v51
	ds_bpermute_b32 v51, v83, v50
	s_waitcnt lgkmcnt(0)
	v_add_f32_e32 v50, v50, v51
	ds_bpermute_b32 v51, v84, v50
	s_waitcnt lgkmcnt(0)
	v_add_f32_e32 v50, v50, v51
	v_fmamk_f32 v50, v50, 0x3a000000, v101
	v_mul_f32_e32 v51, 0x4f800000, v50
	v_cmp_gt_f32_e32 vcc, s7, v50
	s_nop 1
	v_cndmask_b32_e32 v50, v50, v51, vcc
	v_sqrt_f32_e32 v51, v50
	s_nop 0
	v_add_u32_e32 v52, -1, v51
	v_add_u32_e32 v53, 1, v51
	v_fma_f32 v54, -v52, v51, v50
	v_fma_f32 v55, -v53, v51, v50
	v_cmp_ge_f32_e64 s[0:1], 0, v54
	s_nop 1
	v_cndmask_b32_e64 v51, v51, v52, s[0:1]
	v_cmp_lt_f32_e64 s[0:1], 0, v55
	s_nop 1
	v_cndmask_b32_e64 v51, v51, v53, s[0:1]
	v_mul_f32_e32 v52, 0x37800000, v51
	v_cndmask_b32_e32 v51, v51, v52, vcc
	v_cmp_class_f32_e32 vcc, v50, v102
	s_nop 1
	v_cndmask_b32_e32 v50, v51, v50, vcc
	v_div_scale_f32 v51, s[0:1], v50, v50, 1.0
	v_rcp_f32_e32 v52, v51
	v_div_scale_f32 v53, vcc, 1.0, v50, 1.0
	s_mov_b64 s[0:1], 0
	v_fma_f32 v54, -v51, v52, 1.0
	v_fmac_f32_e32 v52, v54, v52
	v_mul_f32_e32 v54, v53, v52
	v_fma_f32 v55, -v51, v54, v53
	v_fmac_f32_e32 v54, v55, v52
	v_fma_f32 v51, -v51, v54, v53
	v_div_fmas_f32 v51, v51, v52, v54
	v_div_fixup_f32 v50, v51, v50, 1.0
	v_pk_mul_f32 v[42:43], v[42:43], v[50:51] op_sel_hi:[1,0]
	v_pk_mul_f32 v[24:25], v[24:25], v[50:51] op_sel_hi:[1,0]
	v_pk_fma_f32 v[0:1], v[172:173], v[42:43], v[204:205]
	v_pk_fma_f32 v[2:3], v[174:175], v[24:25], v[206:207]
	global_store_dwordx4 v[36:37], v[0:3], off
	s_nop 1
	s_nop 0
	v_pk_mul_f32 v[24:25], v[26:27], v[50:51] op_sel_hi:[1,0]
	v_pk_mul_f32 v[26:27], v[46:47], v[50:51] op_sel_hi:[1,0]
	v_pk_mul_f32 v[16:17], v[16:17], v[50:51] op_sel_hi:[1,0]
	v_pk_mul_f32 v[8:9], v[8:9], v[50:51] op_sel_hi:[1,0]
	v_pk_fma_f32 v[0:1], v[176:177], v[26:27], v[208:209]
	v_pk_fma_f32 v[2:3], v[178:179], v[24:25], v[210:211]
	global_store_dwordx4 v[36:37], v[0:3], off offset:16
	s_nop 1
	s_nop 0
	v_pk_mul_f32 v[24:25], v[28:29], v[50:51] op_sel_hi:[1,0]
	v_pk_fma_f32 v[2:3], v[182:183], v[16:17], v[214:215]
	v_pk_fma_f32 v[0:1], v[180:181], v[24:25], v[212:213]
	global_store_dwordx4 v[36:37], v[0:3], off offset:32
	s_nop 1
	s_nop 0
	v_pk_mul_f32 v[16:17], v[18:19], v[50:51] op_sel_hi:[1,0]
	v_pk_mul_f32 v[18:19], v[20:21], v[50:51] op_sel_hi:[1,0]
	v_pk_fma_f32 v[2:3], v[186:187], v[16:17], v[218:219]
	v_pk_fma_f32 v[0:1], v[184:185], v[18:19], v[216:217]
	global_store_dwordx4 v[36:37], v[0:3], off offset:48
	s_nop 1
	s_nop 0
	v_add_co_u32_e32 v16, vcc, s12, v36
	v_pk_mul_f32 v[18:19], v[22:23], v[50:51] op_sel_hi:[1,0]
	s_nop 0
	v_addc_co_u32_e32 v17, vcc, 0, v37, vcc
	s_and_b64 vcc, exec, s[8:9]
	v_pk_fma_f32 v[0:1], v[188:189], v[18:19], v[220:221]
	v_pk_fma_f32 v[2:3], v[190:191], v[8:9], v[222:223]
	global_store_dwordx4 v[16:17], v[0:3], off
	s_nop 1
	s_nop 0
	v_pk_mul_f32 v[8:9], v[10:11], v[50:51] op_sel_hi:[1,0]
	v_pk_mul_f32 v[10:11], v[12:13], v[50:51] op_sel_hi:[1,0]
	v_pk_fma_f32 v[2:3], v[194:195], v[8:9], v[226:227]
	v_pk_fma_f32 v[0:1], v[192:193], v[10:11], v[224:225]
	global_store_dwordx4 v[16:17], v[0:3], off offset:16
	s_nop 1
	s_nop 0
	v_pk_mul_f32 v[8:9], v[48:49], v[50:51] op_sel_hi:[1,0]
	v_pk_mul_f32 v[10:11], v[14:15], v[50:51] op_sel_hi:[1,0]
	v_pk_fma_f32 v[2:3], v[198:199], v[8:9], v[230:231]
	v_pk_fma_f32 v[0:1], v[196:197], v[10:11], v[228:229]
	global_store_dwordx4 v[16:17], v[0:3], off offset:32
	s_nop 1
	s_nop 0
	v_pk_mul_f32 v[8:9], v[44:45], v[50:51] op_sel_hi:[1,0]
	v_pk_mul_f32 v[10:11], v[30:31], v[50:51] op_sel_hi:[1,0]
	v_pk_fma_f32 v[2:3], v[202:203], v[8:9], v[234:235]
	v_pk_fma_f32 v[0:1], v[200:201], v[10:11], v[232:233]
	global_store_dwordx4 v[16:17], v[0:3], off offset:48
	s_nop 1
	s_waitcnt vmcnt(0)
	s_cbranch_vccz .LBB0_1012

	.amdhsa_kernel _Z6mk_fwd4Args
		.amdhsa_group_segment_fixed_size 0
		.amdhsa_private_segment_fixed_size 0
		.amdhsa_kernarg_size 424
		.amdhsa_user_sgpr_count 2
		.amdhsa_user_sgpr_dispatch_ptr 0
		.amdhsa_user_sgpr_queue_ptr 0
		.amdhsa_user_sgpr_kernarg_segment_ptr 1
		.amdhsa_user_sgpr_dispatch_id 0
		.amdhsa_user_sgpr_kernarg_preload_length 0
		.amdhsa_user_sgpr_kernarg_preload_offset 0
		.amdhsa_user_sgpr_private_segment_size 0
		.amdhsa_uses_dynamic_stack 0
		.amdhsa_enable_private_segment 0
		.amdhsa_system_sgpr_workgroup_id_x 1
		.amdhsa_system_sgpr_workgroup_id_y 0
		.amdhsa_system_sgpr_workgroup_id_z 0
		.amdhsa_system_sgpr_workgroup_info 0
		.amdhsa_system_vgpr_workitem_id 0
		.amdhsa_next_free_vgpr 256
		.amdhsa_next_free_sgpr 100
		.amdhsa_accum_offset 256
		.amdhsa_reserve_vcc 1
		.amdhsa_float_round_mode_32 0
		.amdhsa_float_round_mode_16_64 0
		.amdhsa_float_denorm_mode_32 3
		.amdhsa_float_denorm_mode_16_64 3
		.amdhsa_dx10_clamp 1
		.amdhsa_ieee_mode 1
		.amdhsa_fp16_overflow 0
		.amdhsa_tg_split 0
		.amdhsa_exception_fp_ieee_invalid_op 0
		.amdhsa_exception_fp_denorm_src 0
		.amdhsa_exception_fp_ieee_div_zero 0
		.amdhsa_exception_fp_ieee_overflow 0
		.amdhsa_exception_fp_ieee_underflow 0
		.amdhsa_exception_fp_ieee_inexact 0
		.amdhsa_exception_int_div_zero 0
	.end_amdhsa_kernel

amdhsa.kernels:
  - .agpr_count:     0
    .args:
      - .offset:         0
        .size:           168
        .value_kind:     by_value
      - .offset:         168
        .size:           4
        .value_kind:     hidden_block_count_x
      - .offset:         172
        .size:           4
        .value_kind:     hidden_block_count_y
      - .offset:         176
        .size:           4
        .value_kind:     hidden_block_count_z
      - .offset:         180
        .size:           2
        .value_kind:     hidden_group_size_x
      - .offset:         182
        .size:           2
        .value_kind:     hidden_group_size_y
      - .offset:         184
        .size:           2
        .value_kind:     hidden_group_size_z
      - .offset:         186
        .size:           2
        .value_kind:     hidden_remainder_x
      - .offset:         188
        .size:           2
        .value_kind:     hidden_remainder_y
      - .offset:         190
        .size:           2
        .value_kind:     hidden_remainder_z
      - .offset:         208
        .size:           8
        .value_kind:     hidden_global_offset_x
      - .offset:         216
        .size:           8
        .value_kind:     hidden_global_offset_y
      - .offset:         224
        .size:           8
        .value_kind:     hidden_global_offset_z
      - .offset:         232
        .size:           2
        .value_kind:     hidden_grid_dims
      - .offset:         288
        .size:           4
        .value_kind:     hidden_dynamic_lds_size
    .group_segment_fixed_size: 0
    .kernarg_segment_align: 8
    .kernarg_segment_size: 424
    .language:       OpenCL C
    .language_version:
      - 2
      - 0
    .max_flat_workgroup_size: 512
    .name:           _Z6mk_fwd4Args
    .private_segment_fixed_size: 0
    .sgpr_count:     106
    .sgpr_spill_count: 111
    .symbol:         _Z6mk_fwd4Args.kd
    .uniform_work_group_size: 1
    .uses_dynamic_stack: false
    .vgpr_count:     256
    .vgpr_spill_count: 0
    .wavefront_size: 64
